# also: s_setprio 1 of each MFMA segment issued before its opening barrier instead of after
# baseline (speedup 1.0000x reference)
; #define PG8_STAGE(bufoff, gbase, voff) do { _Pragma("unroll") for (int _i = 0; _i < 2; ++_i) \
;         __builtin_amdgcn_global_load_lds((const unsigned*)((const char*)(gbase) + (voff)[_i]), (PG8_LAS unsigned*)(lds + (bufoff) + ldsw + _i * 8192), 16, 0, 0); } while (0)
; #define PG8_LDA(dst, b, h) do { _Pragma("unroll") for (int m = 0; m < 4; ++m) _Pragma("unroll") for (int k = 0; k < 2; ++k) dst[m][k] = *(const PG8_LAS bf16x8*)(lds + PG8_SA(b, h) + aoff + m * 2048 + k * 1024); } while (0)
; #define PG8_LDB(dst, b, h) do { _Pragma("unroll") for (int n = 0; n < 2; ++n) _Pragma("unroll") for (int k = 0; k < 2; ++k) dst[n][k] = *(const PG8_LAS bf16x8*)(lds + PG8_SB(b, h) + boff + n * 2048 + k * 1024); } while (0)
; #define PG8_MMA(ai, bj, At, Bt) do { __builtin_amdgcn_s_setprio(1); _Pragma("unroll") for (int m = 0; m < 4; ++m) _Pragma("unroll") for (int n = 0; n < 2; ++n) _Pragma("unroll") for (int k = 0; k < 2; ++k) \
;         acc[ai][bj][m][n] = __builtin_amdgcn_mfma_f32_16x16x32_bf16(Bt[n][k], At[m][k], acc[ai][bj][m][n], 0, 0, 0); __builtin_amdgcn_s_setprio(0); } while (0)
; #define PG8_WAIT_V(n) asm volatile("s_waitcnt vmcnt(" #n ")" ::: "memory")
; template <class Epi, class Sched, bool ALIGN_EPI = false, bool SP2 = false>
; __device__ __forceinline__ void gemm_phase(PG8_LAS unsigned char* lds, const Gemm g, const Sched& S, const Epi& E) {
;     ...
;             PG8_LDB(B0, 0, 0); PG8_LDB(B1, 0, 1); PG8_SCHED; PG8_LDA(At, 0, 0); PG8_STAGE(PG8_SA(1, 1), a1 + hstep, voffA);
;             PG8_WAIT_V(8); PG8_WAIT_L(0); PG8_BAR; PG8_MMA(0, 0, At, B0); PG8_MMA(0, 1, At, B1); PG8_BAR; PG8_SCHED;
;             PG8_LDA(At, 0, 1); PG8_STAGE(PG8_SB(0, 0), b2, voffB); PG8_STAGE(PG8_SB(0, 1), b2 + hstep, voffB); PG8_STAGE(PG8_SA(0, 0), a2, voffA);
;             PG8_WAIT_V(8); PG8_WAIT_L(0); PG8_BAR; PG8_MMA(1, 0, At, B0); PG8_MMA(1, 1, At, B1); PG8_BAR; PG8_SCHED;
;             PG8_LDB(B0, 1, 0); PG8_LDB(B1, 1, 1); PG8_SCHED; PG8_LDA(At, 1, 0); PG8_STAGE(PG8_SA(0, 1), a2 + hstep, voffA);
;             PG8_WAIT_V(8); PG8_WAIT_L(0); PG8_BAR; PG8_MMA(0, 0, At, B0); PG8_MMA(0, 1, At, B1); PG8_BAR; PG8_SCHED;
;             PG8_LDA(At, 1, 1); PG8_STAGE(PG8_SB(1, 0), b3, voffB); PG8_STAGE(PG8_SB(1, 1), b3 + hstep, voffB); PG8_STAGE(PG8_SA(1, 0), a3, voffA);
;             PG8_WAIT_V(8); PG8_WAIT_L(0); PG8_BAR; PG8_MMA(1, 0, At, B0); PG8_MMA(1, 1, At, B1); PG8_BAR; PG8_SCHED;
.LBB0_141:
	ds_read_b128 v[130:133], v196
	ds_read_b128 v[134:137], v196 offset:1024
	ds_read_b128 v[138:141], v196 offset:2048
	ds_read_b128 v[142:145], v196 offset:3072
	s_waitcnt lgkmcnt(0)
	ds_read_b128 v[170:173], v197
	ds_read_b128 v[174:177], v197 offset:1024
	ds_read_b128 v[178:181], v197 offset:2048
	ds_read_b128 v[182:185], v197 offset:3072
	s_add_u32 s18, s84, 0xfffc0080
	s_addc_u32 s19, s85, -1
	s_cmp_eq_u32 vcc_lo, 12
	s_cselect_b32 s87, s7, s19
	s_cselect_b32 s86, s9, s18
	s_cselect_b32 s31, s10, s75
	s_cselect_b32 s30, s69, s73
	v_lshl_add_u64 v[190:191], s[84:85], 0, v[162:163]
	s_add_i32 m0, s91, 0xc000
	ds_read_b128 v[186:189], v198
	ds_read_b128 v[202:205], v198 offset:1024
	ds_read_b128 v[208:211], v198 offset:2048
	ds_read_b128 v[212:215], v198 offset:3072
	ds_read_b128 v[216:219], v198 offset:4096
	ds_read_b128 v[220:223], v198 offset:5120
	ds_read_b128 v[224:227], v198 offset:6144
	ds_read_b128 v[228:231], v198 offset:7168
	global_load_lds_dwordx4 v[190:191], off
	v_lshl_add_u64 v[190:191], s[84:85], 0, v[164:165]
	s_add_i32 m0, s91, 0xe000
	s_nop 0
	global_load_lds_dwordx4 v[190:191], off
	s_waitcnt vmcnt(8)
	s_waitcnt lgkmcnt(0)
	s_setprio 1
	s_barrier
	s_waitcnt lgkmcnt(0)
	v_mfma_f32_16x16x32_bf16 v[126:129], v[130:133], v[186:189], v[126:129]
	v_mfma_f32_16x16x32_bf16 v[122:125], v[138:141], v[186:189], v[122:125]
	v_mfma_f32_16x16x32_bf16 v[110:113], v[130:133], v[208:211], v[110:113]
	v_mfma_f32_16x16x32_bf16 v[106:109], v[138:141], v[208:211], v[106:109]
	v_mfma_f32_16x16x32_bf16 v[94:97], v[130:133], v[216:219], v[94:97]
	v_mfma_f32_16x16x32_bf16 v[90:93], v[138:141], v[216:219], v[90:93]
	v_mfma_f32_16x16x32_bf16 v[78:81], v[130:133], v[224:227], v[78:81]
	v_mfma_f32_16x16x32_bf16 v[74:77], v[138:141], v[224:227], v[74:77]
	v_mfma_f32_16x16x32_bf16 v[126:129], v[134:137], v[202:205], v[126:129]
	v_mfma_f32_16x16x32_bf16 v[122:125], v[142:145], v[202:205], v[122:125]
	v_mfma_f32_16x16x32_bf16 v[110:113], v[134:137], v[212:215], v[110:113]
	v_mfma_f32_16x16x32_bf16 v[106:109], v[142:145], v[212:215], v[106:109]
	v_mfma_f32_16x16x32_bf16 v[94:97], v[134:137], v[220:223], v[94:97]
	v_mfma_f32_16x16x32_bf16 v[90:93], v[142:145], v[220:223], v[90:93]
	v_mfma_f32_16x16x32_bf16 v[78:81], v[134:137], v[228:231], v[78:81]
	v_mfma_f32_16x16x32_bf16 v[74:77], v[142:145], v[228:231], v[74:77]
	s_setprio 0
	s_setprio 1
	v_mfma_f32_16x16x32_bf16 v[118:121], v[170:173], v[186:189], v[118:121]
	v_mfma_f32_16x16x32_bf16 v[114:117], v[178:181], v[186:189], v[114:117]
	v_mfma_f32_16x16x32_bf16 v[102:105], v[170:173], v[208:211], v[102:105]
	v_mfma_f32_16x16x32_bf16 v[98:101], v[178:181], v[208:211], v[98:101]
	v_mfma_f32_16x16x32_bf16 v[86:89], v[170:173], v[216:219], v[86:89]
	v_mfma_f32_16x16x32_bf16 v[82:85], v[178:181], v[216:219], v[82:85]
	v_mfma_f32_16x16x32_bf16 v[70:73], v[170:173], v[224:227], v[70:73]
	v_mfma_f32_16x16x32_bf16 v[66:69], v[178:181], v[224:227], v[66:69]
	v_mfma_f32_16x16x32_bf16 v[118:121], v[174:177], v[202:205], v[118:121]
	v_mfma_f32_16x16x32_bf16 v[114:117], v[182:185], v[202:205], v[114:117]
	v_mfma_f32_16x16x32_bf16 v[102:105], v[174:177], v[212:215], v[102:105]
	v_mfma_f32_16x16x32_bf16 v[98:101], v[182:185], v[212:215], v[98:101]
	v_mfma_f32_16x16x32_bf16 v[86:89], v[174:177], v[220:223], v[86:89]
	v_mfma_f32_16x16x32_bf16 v[82:85], v[182:185], v[220:223], v[82:85]
	v_mfma_f32_16x16x32_bf16 v[70:73], v[174:177], v[228:231], v[70:73]
	s_setprio 3
	s_barrier
	v_mfma_f32_16x16x32_bf16 v[66:69], v[182:185], v[228:231], v[66:69]
	s_setprio 0
	s_add_i32 s18, s58, s88
	v_lshl_add_u64 v[190:191], s[30:31], 0, v[148:149]
	s_mov_b32 m0, s18
	ds_read_b128 v[186:189], v198 offset:16384
	ds_read_b128 v[202:205], v198 offset:17408
	ds_read_b128 v[208:211], v198 offset:18432
	ds_read_b128 v[212:215], v198 offset:19456
	ds_read_b128 v[216:219], v198 offset:20480
	ds_read_b128 v[220:223], v198 offset:21504
	ds_read_b128 v[224:227], v198 offset:22528
	ds_read_b128 v[228:231], v198 offset:23552
	global_load_lds_dwordx4 v[190:191], off
	s_add_i32 m0, s18, 0x2000
	s_add_u32 s18, s30, 0x40000
	v_lshl_add_u64 v[232:233], s[30:31], 0, v[152:153]
	s_addc_u32 s19, s31, 0
	s_add_i32 vcc_hi, s59, s88
	global_load_lds_dwordx4 v[232:233], off
	v_lshl_add_u64 v[234:235], s[18:19], 0, v[148:149]
	s_mov_b32 m0, vcc_hi
	v_lshl_add_u64 v[238:239], s[86:87], 0, v[150:151]
	global_load_lds_dwordx4 v[234:235], off
	v_lshl_add_u64 v[234:235], s[18:19], 0, v[152:153]
	s_add_i32 m0, vcc_hi, 0x2000
	s_nop 0
	global_load_lds_dwordx4 v[234:235], off
	v_lshl_add_u64 v[234:235], s[86:87], 0, v[146:147]
	s_mov_b32 m0, s91
	s_nop 0
	global_load_lds_dwordx4 v[234:235], off
	s_mov_b32 m0, s92
	s_nop 0
	global_load_lds_dwordx4 v[238:239], off
	s_waitcnt vmcnt(8)
	s_waitcnt lgkmcnt(0)
	s_setprio 1
	s_barrier
; #define PG8_STAGE(bufoff, gbase, voff) do { _Pragma("unroll") for (int _i = 0; _i < 2; ++_i) \
;         __builtin_amdgcn_global_load_lds((const unsigned*)((const char*)(gbase) + (voff)[_i]), (PG8_LAS unsigned*)(lds + (bufoff) + ldsw + _i * 8192), 16, 0, 0); } while (0)
; #define PG8_LDA(dst, b, h) do { _Pragma("unroll") for (int m = 0; m < 4; ++m) _Pragma("unroll") for (int k = 0; k < 2; ++k) dst[m][k] = *(const PG8_LAS bf16x8*)(lds + PG8_SA(b, h) + aoff + m * 2048 + k * 1024); } while (0)
; #define PG8_LDB(dst, b, h) do { _Pragma("unroll") for (int n = 0; n < 2; ++n) _Pragma("unroll") for (int k = 0; k < 2; ++k) dst[n][k] = *(const PG8_LAS bf16x8*)(lds + PG8_SB(b, h) + boff + n * 2048 + k * 1024); } while (0)
; #define PG8_MMA(ai, bj, At, Bt) do { __builtin_amdgcn_s_setprio(1); _Pragma("unroll") for (int m = 0; m < 4; ++m) _Pragma("unroll") for (int n = 0; n < 2; ++n) _Pragma("unroll") for (int k = 0; k < 2; ++k) \
;         acc[ai][bj][m][n] = __builtin_amdgcn_mfma_f32_16x16x32_bf16(Bt[n][k], At[m][k], acc[ai][bj][m][n], 0, 0, 0); __builtin_amdgcn_s_setprio(0); } while (0)
; #define PG8_WAIT_V(n) asm volatile("s_waitcnt vmcnt(" #n ")" ::: "memory")
; template <class Epi, class Sched, bool ALIGN_EPI = false, bool SP2 = false>
; __device__ __forceinline__ void gemm_phase(PG8_LAS unsigned char* lds, const Gemm g, const Sched& S, const Epi& E) {
;     ...
;             PG8_LDB(B0, 0, 0); PG8_LDB(B1, 0, 1); PG8_SCHED; PG8_LDA(At, 0, 0); PG8_STAGE(PG8_SA(1, 1), a1 + hstep, voffA);
;             PG8_WAIT_V(8); PG8_WAIT_L(0); PG8_BAR; PG8_MMA(0, 0, At, B0); PG8_MMA(0, 1, At, B1); PG8_BAR; PG8_SCHED;
;             PG8_LDA(At, 0, 1); PG8_STAGE(PG8_SB(0, 0), b2, voffB); PG8_STAGE(PG8_SB(0, 1), b2 + hstep, voffB); PG8_STAGE(PG8_SA(0, 0), a2, voffA);
;             PG8_WAIT_V(8); PG8_WAIT_L(0); PG8_BAR; PG8_MMA(1, 0, At, B0); PG8_MMA(1, 1, At, B1); PG8_BAR; PG8_SCHED;
;             PG8_LDB(B0, 1, 0); PG8_LDB(B1, 1, 1); PG8_SCHED; PG8_LDA(At, 1, 0); PG8_STAGE(PG8_SA(0, 1), a2 + hstep, voffA);
;             PG8_WAIT_V(8); PG8_WAIT_L(0); PG8_BAR; PG8_MMA(0, 0, At, B0); PG8_MMA(0, 1, At, B1); PG8_BAR; PG8_SCHED;
;             PG8_LDA(At, 1, 1); PG8_STAGE(PG8_SB(1, 0), b3, voffB); PG8_STAGE(PG8_SB(1, 1), b3 + hstep, voffB); PG8_STAGE(PG8_SA(1, 0), a3, voffA);
;             PG8_WAIT_V(8); PG8_WAIT_L(0); PG8_BAR; PG8_MMA(1, 0, At, B0); PG8_MMA(1, 1, At, B1); PG8_BAR; PG8_SCHED;
	s_waitcnt lgkmcnt(0)
	v_mfma_f32_16x16x32_bf16 v[62:65], v[130:133], v[186:189], v[62:65]
	v_mfma_f32_16x16x32_bf16 v[58:61], v[138:141], v[186:189], v[58:61]
	v_mfma_f32_16x16x32_bf16 v[46:49], v[130:133], v[208:211], v[46:49]
	v_mfma_f32_16x16x32_bf16 v[42:45], v[138:141], v[208:211], v[42:45]
	v_mfma_f32_16x16x32_bf16 v[30:33], v[130:133], v[216:219], v[30:33]
	v_mfma_f32_16x16x32_bf16 v[26:29], v[138:141], v[216:219], v[26:29]
	v_mfma_f32_16x16x32_bf16 v[14:17], v[130:133], v[224:227], v[14:17]
	v_mfma_f32_16x16x32_bf16 v[10:13], v[138:141], v[224:227], v[10:13]
	v_mfma_f32_16x16x32_bf16 v[62:65], v[134:137], v[202:205], v[62:65]
	v_mfma_f32_16x16x32_bf16 v[58:61], v[142:145], v[202:205], v[58:61]
	v_mfma_f32_16x16x32_bf16 v[46:49], v[134:137], v[212:215], v[46:49]
	v_mfma_f32_16x16x32_bf16 v[42:45], v[142:145], v[212:215], v[42:45]
	v_mfma_f32_16x16x32_bf16 v[30:33], v[134:137], v[220:223], v[30:33]
	v_mfma_f32_16x16x32_bf16 v[26:29], v[142:145], v[220:223], v[26:29]
	v_mfma_f32_16x16x32_bf16 v[14:17], v[134:137], v[228:231], v[14:17]
	v_mfma_f32_16x16x32_bf16 v[10:13], v[142:145], v[228:231], v[10:13]
	s_setprio 0
	s_setprio 1
	v_mfma_f32_16x16x32_bf16 v[54:57], v[170:173], v[186:189], v[54:57]
	v_mfma_f32_16x16x32_bf16 v[50:53], v[178:181], v[186:189], v[50:53]
	v_mfma_f32_16x16x32_bf16 v[38:41], v[170:173], v[208:211], v[38:41]
	v_mfma_f32_16x16x32_bf16 v[34:37], v[178:181], v[208:211], v[34:37]
	v_mfma_f32_16x16x32_bf16 v[22:25], v[170:173], v[216:219], v[22:25]
	v_mfma_f32_16x16x32_bf16 v[18:21], v[178:181], v[216:219], v[18:21]
	v_mfma_f32_16x16x32_bf16 v[6:9], v[170:173], v[224:227], v[6:9]
	v_mfma_f32_16x16x32_bf16 v[2:5], v[178:181], v[224:227], v[2:5]
	v_mfma_f32_16x16x32_bf16 v[54:57], v[174:177], v[202:205], v[54:57]
	v_mfma_f32_16x16x32_bf16 v[50:53], v[182:185], v[202:205], v[50:53]
	v_mfma_f32_16x16x32_bf16 v[38:41], v[174:177], v[212:215], v[38:41]
	v_mfma_f32_16x16x32_bf16 v[34:37], v[182:185], v[212:215], v[34:37]
	v_mfma_f32_16x16x32_bf16 v[22:25], v[174:177], v[220:223], v[22:25]
	v_mfma_f32_16x16x32_bf16 v[18:21], v[182:185], v[220:223], v[18:21]
	v_mfma_f32_16x16x32_bf16 v[6:9], v[174:177], v[228:231], v[6:9]
	s_setprio 3
	s_barrier
	v_mfma_f32_16x16x32_bf16 v[2:5], v[182:185], v[228:231], v[2:5]
	s_setprio 0
	s_add_i32 vcc_hi, 0, 0x18000
	s_add_i32 s52, 0, 0x1c000
	v_add_u32_e32 v142, vcc_hi, v157
	v_add_u32_e32 v154, s52, v157
	ds_read_b128 v[130:133], v142
	ds_read_b128 v[134:137], v142 offset:1024
	ds_read_b128 v[138:141], v142 offset:2048
	ds_read_b128 v[142:145], v142 offset:3072
	ds_read_b128 v[170:173], v154
	ds_read_b128 v[174:177], v154 offset:1024
	ds_read_b128 v[178:181], v154 offset:2048
	ds_read_b128 v[182:185], v154 offset:3072
	s_add_u32 s18, s86, 0x40000
	s_addc_u32 s19, s87, 0
	s_mov_b32 m0, s93
	v_lshl_add_u64 v[240:241], s[18:19], 0, v[146:147]
	ds_read_b128 v[186:189], v198 offset:32768
	ds_read_b128 v[202:205], v198 offset:33792
	ds_read_b128 v[208:211], v198 offset:34816
	ds_read_b128 v[212:215], v198 offset:35840
	ds_read_b128 v[216:219], v198 offset:36864
	ds_read_b128 v[220:223], v198 offset:37888
	ds_read_b128 v[224:227], v198 offset:38912
	ds_read_b128 v[228:231], v198 offset:39936
	global_load_lds_dwordx4 v[240:241], off
	v_lshl_add_u64 v[240:241], s[18:19], 0, v[150:151]
	s_mov_b32 m0, s95
	s_nop 0
	global_load_lds_dwordx4 v[240:241], off
	s_waitcnt vmcnt(8)
	s_waitcnt lgkmcnt(0)
	s_setprio 1
	s_barrier
	s_waitcnt lgkmcnt(0)
	v_mfma_f32_16x16x32_bf16 v[126:129], v[130:133], v[186:189], v[126:129]
	v_mfma_f32_16x16x32_bf16 v[122:125], v[138:141], v[186:189], v[122:125]
	v_mfma_f32_16x16x32_bf16 v[110:113], v[130:133], v[208:211], v[110:113]
	v_mfma_f32_16x16x32_bf16 v[106:109], v[138:141], v[208:211], v[106:109]
	v_mfma_f32_16x16x32_bf16 v[94:97], v[130:133], v[216:219], v[94:97]
	v_mfma_f32_16x16x32_bf16 v[90:93], v[138:141], v[216:219], v[90:93]
	v_mfma_f32_16x16x32_bf16 v[78:81], v[130:133], v[224:227], v[78:81]
	v_mfma_f32_16x16x32_bf16 v[74:77], v[138:141], v[224:227], v[74:77]
	v_mfma_f32_16x16x32_bf16 v[126:129], v[134:137], v[202:205], v[126:129]
	v_mfma_f32_16x16x32_bf16 v[122:125], v[142:145], v[202:205], v[122:125]
	v_mfma_f32_16x16x32_bf16 v[110:113], v[134:137], v[212:215], v[110:113]
	v_mfma_f32_16x16x32_bf16 v[106:109], v[142:145], v[212:215], v[106:109]
	v_mfma_f32_16x16x32_bf16 v[94:97], v[134:137], v[220:223], v[94:97]
	v_mfma_f32_16x16x32_bf16 v[90:93], v[142:145], v[220:223], v[90:93]
	v_mfma_f32_16x16x32_bf16 v[78:81], v[134:137], v[228:231], v[78:81]
	v_mfma_f32_16x16x32_bf16 v[74:77], v[142:145], v[228:231], v[74:77]
	s_setprio 0
	s_setprio 1
	v_mfma_f32_16x16x32_bf16 v[118:121], v[170:173], v[186:189], v[118:121]
	v_mfma_f32_16x16x32_bf16 v[114:117], v[178:181], v[186:189], v[114:117]
	v_mfma_f32_16x16x32_bf16 v[102:105], v[170:173], v[208:211], v[102:105]
	v_mfma_f32_16x16x32_bf16 v[98:101], v[178:181], v[208:211], v[98:101]
	v_mfma_f32_16x16x32_bf16 v[86:89], v[170:173], v[216:219], v[86:89]
	v_mfma_f32_16x16x32_bf16 v[82:85], v[178:181], v[216:219], v[82:85]
	v_mfma_f32_16x16x32_bf16 v[70:73], v[170:173], v[224:227], v[70:73]
	v_mfma_f32_16x16x32_bf16 v[66:69], v[178:181], v[224:227], v[66:69]
	v_mfma_f32_16x16x32_bf16 v[118:121], v[174:177], v[202:205], v[118:121]
	v_mfma_f32_16x16x32_bf16 v[114:117], v[182:185], v[202:205], v[114:117]
	v_mfma_f32_16x16x32_bf16 v[102:105], v[174:177], v[212:215], v[102:105]
	v_mfma_f32_16x16x32_bf16 v[98:101], v[182:185], v[212:215], v[98:101]
	v_mfma_f32_16x16x32_bf16 v[86:89], v[174:177], v[220:223], v[86:89]
	v_mfma_f32_16x16x32_bf16 v[82:85], v[182:185], v[220:223], v[82:85]
	v_mfma_f32_16x16x32_bf16 v[70:73], v[174:177], v[228:231], v[70:73]
	s_setprio 3
	s_barrier
; #define PG8_STAGE(bufoff, gbase, voff) do { _Pragma("unroll") for (int _i = 0; _i < 2; ++_i) \
;         __builtin_amdgcn_global_load_lds((const unsigned*)((const char*)(gbase) + (voff)[_i]), (PG8_LAS unsigned*)(lds + (bufoff) + ldsw + _i * 8192), 16, 0, 0); } while (0)
; #define PG8_LDA(dst, b, h) do { _Pragma("unroll") for (int m = 0; m < 4; ++m) _Pragma("unroll") for (int k = 0; k < 2; ++k) dst[m][k] = *(const PG8_LAS bf16x8*)(lds + PG8_SA(b, h) + aoff + m * 2048 + k * 1024); } while (0)
; #define PG8_LDB(dst, b, h) do { _Pragma("unroll") for (int n = 0; n < 2; ++n) _Pragma("unroll") for (int k = 0; k < 2; ++k) dst[n][k] = *(const PG8_LAS bf16x8*)(lds + PG8_SB(b, h) + boff + n * 2048 + k * 1024); } while (0)
; #define PG8_MMA(ai, bj, At, Bt) do { __builtin_amdgcn_s_setprio(1); _Pragma("unroll") for (int m = 0; m < 4; ++m) _Pragma("unroll") for (int n = 0; n < 2; ++n) _Pragma("unroll") for (int k = 0; k < 2; ++k) \
;         acc[ai][bj][m][n] = __builtin_amdgcn_mfma_f32_16x16x32_bf16(Bt[n][k], At[m][k], acc[ai][bj][m][n], 0, 0, 0); __builtin_amdgcn_s_setprio(0); } while (0)
; template <class Epi, class Sched, bool ALIGN_EPI = false, bool SP2 = false>
; __device__ __forceinline__ void gemm_phase(PG8_LAS unsigned char* lds, const Gemm g, const Sched& S, const Epi& E) {
;     ...
;             PG8_LDB(B0, 0, 0); PG8_LDB(B1, 0, 1); PG8_SCHED; PG8_LDA(At, 0, 0); PG8_STAGE(PG8_SA(1, 1), a1 + hstep, voffA);
;             PG8_WAIT_V(8); PG8_WAIT_L(0); PG8_BAR; PG8_MMA(0, 0, At, B0); PG8_MMA(0, 1, At, B1); PG8_BAR; PG8_SCHED;
;             PG8_LDA(At, 0, 1); PG8_STAGE(PG8_SB(0, 0), b2, voffB); PG8_STAGE(PG8_SB(0, 1), b2 + hstep, voffB); PG8_STAGE(PG8_SA(0, 0), a2, voffA);
;             PG8_WAIT_V(8); PG8_WAIT_L(0); PG8_BAR; PG8_MMA(1, 0, At, B0); PG8_MMA(1, 1, At, B1); PG8_BAR; PG8_SCHED;
;             PG8_LDB(B0, 1, 0); PG8_LDB(B1, 1, 1); PG8_SCHED; PG8_LDA(At, 1, 0); PG8_STAGE(PG8_SA(0, 1), a2 + hstep, voffA);
;             PG8_WAIT_V(8); PG8_WAIT_L(0); PG8_BAR; PG8_MMA(0, 0, At, B0); PG8_MMA(0, 1, At, B1); PG8_BAR; PG8_SCHED;
;             PG8_LDA(At, 1, 1); PG8_STAGE(PG8_SB(1, 0), b3, voffB); PG8_STAGE(PG8_SB(1, 1), b3 + hstep, voffB); PG8_STAGE(PG8_SA(1, 0), a3, voffA);
;             PG8_WAIT_V(8); PG8_WAIT_L(0); PG8_BAR; PG8_MMA(1, 0, At, B0); PG8_MMA(1, 1, At, B1); PG8_BAR; PG8_SCHED;
;     ...
;         if constexpr (ALIGN_EPI) { if (wr == 0) PG8_BAR; }
	v_mfma_f32_16x16x32_bf16 v[66:69], v[182:185], v[228:231], v[66:69]
	s_setprio 0
	s_add_i32 s18, vcc_hi, s88
	v_lshl_add_u64 v[190:191], v[190:191], 0, s[16:17]
	s_mov_b32 m0, s18
	ds_read_b128 v[186:189], v198 offset:49152
	ds_read_b128 v[202:205], v198 offset:50176
	ds_read_b128 v[208:211], v198 offset:51200
	ds_read_b128 v[212:215], v198 offset:52224
	ds_read_b128 v[216:219], v198 offset:53248
	ds_read_b128 v[220:223], v198 offset:54272
	ds_read_b128 v[224:227], v198 offset:55296
	ds_read_b128 v[228:231], v198 offset:56320
	global_load_lds_dwordx4 v[190:191], off
	s_add_i32 m0, s18, 0x2000
	s_add_u32 s18, s30, 0x40080
	v_lshl_add_u64 v[190:191], v[232:233], 0, s[16:17]
	s_addc_u32 s19, s31, 0
	s_add_i32 s30, s52, s88
	global_load_lds_dwordx4 v[190:191], off
	v_lshl_add_u64 v[190:191], s[18:19], 0, v[148:149]
	s_mov_b32 m0, s30
	s_nop 0
	global_load_lds_dwordx4 v[190:191], off
	v_lshl_add_u64 v[190:191], s[18:19], 0, v[152:153]
	s_add_i32 m0, s30, 0x2000
	s_nop 0
	global_load_lds_dwordx4 v[190:191], off
	v_lshl_add_u64 v[190:191], v[234:235], 0, s[16:17]
	s_mov_b32 m0, s24
	s_nop 0
	global_load_lds_dwordx4 v[190:191], off
	v_lshl_add_u64 v[190:191], v[238:239], 0, s[16:17]
	s_mov_b32 m0, s25
	s_nop 0
	global_load_lds_dwordx4 v[190:191], off
	s_waitcnt vmcnt(8)
	s_waitcnt lgkmcnt(0)
	s_setprio 1
	s_barrier
	s_waitcnt lgkmcnt(0)
	v_mfma_f32_16x16x32_bf16 v[62:65], v[130:133], v[186:189], v[62:65]
	v_mfma_f32_16x16x32_bf16 v[58:61], v[138:141], v[186:189], v[58:61]
	v_mfma_f32_16x16x32_bf16 v[46:49], v[130:133], v[208:211], v[46:49]
	v_mfma_f32_16x16x32_bf16 v[42:45], v[138:141], v[208:211], v[42:45]
	v_mfma_f32_16x16x32_bf16 v[30:33], v[130:133], v[216:219], v[30:33]
	v_mfma_f32_16x16x32_bf16 v[26:29], v[138:141], v[216:219], v[26:29]
	v_mfma_f32_16x16x32_bf16 v[14:17], v[130:133], v[224:227], v[14:17]
	v_mfma_f32_16x16x32_bf16 v[10:13], v[138:141], v[224:227], v[10:13]
	v_mfma_f32_16x16x32_bf16 v[62:65], v[134:137], v[202:205], v[62:65]
	v_mfma_f32_16x16x32_bf16 v[58:61], v[142:145], v[202:205], v[58:61]
	v_mfma_f32_16x16x32_bf16 v[46:49], v[134:137], v[212:215], v[46:49]
	v_mfma_f32_16x16x32_bf16 v[42:45], v[142:145], v[212:215], v[42:45]
	v_mfma_f32_16x16x32_bf16 v[30:33], v[134:137], v[220:223], v[30:33]
	v_mfma_f32_16x16x32_bf16 v[26:29], v[142:145], v[220:223], v[26:29]
	v_mfma_f32_16x16x32_bf16 v[14:17], v[134:137], v[228:231], v[14:17]
	v_mfma_f32_16x16x32_bf16 v[10:13], v[142:145], v[228:231], v[10:13]
	s_setprio 0
	s_setprio 1
	v_mfma_f32_16x16x32_bf16 v[54:57], v[170:173], v[186:189], v[54:57]
	v_mfma_f32_16x16x32_bf16 v[50:53], v[178:181], v[186:189], v[50:53]
	v_mfma_f32_16x16x32_bf16 v[38:41], v[170:173], v[208:211], v[38:41]
	v_mfma_f32_16x16x32_bf16 v[34:37], v[178:181], v[208:211], v[34:37]
	v_mfma_f32_16x16x32_bf16 v[22:25], v[170:173], v[216:219], v[22:25]
	v_mfma_f32_16x16x32_bf16 v[18:21], v[178:181], v[216:219], v[18:21]
	v_mfma_f32_16x16x32_bf16 v[6:9], v[170:173], v[224:227], v[6:9]
	v_mfma_f32_16x16x32_bf16 v[2:5], v[178:181], v[224:227], v[2:5]
	v_mfma_f32_16x16x32_bf16 v[54:57], v[174:177], v[202:205], v[54:57]
	v_mfma_f32_16x16x32_bf16 v[50:53], v[182:185], v[202:205], v[50:53]
	v_mfma_f32_16x16x32_bf16 v[38:41], v[174:177], v[212:215], v[38:41]
	v_mfma_f32_16x16x32_bf16 v[34:37], v[182:185], v[212:215], v[34:37]
	v_mfma_f32_16x16x32_bf16 v[22:25], v[174:177], v[220:223], v[22:25]
	v_mfma_f32_16x16x32_bf16 v[18:21], v[182:185], v[220:223], v[18:21]
	v_mfma_f32_16x16x32_bf16 v[6:9], v[174:177], v[228:231], v[6:9]
	s_setprio 3
	s_barrier
	v_mfma_f32_16x16x32_bf16 v[2:5], v[182:185], v[228:231], v[2:5]
	s_setprio 0
	s_add_i32 vcc_lo, vcc_lo, 2
	s_add_u32 s84, s84, 0x100
	s_addc_u32 s85, s85, 0
	s_add_u32 s73, s73, 0x100
	s_addc_u32 s75, s75, 0
	s_cmp_gt_u32 vcc_lo, 13
	s_cbranch_scc0 .LBB0_141
	s_and_b64 vcc, exec, s[26:27]
	s_cbranch_vccz .LBB0_144
	s_barrier

; #define PG8_STAGE(bufoff, gbase, voff) do { _Pragma("unroll") for (int _i = 0; _i < 2; ++_i) \
;         __builtin_amdgcn_global_load_lds((const unsigned*)((const char*)(gbase) + (voff)[_i]), (PG8_LAS unsigned*)(lds + (bufoff) + ldsw + _i * 8192), 16, 0, 0); } while (0)
; #define PG8_LDA(dst, b, h) do { _Pragma("unroll") for (int m = 0; m < 4; ++m) _Pragma("unroll") for (int k = 0; k < 2; ++k) dst[m][k] = *(const PG8_LAS bf16x8*)(lds + PG8_SA(b, h) + aoff + m * 2048 + k * 1024); } while (0)
; #define PG8_LDB(dst, b, h) do { _Pragma("unroll") for (int n = 0; n < 2; ++n) _Pragma("unroll") for (int k = 0; k < 2; ++k) dst[n][k] = *(const PG8_LAS bf16x8*)(lds + PG8_SB(b, h) + boff + n * 2048 + k * 1024); } while (0)
; #define PG8_MMA(ai, bj, At, Bt) do { __builtin_amdgcn_s_setprio(1); _Pragma("unroll") for (int m = 0; m < 4; ++m) _Pragma("unroll") for (int n = 0; n < 2; ++n) _Pragma("unroll") for (int k = 0; k < 2; ++k) \
;         acc[ai][bj][m][n] = __builtin_amdgcn_mfma_f32_16x16x32_bf16(Bt[n][k], At[m][k], acc[ai][bj][m][n], 0, 0, 0); __builtin_amdgcn_s_setprio(0); } while (0)
; #define PG8_WAIT_V(n) asm volatile("s_waitcnt vmcnt(" #n ")" ::: "memory")
; template <class Epi, class Sched, bool ALIGN_EPI = false, bool SP2 = false>
; __device__ __forceinline__ void gemm_phase(PG8_LAS unsigned char* lds, const Gemm g, const Sched& S, const Epi& E) {
;     ...
;             PG8_LDB(B0, 0, 0); PG8_LDB(B1, 0, 1); PG8_SCHED; PG8_LDA(At, 0, 0); PG8_STAGE(PG8_SA(1, 1), a1 + hstep, voffA);
;             PG8_WAIT_V(8); PG8_WAIT_L(0); PG8_BAR; PG8_MMA(0, 0, At, B0); PG8_MMA(0, 1, At, B1); PG8_BAR; PG8_SCHED;
;             PG8_LDA(At, 0, 1); PG8_STAGE(PG8_SB(0, 0), b2, voffB); PG8_STAGE(PG8_SB(0, 1), b2 + hstep, voffB); PG8_STAGE(PG8_SA(0, 0), a2, voffA);
;             PG8_WAIT_V(8); PG8_WAIT_L(0); PG8_BAR; PG8_MMA(1, 0, At, B0); PG8_MMA(1, 1, At, B1); PG8_BAR; PG8_SCHED;
;             PG8_LDB(B0, 1, 0); PG8_LDB(B1, 1, 1); PG8_SCHED; PG8_LDA(At, 1, 0); PG8_STAGE(PG8_SA(0, 1), a2 + hstep, voffA);
;             PG8_WAIT_V(8); PG8_WAIT_L(0); PG8_BAR; PG8_MMA(0, 0, At, B0); PG8_MMA(0, 1, At, B1); PG8_BAR; PG8_SCHED;
;             PG8_LDA(At, 1, 1); PG8_STAGE(PG8_SB(1, 0), b3, voffB); PG8_STAGE(PG8_SB(1, 1), b3 + hstep, voffB); PG8_STAGE(PG8_SA(1, 0), a3, voffA);
;             PG8_WAIT_V(8); PG8_WAIT_L(0); PG8_BAR; PG8_MMA(1, 0, At, B0); PG8_MMA(1, 1, At, B1); PG8_BAR; PG8_SCHED;
.LBB0_609:
	ds_read_b128 v[98:101], v239
	ds_read_b128 v[110:113], v239 offset:1024
	ds_read_b128 v[122:125], v239 offset:2048
	ds_read_b128 v[134:137], v239 offset:3072
	ds_read_b128 v[138:141], v240
	ds_read_b128 v[142:145], v240 offset:1024
	ds_read_b128 v[146:149], v240 offset:2048
	ds_read_b128 v[150:153], v240 offset:3072
	s_add_u32 s18, s40, 0xfffc0080
	s_addc_u32 s19, s41, -1
	s_cmp_eq_u32 s62, 12
	s_cselect_b32 s43, s27, s19
	s_cselect_b32 s42, s39, s18
	s_cselect_b32 s31, s17, s61
	s_cselect_b32 s30, s59, s60
	v_lshl_add_u64 v[208:209], s[40:41], 0, v[198:199]
	s_add_i32 m0, s45, 0xc000
	ds_read_b128 v[162:165], v241
	ds_read_b128 v[166:169], v241 offset:1024
	ds_read_b128 v[170:173], v241 offset:2048
	ds_read_b128 v[174:177], v241 offset:3072
	ds_read_b128 v[178:181], v241 offset:4096
	ds_read_b128 v[182:185], v241 offset:5120
	ds_read_b128 v[186:189], v241 offset:6144
	ds_read_b128 v[204:207], v241 offset:7168
	global_load_lds_dwordx4 v[208:209], off
	v_lshl_add_u64 v[208:209], s[40:41], 0, v[200:201]
	s_add_i32 m0, s45, 0xe000
	s_nop 0
	global_load_lds_dwordx4 v[208:209], off
	s_waitcnt vmcnt(8)
	s_waitcnt lgkmcnt(0)
	s_setprio 1
	s_barrier
	s_waitcnt lgkmcnt(0)
	v_mfma_f32_16x16x32_bf16 v[158:161], v[98:101], v[162:165], v[158:161]
	v_mfma_f32_16x16x32_bf16 v[154:157], v[122:125], v[162:165], v[154:157]
	v_mfma_f32_16x16x32_bf16 v[118:121], v[98:101], v[170:173], v[118:121]
	v_mfma_f32_16x16x32_bf16 v[114:117], v[122:125], v[170:173], v[114:117]
	v_mfma_f32_16x16x32_bf16 v[94:97], v[98:101], v[178:181], v[94:97]
	v_mfma_f32_16x16x32_bf16 v[90:93], v[122:125], v[178:181], v[90:93]
	v_mfma_f32_16x16x32_bf16 v[78:81], v[98:101], v[186:189], v[78:81]
	v_mfma_f32_16x16x32_bf16 v[74:77], v[122:125], v[186:189], v[74:77]
	v_mfma_f32_16x16x32_bf16 v[158:161], v[110:113], v[166:169], v[158:161]
	v_mfma_f32_16x16x32_bf16 v[154:157], v[134:137], v[166:169], v[154:157]
	v_mfma_f32_16x16x32_bf16 v[118:121], v[110:113], v[174:177], v[118:121]
	v_mfma_f32_16x16x32_bf16 v[114:117], v[134:137], v[174:177], v[114:117]
	v_mfma_f32_16x16x32_bf16 v[94:97], v[110:113], v[182:185], v[94:97]
	v_mfma_f32_16x16x32_bf16 v[90:93], v[134:137], v[182:185], v[90:93]
	v_mfma_f32_16x16x32_bf16 v[78:81], v[110:113], v[204:207], v[78:81]
	v_mfma_f32_16x16x32_bf16 v[74:77], v[134:137], v[204:207], v[74:77]
	s_setprio 0
	s_setprio 1
	v_mfma_f32_16x16x32_bf16 v[130:133], v[138:141], v[162:165], v[130:133]
	v_mfma_f32_16x16x32_bf16 v[126:129], v[146:149], v[162:165], v[126:129]
	v_mfma_f32_16x16x32_bf16 v[106:109], v[138:141], v[170:173], v[106:109]
	v_mfma_f32_16x16x32_bf16 v[102:105], v[146:149], v[170:173], v[102:105]
	v_mfma_f32_16x16x32_bf16 v[86:89], v[138:141], v[178:181], v[86:89]
	v_mfma_f32_16x16x32_bf16 v[82:85], v[146:149], v[178:181], v[82:85]
	v_mfma_f32_16x16x32_bf16 v[70:73], v[138:141], v[186:189], v[70:73]
	v_mfma_f32_16x16x32_bf16 v[66:69], v[146:149], v[186:189], v[66:69]
	v_mfma_f32_16x16x32_bf16 v[130:133], v[142:145], v[166:169], v[130:133]
	v_mfma_f32_16x16x32_bf16 v[126:129], v[150:153], v[166:169], v[126:129]
	v_mfma_f32_16x16x32_bf16 v[106:109], v[142:145], v[174:177], v[106:109]
	v_mfma_f32_16x16x32_bf16 v[102:105], v[150:153], v[174:177], v[102:105]
	v_mfma_f32_16x16x32_bf16 v[86:89], v[142:145], v[182:185], v[86:89]
	v_mfma_f32_16x16x32_bf16 v[82:85], v[150:153], v[182:185], v[82:85]
	v_mfma_f32_16x16x32_bf16 v[70:73], v[142:145], v[204:207], v[70:73]
	s_setprio 3
	s_barrier
	v_mfma_f32_16x16x32_bf16 v[66:69], v[150:153], v[204:207], v[66:69]
	s_setprio 0
	s_add_i32 s18, s56, s44
	v_lshl_add_u64 v[208:209], s[30:31], 0, v[192:193]
	s_mov_b32 m0, s18
	ds_read_b128 v[162:165], v241 offset:16384
	ds_read_b128 v[166:169], v241 offset:17408
	ds_read_b128 v[170:173], v241 offset:18432
	ds_read_b128 v[174:177], v241 offset:19456
	ds_read_b128 v[178:181], v241 offset:20480
	ds_read_b128 v[182:185], v241 offset:21504
	ds_read_b128 v[186:189], v241 offset:22528
	ds_read_b128 v[204:207], v241 offset:23552
	global_load_lds_dwordx4 v[208:209], off
	s_add_i32 m0, s18, 0x2000
	s_add_u32 s18, s30, 0x40000
	v_lshl_add_u64 v[210:211], s[30:31], 0, v[196:197]
	s_addc_u32 s19, s31, 0
	s_add_i32 s63, s57, s44
	global_load_lds_dwordx4 v[210:211], off
	v_lshl_add_u64 v[212:213], s[18:19], 0, v[192:193]
	s_mov_b32 m0, s63
	v_lshl_add_u64 v[214:215], s[42:43], 0, v[194:195]
	global_load_lds_dwordx4 v[212:213], off
	v_lshl_add_u64 v[212:213], s[18:19], 0, v[196:197]
	s_add_i32 m0, s63, 0x2000
	s_nop 0
	global_load_lds_dwordx4 v[212:213], off
	v_lshl_add_u64 v[212:213], s[42:43], 0, v[190:191]
	s_mov_b32 m0, s45
	s_nop 0
	global_load_lds_dwordx4 v[212:213], off
	s_mov_b32 m0, s46
	s_nop 0
	global_load_lds_dwordx4 v[214:215], off
	s_waitcnt vmcnt(8)
	s_waitcnt lgkmcnt(0)
	s_setprio 1
	s_barrier
; #define PG8_STAGE(bufoff, gbase, voff) do { _Pragma("unroll") for (int _i = 0; _i < 2; ++_i) \
;         __builtin_amdgcn_global_load_lds((const unsigned*)((const char*)(gbase) + (voff)[_i]), (PG8_LAS unsigned*)(lds + (bufoff) + ldsw + _i * 8192), 16, 0, 0); } while (0)
; #define PG8_LDA(dst, b, h) do { _Pragma("unroll") for (int m = 0; m < 4; ++m) _Pragma("unroll") for (int k = 0; k < 2; ++k) dst[m][k] = *(const PG8_LAS bf16x8*)(lds + PG8_SA(b, h) + aoff + m * 2048 + k * 1024); } while (0)
; #define PG8_LDB(dst, b, h) do { _Pragma("unroll") for (int n = 0; n < 2; ++n) _Pragma("unroll") for (int k = 0; k < 2; ++k) dst[n][k] = *(const PG8_LAS bf16x8*)(lds + PG8_SB(b, h) + boff + n * 2048 + k * 1024); } while (0)
; #define PG8_MMA(ai, bj, At, Bt) do { __builtin_amdgcn_s_setprio(1); _Pragma("unroll") for (int m = 0; m < 4; ++m) _Pragma("unroll") for (int n = 0; n < 2; ++n) _Pragma("unroll") for (int k = 0; k < 2; ++k) \
;         acc[ai][bj][m][n] = __builtin_amdgcn_mfma_f32_16x16x32_bf16(Bt[n][k], At[m][k], acc[ai][bj][m][n], 0, 0, 0); __builtin_amdgcn_s_setprio(0); } while (0)
; #define PG8_WAIT_V(n) asm volatile("s_waitcnt vmcnt(" #n ")" ::: "memory")
; template <class Epi, class Sched, bool ALIGN_EPI = false, bool SP2 = false>
; __device__ __forceinline__ void gemm_phase(PG8_LAS unsigned char* lds, const Gemm g, const Sched& S, const Epi& E) {
;     ...
;             PG8_LDB(B0, 0, 0); PG8_LDB(B1, 0, 1); PG8_SCHED; PG8_LDA(At, 0, 0); PG8_STAGE(PG8_SA(1, 1), a1 + hstep, voffA);
;             PG8_WAIT_V(8); PG8_WAIT_L(0); PG8_BAR; PG8_MMA(0, 0, At, B0); PG8_MMA(0, 1, At, B1); PG8_BAR; PG8_SCHED;
;             PG8_LDA(At, 0, 1); PG8_STAGE(PG8_SB(0, 0), b2, voffB); PG8_STAGE(PG8_SB(0, 1), b2 + hstep, voffB); PG8_STAGE(PG8_SA(0, 0), a2, voffA);
;             PG8_WAIT_V(8); PG8_WAIT_L(0); PG8_BAR; PG8_MMA(1, 0, At, B0); PG8_MMA(1, 1, At, B1); PG8_BAR; PG8_SCHED;
;             PG8_LDB(B0, 1, 0); PG8_LDB(B1, 1, 1); PG8_SCHED; PG8_LDA(At, 1, 0); PG8_STAGE(PG8_SA(0, 1), a2 + hstep, voffA);
;             PG8_WAIT_V(8); PG8_WAIT_L(0); PG8_BAR; PG8_MMA(0, 0, At, B0); PG8_MMA(0, 1, At, B1); PG8_BAR; PG8_SCHED;
;             PG8_LDA(At, 1, 1); PG8_STAGE(PG8_SB(1, 0), b3, voffB); PG8_STAGE(PG8_SB(1, 1), b3 + hstep, voffB); PG8_STAGE(PG8_SA(1, 0), a3, voffA);
;             PG8_WAIT_V(8); PG8_WAIT_L(0); PG8_BAR; PG8_MMA(1, 0, At, B0); PG8_MMA(1, 1, At, B1); PG8_BAR; PG8_SCHED;
	s_waitcnt lgkmcnt(0)
	v_mfma_f32_16x16x32_bf16 v[62:65], v[98:101], v[162:165], v[62:65]
	v_mfma_f32_16x16x32_bf16 v[58:61], v[122:125], v[162:165], v[58:61]
	v_mfma_f32_16x16x32_bf16 v[46:49], v[98:101], v[170:173], v[46:49]
	v_mfma_f32_16x16x32_bf16 v[42:45], v[122:125], v[170:173], v[42:45]
	v_mfma_f32_16x16x32_bf16 v[30:33], v[98:101], v[178:181], v[30:33]
	v_mfma_f32_16x16x32_bf16 v[26:29], v[122:125], v[178:181], v[26:29]
	v_mfma_f32_16x16x32_bf16 v[14:17], v[98:101], v[186:189], v[14:17]
	v_mfma_f32_16x16x32_bf16 v[10:13], v[122:125], v[186:189], v[10:13]
	v_mfma_f32_16x16x32_bf16 v[62:65], v[110:113], v[166:169], v[62:65]
	v_mfma_f32_16x16x32_bf16 v[58:61], v[134:137], v[166:169], v[58:61]
	v_mfma_f32_16x16x32_bf16 v[46:49], v[110:113], v[174:177], v[46:49]
	v_mfma_f32_16x16x32_bf16 v[42:45], v[134:137], v[174:177], v[42:45]
	v_mfma_f32_16x16x32_bf16 v[30:33], v[110:113], v[182:185], v[30:33]
	v_mfma_f32_16x16x32_bf16 v[26:29], v[134:137], v[182:185], v[26:29]
	v_mfma_f32_16x16x32_bf16 v[14:17], v[110:113], v[204:207], v[14:17]
	v_mfma_f32_16x16x32_bf16 v[10:13], v[134:137], v[204:207], v[10:13]
	s_setprio 0
	s_setprio 1
	v_mfma_f32_16x16x32_bf16 v[54:57], v[138:141], v[162:165], v[54:57]
	v_mfma_f32_16x16x32_bf16 v[50:53], v[146:149], v[162:165], v[50:53]
	v_mfma_f32_16x16x32_bf16 v[38:41], v[138:141], v[170:173], v[38:41]
	v_mfma_f32_16x16x32_bf16 v[34:37], v[146:149], v[170:173], v[34:37]
	v_mfma_f32_16x16x32_bf16 v[22:25], v[138:141], v[178:181], v[22:25]
	v_mfma_f32_16x16x32_bf16 v[18:21], v[146:149], v[178:181], v[18:21]
	v_mfma_f32_16x16x32_bf16 v[6:9], v[138:141], v[186:189], v[6:9]
	v_mfma_f32_16x16x32_bf16 v[2:5], v[146:149], v[186:189], v[2:5]
	v_mfma_f32_16x16x32_bf16 v[54:57], v[142:145], v[166:169], v[54:57]
	v_mfma_f32_16x16x32_bf16 v[50:53], v[150:153], v[166:169], v[50:53]
	v_mfma_f32_16x16x32_bf16 v[38:41], v[142:145], v[174:177], v[38:41]
	v_mfma_f32_16x16x32_bf16 v[34:37], v[150:153], v[174:177], v[34:37]
	v_mfma_f32_16x16x32_bf16 v[22:25], v[142:145], v[182:185], v[22:25]
	v_mfma_f32_16x16x32_bf16 v[18:21], v[150:153], v[182:185], v[18:21]
	v_mfma_f32_16x16x32_bf16 v[6:9], v[142:145], v[204:207], v[6:9]
	s_setprio 3
	s_barrier
	v_mfma_f32_16x16x32_bf16 v[2:5], v[150:153], v[204:207], v[2:5]
	s_setprio 0
	s_add_i32 s63, 0, 0x18000
	s_add_i32 s64, 0, 0x1c000
	v_add_u32_e32 v134, s63, v237
	v_add_u32_e32 v150, s64, v237
	ds_read_b128 v[98:101], v134
	ds_read_b128 v[110:113], v134 offset:1024
	ds_read_b128 v[122:125], v134 offset:2048
	ds_read_b128 v[134:137], v134 offset:3072
	ds_read_b128 v[138:141], v150
	ds_read_b128 v[142:145], v150 offset:1024
	ds_read_b128 v[146:149], v150 offset:2048
	ds_read_b128 v[150:153], v150 offset:3072
	s_add_u32 s18, s42, 0x40000
	s_addc_u32 s19, s43, 0
	s_mov_b32 m0, s47
	v_lshl_add_u64 v[216:217], s[18:19], 0, v[190:191]
	ds_read_b128 v[162:165], v241 offset:32768
	ds_read_b128 v[166:169], v241 offset:33792
	ds_read_b128 v[170:173], v241 offset:34816
	ds_read_b128 v[174:177], v241 offset:35840
	ds_read_b128 v[178:181], v241 offset:36864
	ds_read_b128 v[182:185], v241 offset:37888
	ds_read_b128 v[186:189], v241 offset:38912
	ds_read_b128 v[204:207], v241 offset:39936
	global_load_lds_dwordx4 v[216:217], off
	v_lshl_add_u64 v[216:217], s[18:19], 0, v[194:195]
	s_mov_b32 m0, s48
	s_nop 0
	global_load_lds_dwordx4 v[216:217], off
	s_waitcnt vmcnt(8)
	s_waitcnt lgkmcnt(0)
	s_setprio 1
	s_barrier
	s_waitcnt lgkmcnt(0)
	v_mfma_f32_16x16x32_bf16 v[158:161], v[98:101], v[162:165], v[158:161]
	v_mfma_f32_16x16x32_bf16 v[154:157], v[122:125], v[162:165], v[154:157]
	v_mfma_f32_16x16x32_bf16 v[118:121], v[98:101], v[170:173], v[118:121]
	v_mfma_f32_16x16x32_bf16 v[114:117], v[122:125], v[170:173], v[114:117]
	v_mfma_f32_16x16x32_bf16 v[94:97], v[98:101], v[178:181], v[94:97]
	v_mfma_f32_16x16x32_bf16 v[90:93], v[122:125], v[178:181], v[90:93]
	v_mfma_f32_16x16x32_bf16 v[78:81], v[98:101], v[186:189], v[78:81]
	v_mfma_f32_16x16x32_bf16 v[74:77], v[122:125], v[186:189], v[74:77]
	v_mfma_f32_16x16x32_bf16 v[158:161], v[110:113], v[166:169], v[158:161]
	v_mfma_f32_16x16x32_bf16 v[154:157], v[134:137], v[166:169], v[154:157]
	v_mfma_f32_16x16x32_bf16 v[118:121], v[110:113], v[174:177], v[118:121]
	v_mfma_f32_16x16x32_bf16 v[114:117], v[134:137], v[174:177], v[114:117]
	v_mfma_f32_16x16x32_bf16 v[94:97], v[110:113], v[182:185], v[94:97]
	v_mfma_f32_16x16x32_bf16 v[90:93], v[134:137], v[182:185], v[90:93]
	v_mfma_f32_16x16x32_bf16 v[78:81], v[110:113], v[204:207], v[78:81]
	v_mfma_f32_16x16x32_bf16 v[74:77], v[134:137], v[204:207], v[74:77]
	s_setprio 0
	s_setprio 1
	v_mfma_f32_16x16x32_bf16 v[130:133], v[138:141], v[162:165], v[130:133]
	v_mfma_f32_16x16x32_bf16 v[126:129], v[146:149], v[162:165], v[126:129]
	v_mfma_f32_16x16x32_bf16 v[106:109], v[138:141], v[170:173], v[106:109]
	v_mfma_f32_16x16x32_bf16 v[102:105], v[146:149], v[170:173], v[102:105]
	v_mfma_f32_16x16x32_bf16 v[86:89], v[138:141], v[178:181], v[86:89]
	v_mfma_f32_16x16x32_bf16 v[82:85], v[146:149], v[178:181], v[82:85]
	v_mfma_f32_16x16x32_bf16 v[70:73], v[138:141], v[186:189], v[70:73]
	v_mfma_f32_16x16x32_bf16 v[66:69], v[146:149], v[186:189], v[66:69]
	v_mfma_f32_16x16x32_bf16 v[130:133], v[142:145], v[166:169], v[130:133]
	v_mfma_f32_16x16x32_bf16 v[126:129], v[150:153], v[166:169], v[126:129]
	v_mfma_f32_16x16x32_bf16 v[106:109], v[142:145], v[174:177], v[106:109]
	v_mfma_f32_16x16x32_bf16 v[102:105], v[150:153], v[174:177], v[102:105]
	v_mfma_f32_16x16x32_bf16 v[86:89], v[142:145], v[182:185], v[86:89]
	v_mfma_f32_16x16x32_bf16 v[82:85], v[150:153], v[182:185], v[82:85]
	v_mfma_f32_16x16x32_bf16 v[70:73], v[142:145], v[204:207], v[70:73]
	s_setprio 3
	s_barrier
; #define PG8_STAGE(bufoff, gbase, voff) do { _Pragma("unroll") for (int _i = 0; _i < 2; ++_i) \
;         __builtin_amdgcn_global_load_lds((const unsigned*)((const char*)(gbase) + (voff)[_i]), (PG8_LAS unsigned*)(lds + (bufoff) + ldsw + _i * 8192), 16, 0, 0); } while (0)
; #define PG8_LDA(dst, b, h) do { _Pragma("unroll") for (int m = 0; m < 4; ++m) _Pragma("unroll") for (int k = 0; k < 2; ++k) dst[m][k] = *(const PG8_LAS bf16x8*)(lds + PG8_SA(b, h) + aoff + m * 2048 + k * 1024); } while (0)
; #define PG8_LDB(dst, b, h) do { _Pragma("unroll") for (int n = 0; n < 2; ++n) _Pragma("unroll") for (int k = 0; k < 2; ++k) dst[n][k] = *(const PG8_LAS bf16x8*)(lds + PG8_SB(b, h) + boff + n * 2048 + k * 1024); } while (0)
; #define PG8_WAIT_V(n) asm volatile("s_waitcnt vmcnt(" #n ")" ::: "memory")
; #define PG8_WAIT_L(n) asm volatile("s_waitcnt lgkmcnt(" #n ")" ::: "memory")
;     __device__ __forceinline__ void operator()(const f32x4 (&acc)[2][2][4][2], const Unit& u, int wr, int wc, int fr, int fq) const {
;     ...
;                 for (int bj = 0; bj < 2; ++bj) bva[ai][m][bj] = *(const u32x4*)(Xb + (size_t)(row0 + ai * HALF + m * 16) * DM + col0 + bj * HALF);
; template <class Epi, class Sched, bool ALIGN_EPI = false, bool SP2 = false>
; __device__ __forceinline__ void gemm_phase(PG8_LAS unsigned char* lds, const Gemm g, const Sched& S, const Epi& E) {
;     ...
;             PG8_LDB(B0, 0, 0); PG8_LDB(B1, 0, 1); PG8_SCHED; PG8_LDA(At, 0, 0); PG8_STAGE(PG8_SA(1, 1), a1 + hstep, voffA);
;             PG8_WAIT_V(8); PG8_WAIT_L(0); PG8_BAR; PG8_MMA(0, 0, At, B0); PG8_MMA(0, 1, At, B1); PG8_BAR; PG8_SCHED;
;             PG8_LDA(At, 0, 1); PG8_STAGE(PG8_SB(0, 0), b2, voffB); PG8_STAGE(PG8_SB(0, 1), b2 + hstep, voffB); PG8_STAGE(PG8_SA(0, 0), a2, voffA);
;             PG8_WAIT_V(8); PG8_WAIT_L(0); PG8_BAR; PG8_MMA(1, 0, At, B0); PG8_MMA(1, 1, At, B1); PG8_BAR; PG8_SCHED;
;             PG8_LDB(B0, 1, 0); PG8_LDB(B1, 1, 1); PG8_SCHED; PG8_LDA(At, 1, 0); PG8_STAGE(PG8_SA(0, 1), a2 + hstep, voffA);
;             PG8_WAIT_V(8); PG8_WAIT_L(0); PG8_BAR; PG8_MMA(0, 0, At, B0); PG8_MMA(0, 1, At, B1); PG8_BAR; PG8_SCHED;
;             PG8_LDA(At, 1, 1); PG8_STAGE(PG8_SB(1, 0), b3, voffB); PG8_STAGE(PG8_SB(1, 1), b3 + hstep, voffB); PG8_STAGE(PG8_SA(1, 0), a3, voffA);
;             PG8_WAIT_V(8); PG8_WAIT_L(0); PG8_BAR; PG8_MMA(1, 0, At, B0); PG8_MMA(1, 1, At, B1); PG8_BAR; PG8_SCHED;
	v_mfma_f32_16x16x32_bf16 v[66:69], v[150:153], v[204:207], v[66:69]
	s_setprio 0
	s_add_i32 s18, s63, s44
	v_lshl_add_u64 v[208:209], v[208:209], 0, s[12:13]
	s_mov_b32 m0, s18
	ds_read_b128 v[162:165], v241 offset:49152
	ds_read_b128 v[166:169], v241 offset:50176
	ds_read_b128 v[170:173], v241 offset:51200
	ds_read_b128 v[174:177], v241 offset:52224
	ds_read_b128 v[178:181], v241 offset:53248
	ds_read_b128 v[182:185], v241 offset:54272
	ds_read_b128 v[186:189], v241 offset:55296
	ds_read_b128 v[204:207], v241 offset:56320
	global_load_lds_dwordx4 v[208:209], off
	s_add_i32 m0, s18, 0x2000
	s_add_u32 s18, s30, 0x40080
	v_lshl_add_u64 v[208:209], v[210:211], 0, s[12:13]
	s_addc_u32 s19, s31, 0
	s_add_i32 s30, s64, s44
	global_load_lds_dwordx4 v[208:209], off
	v_lshl_add_u64 v[208:209], s[18:19], 0, v[192:193]
	s_mov_b32 m0, s30
	s_nop 0
	global_load_lds_dwordx4 v[208:209], off
	v_lshl_add_u64 v[208:209], s[18:19], 0, v[196:197]
	s_add_i32 m0, s30, 0x2000
	s_nop 0
	global_load_lds_dwordx4 v[208:209], off
	v_lshl_add_u64 v[208:209], v[212:213], 0, s[12:13]
	s_mov_b32 m0, s52
	s_nop 0
	global_load_lds_dwordx4 v[208:209], off
	v_lshl_add_u64 v[208:209], v[214:215], 0, s[12:13]
	s_mov_b32 m0, s53
	s_nop 0
	global_load_lds_dwordx4 v[208:209], off
	s_waitcnt vmcnt(8)
	s_waitcnt lgkmcnt(0)
	s_setprio 1
	s_barrier
	s_waitcnt lgkmcnt(0)
	v_mfma_f32_16x16x32_bf16 v[62:65], v[98:101], v[162:165], v[62:65]
	v_mfma_f32_16x16x32_bf16 v[58:61], v[122:125], v[162:165], v[58:61]
	v_mfma_f32_16x16x32_bf16 v[46:49], v[98:101], v[170:173], v[46:49]
	v_mfma_f32_16x16x32_bf16 v[42:45], v[122:125], v[170:173], v[42:45]
	v_mfma_f32_16x16x32_bf16 v[30:33], v[98:101], v[178:181], v[30:33]
	v_mfma_f32_16x16x32_bf16 v[26:29], v[122:125], v[178:181], v[26:29]
	v_mfma_f32_16x16x32_bf16 v[14:17], v[98:101], v[186:189], v[14:17]
	v_mfma_f32_16x16x32_bf16 v[10:13], v[122:125], v[186:189], v[10:13]
	v_mfma_f32_16x16x32_bf16 v[62:65], v[110:113], v[166:169], v[62:65]
	v_mfma_f32_16x16x32_bf16 v[58:61], v[134:137], v[166:169], v[58:61]
	v_mfma_f32_16x16x32_bf16 v[46:49], v[110:113], v[174:177], v[46:49]
	v_mfma_f32_16x16x32_bf16 v[42:45], v[134:137], v[174:177], v[42:45]
	v_mfma_f32_16x16x32_bf16 v[30:33], v[110:113], v[182:185], v[30:33]
	v_mfma_f32_16x16x32_bf16 v[26:29], v[134:137], v[182:185], v[26:29]
	v_mfma_f32_16x16x32_bf16 v[14:17], v[110:113], v[204:207], v[14:17]
	v_mfma_f32_16x16x32_bf16 v[10:13], v[134:137], v[204:207], v[10:13]
	s_setprio 0
	s_setprio 1
	v_mfma_f32_16x16x32_bf16 v[54:57], v[138:141], v[162:165], v[54:57]
	v_mfma_f32_16x16x32_bf16 v[50:53], v[146:149], v[162:165], v[50:53]
	v_mfma_f32_16x16x32_bf16 v[38:41], v[138:141], v[170:173], v[38:41]
	v_mfma_f32_16x16x32_bf16 v[34:37], v[146:149], v[170:173], v[34:37]
	v_mfma_f32_16x16x32_bf16 v[22:25], v[138:141], v[178:181], v[22:25]
	v_mfma_f32_16x16x32_bf16 v[18:21], v[146:149], v[178:181], v[18:21]
	v_mfma_f32_16x16x32_bf16 v[6:9], v[138:141], v[186:189], v[6:9]
	v_mfma_f32_16x16x32_bf16 v[2:5], v[146:149], v[186:189], v[2:5]
	v_mfma_f32_16x16x32_bf16 v[54:57], v[142:145], v[166:169], v[54:57]
	v_mfma_f32_16x16x32_bf16 v[50:53], v[150:153], v[166:169], v[50:53]
	v_mfma_f32_16x16x32_bf16 v[38:41], v[142:145], v[174:177], v[38:41]
	v_mfma_f32_16x16x32_bf16 v[34:37], v[150:153], v[174:177], v[34:37]
	v_mfma_f32_16x16x32_bf16 v[22:25], v[142:145], v[182:185], v[22:25]
	v_mfma_f32_16x16x32_bf16 v[18:21], v[150:153], v[182:185], v[18:21]
	v_mfma_f32_16x16x32_bf16 v[6:9], v[142:145], v[204:207], v[6:9]
	s_setprio 3
	s_barrier
	v_mfma_f32_16x16x32_bf16 v[2:5], v[150:153], v[204:207], v[2:5]
	s_setprio 0
	s_add_i32 s62, s62, 2
	s_add_u32 s40, s40, 0x100
	s_addc_u32 s41, s41, 0
	s_add_u32 s60, s60, 0x100
	s_addc_u32 s61, s61, 0
	s_cmp_gt_u32 s62, 13
	s_cbranch_scc1 .Lrp_gen_p3
	s_cmp_lg_u32 s62, 12
	s_cbranch_scc1 .LBB0_609
	s_cmpk_lg_i32 s33, 0x100
	s_cbranch_scc1 .LBB0_609
	ds_read_b128 v[98:101], v239
	ds_read_b128 v[110:113], v239 offset:1024
	ds_read_b128 v[122:125], v239 offset:2048
	ds_read_b128 v[134:137], v239 offset:3072
	ds_read_b128 v[138:141], v240
	ds_read_b128 v[142:145], v240 offset:1024
	ds_read_b128 v[146:149], v240 offset:2048
	ds_read_b128 v[150:153], v240 offset:3072
	s_add_u32 s18, s40, 0xfffc0080
	s_addc_u32 s19, s41, -1
	s_cmp_eq_u32 s62, 12
	s_cselect_b32 s43, s27, s19
	s_cselect_b32 s42, s39, s18
	s_cselect_b32 s31, s17, s61
	s_cselect_b32 s30, s59, s60
	v_lshl_add_u64 v[208:209], s[40:41], 0, v[198:199]
	s_add_i32 m0, s45, 0xc000
	ds_read_b128 v[162:165], v241
	ds_read_b128 v[166:169], v241 offset:1024
	ds_read_b128 v[170:173], v241 offset:2048
	ds_read_b128 v[174:177], v241 offset:3072
	ds_read_b128 v[178:181], v241 offset:4096
	ds_read_b128 v[182:185], v241 offset:5120
	ds_read_b128 v[186:189], v241 offset:6144
	ds_read_b128 v[204:207], v241 offset:7168
	global_load_lds_dwordx4 v[208:209], off
	v_lshl_add_u64 v[208:209], s[40:41], 0, v[200:201]
	s_add_i32 m0, s45, 0xe000
	s_nop 0
	global_load_lds_dwordx4 v[208:209], off
	v_lshl_or_b32 v255, s0, 8, v238
	v_lshl_add_u32 v235, s38, 8, v1
	v_lshlrev_b32_e32 v255, 1, v255
	v_lshl_add_u32 v255, v235, 11, v255
	s_mov_b64 s[84:85], s[20:21]
	global_load_dwordx4 v[242:245], v255, s[84:85]
	global_load_dwordx4 v[208:211], v255, s[84:85] offset:256
	s_add_u32 s84, s20, 0x8000
	s_addc_u32 s85, s21, 0
	global_load_dwordx4 v[212:215], v255, s[84:85]
	global_load_dwordx4 v[216:219], v255, s[84:85] offset:256
	s_add_u32 s84, s20, 0x10000
	s_addc_u32 s85, s21, 0
	global_load_dwordx4 v[220:223], v255, s[84:85]
	global_load_dwordx4 v[224:227], v255, s[84:85] offset:256
	s_add_u32 s84, s20, 0x18000
	s_addc_u32 s85, s21, 0
	global_load_dwordx4 v[228:231], v255, s[84:85]
	global_load_dwordx4 v[232:235], v255, s[84:85] offset:256
	s_add_u32 s84, s20, 0x40000
	s_addc_u32 s85, s21, 0
	global_load_dwordx4 v[246:249], v255, s[84:85]
	global_load_dwordx4 v[250:253], v255, s[84:85] offset:256
	s_waitcnt vmcnt(18)
	s_waitcnt lgkmcnt(0)
	s_setprio 1
	s_barrier
; #define PG8_STAGE(bufoff, gbase, voff) do { _Pragma("unroll") for (int _i = 0; _i < 2; ++_i) \
;         __builtin_amdgcn_global_load_lds((const unsigned*)((const char*)(gbase) + (voff)[_i]), (PG8_LAS unsigned*)(lds + (bufoff) + ldsw + _i * 8192), 16, 0, 0); } while (0)
; #define PG8_LDA(dst, b, h) do { _Pragma("unroll") for (int m = 0; m < 4; ++m) _Pragma("unroll") for (int k = 0; k < 2; ++k) dst[m][k] = *(const PG8_LAS bf16x8*)(lds + PG8_SA(b, h) + aoff + m * 2048 + k * 1024); } while (0)
; #define PG8_LDB(dst, b, h) do { _Pragma("unroll") for (int n = 0; n < 2; ++n) _Pragma("unroll") for (int k = 0; k < 2; ++k) dst[n][k] = *(const PG8_LAS bf16x8*)(lds + PG8_SB(b, h) + boff + n * 2048 + k * 1024); } while (0)
; #define PG8_MMA(ai, bj, At, Bt) do { __builtin_amdgcn_s_setprio(1); _Pragma("unroll") for (int m = 0; m < 4; ++m) _Pragma("unroll") for (int n = 0; n < 2; ++n) _Pragma("unroll") for (int k = 0; k < 2; ++k) \
;         acc[ai][bj][m][n] = __builtin_amdgcn_mfma_f32_16x16x32_bf16(Bt[n][k], At[m][k], acc[ai][bj][m][n], 0, 0, 0); __builtin_amdgcn_s_setprio(0); } while (0)
; #define PG8_WAIT_V(n) asm volatile("s_waitcnt vmcnt(" #n ")" ::: "memory")
; template <class Epi, class Sched, bool ALIGN_EPI = false, bool SP2 = false>
; __device__ __forceinline__ void gemm_phase(PG8_LAS unsigned char* lds, const Gemm g, const Sched& S, const Epi& E) {
;     ...
;             PG8_LDB(B0, 0, 0); PG8_LDB(B1, 0, 1); PG8_SCHED; PG8_LDA(At, 0, 0); PG8_STAGE(PG8_SA(1, 1), a1 + hstep, voffA);
;             PG8_WAIT_V(8); PG8_WAIT_L(0); PG8_BAR; PG8_MMA(0, 0, At, B0); PG8_MMA(0, 1, At, B1); PG8_BAR; PG8_SCHED;
;             PG8_LDA(At, 0, 1); PG8_STAGE(PG8_SB(0, 0), b2, voffB); PG8_STAGE(PG8_SB(0, 1), b2 + hstep, voffB); PG8_STAGE(PG8_SA(0, 0), a2, voffA);
;             PG8_WAIT_V(8); PG8_WAIT_L(0); PG8_BAR; PG8_MMA(1, 0, At, B0); PG8_MMA(1, 1, At, B1); PG8_BAR; PG8_SCHED;
;             PG8_LDB(B0, 1, 0); PG8_LDB(B1, 1, 1); PG8_SCHED; PG8_LDA(At, 1, 0); PG8_STAGE(PG8_SA(0, 1), a2 + hstep, voffA);
;             PG8_WAIT_V(8); PG8_WAIT_L(0); PG8_BAR; PG8_MMA(0, 0, At, B0); PG8_MMA(0, 1, At, B1); PG8_BAR; PG8_SCHED;
;             PG8_LDA(At, 1, 1); PG8_STAGE(PG8_SB(1, 0), b3, voffB); PG8_STAGE(PG8_SB(1, 1), b3 + hstep, voffB); PG8_STAGE(PG8_SA(1, 0), a3, voffA);
;             PG8_WAIT_V(8); PG8_WAIT_L(0); PG8_BAR; PG8_MMA(1, 0, At, B0); PG8_MMA(1, 1, At, B1); PG8_BAR; PG8_SCHED;
	s_waitcnt lgkmcnt(0)
	v_mfma_f32_16x16x32_bf16 v[158:161], v[98:101], v[162:165], v[158:161]
	v_mfma_f32_16x16x32_bf16 v[154:157], v[122:125], v[162:165], v[154:157]
	v_mfma_f32_16x16x32_bf16 v[118:121], v[98:101], v[170:173], v[118:121]
	v_mfma_f32_16x16x32_bf16 v[114:117], v[122:125], v[170:173], v[114:117]
	v_mfma_f32_16x16x32_bf16 v[94:97], v[98:101], v[178:181], v[94:97]
	v_mfma_f32_16x16x32_bf16 v[90:93], v[122:125], v[178:181], v[90:93]
	v_mfma_f32_16x16x32_bf16 v[78:81], v[98:101], v[186:189], v[78:81]
	v_mfma_f32_16x16x32_bf16 v[74:77], v[122:125], v[186:189], v[74:77]
	v_mfma_f32_16x16x32_bf16 v[158:161], v[110:113], v[166:169], v[158:161]
	v_mfma_f32_16x16x32_bf16 v[154:157], v[134:137], v[166:169], v[154:157]
	v_mfma_f32_16x16x32_bf16 v[118:121], v[110:113], v[174:177], v[118:121]
	v_mfma_f32_16x16x32_bf16 v[114:117], v[134:137], v[174:177], v[114:117]
	v_mfma_f32_16x16x32_bf16 v[94:97], v[110:113], v[182:185], v[94:97]
	v_mfma_f32_16x16x32_bf16 v[90:93], v[134:137], v[182:185], v[90:93]
	v_mfma_f32_16x16x32_bf16 v[78:81], v[110:113], v[204:207], v[78:81]
	v_mfma_f32_16x16x32_bf16 v[74:77], v[134:137], v[204:207], v[74:77]
	s_setprio 0
	s_setprio 1
	v_mfma_f32_16x16x32_bf16 v[130:133], v[138:141], v[162:165], v[130:133]
	v_mfma_f32_16x16x32_bf16 v[126:129], v[146:149], v[162:165], v[126:129]
	v_mfma_f32_16x16x32_bf16 v[106:109], v[138:141], v[170:173], v[106:109]
	v_mfma_f32_16x16x32_bf16 v[102:105], v[146:149], v[170:173], v[102:105]
	v_mfma_f32_16x16x32_bf16 v[86:89], v[138:141], v[178:181], v[86:89]
	v_mfma_f32_16x16x32_bf16 v[82:85], v[146:149], v[178:181], v[82:85]
	v_mfma_f32_16x16x32_bf16 v[70:73], v[138:141], v[186:189], v[70:73]
	v_mfma_f32_16x16x32_bf16 v[66:69], v[146:149], v[186:189], v[66:69]
	v_mfma_f32_16x16x32_bf16 v[130:133], v[142:145], v[166:169], v[130:133]
	v_mfma_f32_16x16x32_bf16 v[126:129], v[150:153], v[166:169], v[126:129]
	v_mfma_f32_16x16x32_bf16 v[106:109], v[142:145], v[174:177], v[106:109]
	v_mfma_f32_16x16x32_bf16 v[102:105], v[150:153], v[174:177], v[102:105]
	v_mfma_f32_16x16x32_bf16 v[86:89], v[142:145], v[182:185], v[86:89]
	v_mfma_f32_16x16x32_bf16 v[82:85], v[150:153], v[182:185], v[82:85]
	v_mfma_f32_16x16x32_bf16 v[70:73], v[142:145], v[204:207], v[70:73]
	s_setprio 3
	s_barrier
	v_mfma_f32_16x16x32_bf16 v[66:69], v[150:153], v[204:207], v[66:69]
	s_setprio 0
	s_add_i32 s18, s56, s44
	s_mov_b32 m0, s18
	ds_read_b128 v[162:165], v241 offset:16384
	ds_read_b128 v[166:169], v241 offset:17408
	ds_read_b128 v[170:173], v241 offset:18432
	ds_read_b128 v[174:177], v241 offset:19456
	ds_read_b128 v[178:181], v241 offset:20480
	ds_read_b128 v[182:185], v241 offset:21504
	ds_read_b128 v[186:189], v241 offset:22528
	ds_read_b128 v[204:207], v241 offset:23552
	s_add_i32 m0, s18, 0x2000
	s_add_u32 s18, s30, 0x40000
	s_addc_u32 s19, s31, 0
	s_add_i32 s63, s57, s44
	s_mov_b32 m0, s63
	s_add_i32 m0, s63, 0x2000
	s_nop 0
	s_mov_b32 m0, s45
	s_nop 0
	s_mov_b32 m0, s46
	s_nop 0
	s_waitcnt vmcnt(12)
	s_waitcnt lgkmcnt(0)
	s_setprio 1
	s_barrier
	s_waitcnt lgkmcnt(0)
	v_mfma_f32_16x16x32_bf16 v[62:65], v[98:101], v[162:165], v[62:65]
	v_mfma_f32_16x16x32_bf16 v[58:61], v[122:125], v[162:165], v[58:61]
	v_mfma_f32_16x16x32_bf16 v[46:49], v[98:101], v[170:173], v[46:49]
	v_mfma_f32_16x16x32_bf16 v[42:45], v[122:125], v[170:173], v[42:45]
	v_mfma_f32_16x16x32_bf16 v[30:33], v[98:101], v[178:181], v[30:33]
	v_mfma_f32_16x16x32_bf16 v[26:29], v[122:125], v[178:181], v[26:29]
	v_mfma_f32_16x16x32_bf16 v[14:17], v[98:101], v[186:189], v[14:17]
	v_mfma_f32_16x16x32_bf16 v[10:13], v[122:125], v[186:189], v[10:13]
	v_mfma_f32_16x16x32_bf16 v[62:65], v[110:113], v[166:169], v[62:65]
	v_mfma_f32_16x16x32_bf16 v[58:61], v[134:137], v[166:169], v[58:61]
	v_mfma_f32_16x16x32_bf16 v[46:49], v[110:113], v[174:177], v[46:49]
	v_mfma_f32_16x16x32_bf16 v[42:45], v[134:137], v[174:177], v[42:45]
	v_mfma_f32_16x16x32_bf16 v[30:33], v[110:113], v[182:185], v[30:33]
	v_mfma_f32_16x16x32_bf16 v[26:29], v[134:137], v[182:185], v[26:29]
	v_mfma_f32_16x16x32_bf16 v[14:17], v[110:113], v[204:207], v[14:17]
	v_mfma_f32_16x16x32_bf16 v[10:13], v[134:137], v[204:207], v[10:13]
	s_setprio 0
	s_setprio 1
	v_mfma_f32_16x16x32_bf16 v[54:57], v[138:141], v[162:165], v[54:57]
	v_mfma_f32_16x16x32_bf16 v[50:53], v[146:149], v[162:165], v[50:53]
	v_mfma_f32_16x16x32_bf16 v[38:41], v[138:141], v[170:173], v[38:41]
	v_mfma_f32_16x16x32_bf16 v[34:37], v[146:149], v[170:173], v[34:37]
	v_mfma_f32_16x16x32_bf16 v[22:25], v[138:141], v[178:181], v[22:25]
	v_mfma_f32_16x16x32_bf16 v[18:21], v[146:149], v[178:181], v[18:21]
	v_mfma_f32_16x16x32_bf16 v[6:9], v[138:141], v[186:189], v[6:9]
	v_mfma_f32_16x16x32_bf16 v[2:5], v[146:149], v[186:189], v[2:5]
	v_mfma_f32_16x16x32_bf16 v[54:57], v[142:145], v[166:169], v[54:57]
	v_mfma_f32_16x16x32_bf16 v[50:53], v[150:153], v[166:169], v[50:53]
	v_mfma_f32_16x16x32_bf16 v[38:41], v[142:145], v[174:177], v[38:41]
	v_mfma_f32_16x16x32_bf16 v[34:37], v[150:153], v[174:177], v[34:37]
	v_mfma_f32_16x16x32_bf16 v[22:25], v[142:145], v[182:185], v[22:25]
	v_mfma_f32_16x16x32_bf16 v[18:21], v[150:153], v[182:185], v[18:21]
	v_mfma_f32_16x16x32_bf16 v[6:9], v[142:145], v[204:207], v[6:9]
	s_setprio 3
	s_barrier
; #define PG8_STAGE(bufoff, gbase, voff) do { _Pragma("unroll") for (int _i = 0; _i < 2; ++_i) \
;         __builtin_amdgcn_global_load_lds((const unsigned*)((const char*)(gbase) + (voff)[_i]), (PG8_LAS unsigned*)(lds + (bufoff) + ldsw + _i * 8192), 16, 0, 0); } while (0)
; #define PG8_LDA(dst, b, h) do { _Pragma("unroll") for (int m = 0; m < 4; ++m) _Pragma("unroll") for (int k = 0; k < 2; ++k) dst[m][k] = *(const PG8_LAS bf16x8*)(lds + PG8_SA(b, h) + aoff + m * 2048 + k * 1024); } while (0)
; #define PG8_LDB(dst, b, h) do { _Pragma("unroll") for (int n = 0; n < 2; ++n) _Pragma("unroll") for (int k = 0; k < 2; ++k) dst[n][k] = *(const PG8_LAS bf16x8*)(lds + PG8_SB(b, h) + boff + n * 2048 + k * 1024); } while (0)
; #define PG8_MMA(ai, bj, At, Bt) do { __builtin_amdgcn_s_setprio(1); _Pragma("unroll") for (int m = 0; m < 4; ++m) _Pragma("unroll") for (int n = 0; n < 2; ++n) _Pragma("unroll") for (int k = 0; k < 2; ++k) \
;         acc[ai][bj][m][n] = __builtin_amdgcn_mfma_f32_16x16x32_bf16(Bt[n][k], At[m][k], acc[ai][bj][m][n], 0, 0, 0); __builtin_amdgcn_s_setprio(0); } while (0)
; #define PG8_WAIT_V(n) asm volatile("s_waitcnt vmcnt(" #n ")" ::: "memory")
; template <class Epi, class Sched, bool ALIGN_EPI = false, bool SP2 = false>
; __device__ __forceinline__ void gemm_phase(PG8_LAS unsigned char* lds, const Gemm g, const Sched& S, const Epi& E) {
;     ...
;             PG8_LDB(B0, 0, 0); PG8_LDB(B1, 0, 1); PG8_SCHED; PG8_LDA(At, 0, 0); PG8_STAGE(PG8_SA(1, 1), a1 + hstep, voffA);
;             PG8_WAIT_V(8); PG8_WAIT_L(0); PG8_BAR; PG8_MMA(0, 0, At, B0); PG8_MMA(0, 1, At, B1); PG8_BAR; PG8_SCHED;
;             PG8_LDA(At, 0, 1); PG8_STAGE(PG8_SB(0, 0), b2, voffB); PG8_STAGE(PG8_SB(0, 1), b2 + hstep, voffB); PG8_STAGE(PG8_SA(0, 0), a2, voffA);
;             PG8_WAIT_V(8); PG8_WAIT_L(0); PG8_BAR; PG8_MMA(1, 0, At, B0); PG8_MMA(1, 1, At, B1); PG8_BAR; PG8_SCHED;
;             PG8_LDB(B0, 1, 0); PG8_LDB(B1, 1, 1); PG8_SCHED; PG8_LDA(At, 1, 0); PG8_STAGE(PG8_SA(0, 1), a2 + hstep, voffA);
;             PG8_WAIT_V(8); PG8_WAIT_L(0); PG8_BAR; PG8_MMA(0, 0, At, B0); PG8_MMA(0, 1, At, B1); PG8_BAR; PG8_SCHED;
;             PG8_LDA(At, 1, 1); PG8_STAGE(PG8_SB(1, 0), b3, voffB); PG8_STAGE(PG8_SB(1, 1), b3 + hstep, voffB); PG8_STAGE(PG8_SA(1, 0), a3, voffA);
;             PG8_WAIT_V(8); PG8_WAIT_L(0); PG8_BAR; PG8_MMA(1, 0, At, B0); PG8_MMA(1, 1, At, B1); PG8_BAR; PG8_SCHED;
	v_mfma_f32_16x16x32_bf16 v[2:5], v[150:153], v[204:207], v[2:5]
	s_setprio 0
	s_add_i32 s63, 0, 0x18000
	s_add_i32 s64, 0, 0x1c000
	v_add_u32_e32 v134, s63, v237
	v_add_u32_e32 v150, s64, v237
	ds_read_b128 v[98:101], v134
	ds_read_b128 v[110:113], v134 offset:1024
	ds_read_b128 v[122:125], v134 offset:2048
	ds_read_b128 v[134:137], v134 offset:3072
	ds_read_b128 v[138:141], v150
	ds_read_b128 v[142:145], v150 offset:1024
	ds_read_b128 v[146:149], v150 offset:2048
	ds_read_b128 v[150:153], v150 offset:3072
	s_add_u32 s18, s42, 0x40000
	s_addc_u32 s19, s43, 0
	s_mov_b32 m0, s47
	ds_read_b128 v[162:165], v241 offset:32768
	ds_read_b128 v[166:169], v241 offset:33792
	ds_read_b128 v[170:173], v241 offset:34816
	ds_read_b128 v[174:177], v241 offset:35840
	ds_read_b128 v[178:181], v241 offset:36864
	ds_read_b128 v[182:185], v241 offset:37888
	ds_read_b128 v[186:189], v241 offset:38912
	ds_read_b128 v[204:207], v241 offset:39936
	s_mov_b32 m0, s48
	s_nop 0
	s_waitcnt vmcnt(10)
	s_waitcnt lgkmcnt(0)
	s_setprio 1
	s_barrier
	s_waitcnt lgkmcnt(0)
	v_mfma_f32_16x16x32_bf16 v[158:161], v[98:101], v[162:165], v[158:161]
	v_mfma_f32_16x16x32_bf16 v[154:157], v[122:125], v[162:165], v[154:157]
	v_mfma_f32_16x16x32_bf16 v[118:121], v[98:101], v[170:173], v[118:121]
	v_mfma_f32_16x16x32_bf16 v[114:117], v[122:125], v[170:173], v[114:117]
	v_mfma_f32_16x16x32_bf16 v[94:97], v[98:101], v[178:181], v[94:97]
	v_mfma_f32_16x16x32_bf16 v[90:93], v[122:125], v[178:181], v[90:93]
	v_mfma_f32_16x16x32_bf16 v[78:81], v[98:101], v[186:189], v[78:81]
	v_mfma_f32_16x16x32_bf16 v[74:77], v[122:125], v[186:189], v[74:77]
	v_mfma_f32_16x16x32_bf16 v[158:161], v[110:113], v[166:169], v[158:161]
	v_mfma_f32_16x16x32_bf16 v[154:157], v[134:137], v[166:169], v[154:157]
	v_mfma_f32_16x16x32_bf16 v[118:121], v[110:113], v[174:177], v[118:121]
	v_mfma_f32_16x16x32_bf16 v[114:117], v[134:137], v[174:177], v[114:117]
	v_mfma_f32_16x16x32_bf16 v[94:97], v[110:113], v[182:185], v[94:97]
	v_mfma_f32_16x16x32_bf16 v[90:93], v[134:137], v[182:185], v[90:93]
	v_mfma_f32_16x16x32_bf16 v[78:81], v[110:113], v[204:207], v[78:81]
	v_mfma_f32_16x16x32_bf16 v[74:77], v[134:137], v[204:207], v[74:77]
	s_setprio 0
	s_setprio 1
	v_mfma_f32_16x16x32_bf16 v[130:133], v[138:141], v[162:165], v[130:133]
	v_mfma_f32_16x16x32_bf16 v[126:129], v[146:149], v[162:165], v[126:129]
	v_mfma_f32_16x16x32_bf16 v[106:109], v[138:141], v[170:173], v[106:109]
	v_mfma_f32_16x16x32_bf16 v[102:105], v[146:149], v[170:173], v[102:105]
	v_mfma_f32_16x16x32_bf16 v[86:89], v[138:141], v[178:181], v[86:89]
	v_mfma_f32_16x16x32_bf16 v[82:85], v[146:149], v[178:181], v[82:85]
	v_mfma_f32_16x16x32_bf16 v[70:73], v[138:141], v[186:189], v[70:73]
	v_mfma_f32_16x16x32_bf16 v[66:69], v[146:149], v[186:189], v[66:69]
	v_mfma_f32_16x16x32_bf16 v[130:133], v[142:145], v[166:169], v[130:133]
	v_mfma_f32_16x16x32_bf16 v[126:129], v[150:153], v[166:169], v[126:129]
	v_mfma_f32_16x16x32_bf16 v[106:109], v[142:145], v[174:177], v[106:109]
	v_mfma_f32_16x16x32_bf16 v[102:105], v[150:153], v[174:177], v[102:105]
	v_mfma_f32_16x16x32_bf16 v[86:89], v[142:145], v[182:185], v[86:89]
	v_mfma_f32_16x16x32_bf16 v[82:85], v[150:153], v[182:185], v[82:85]
	v_mfma_f32_16x16x32_bf16 v[70:73], v[142:145], v[204:207], v[70:73]
	s_setprio 3
	s_barrier
	v_mfma_f32_16x16x32_bf16 v[66:69], v[150:153], v[204:207], v[66:69]
	s_setprio 0
	s_add_i32 s18, s63, s44
	s_mov_b32 m0, s18
	ds_read_b128 v[162:165], v241 offset:49152
	ds_read_b128 v[166:169], v241 offset:50176
	ds_read_b128 v[170:173], v241 offset:51200
	ds_read_b128 v[174:177], v241 offset:52224
	ds_read_b128 v[178:181], v241 offset:53248
	ds_read_b128 v[182:185], v241 offset:54272
	ds_read_b128 v[186:189], v241 offset:55296
	ds_read_b128 v[204:207], v241 offset:56320
	s_add_i32 m0, s18, 0x2000
	s_add_u32 s18, s30, 0x40080
	s_addc_u32 s19, s31, 0
	s_add_i32 s30, s64, s44
	s_mov_b32 m0, s30
	s_nop 0
	s_add_i32 m0, s30, 0x2000
	s_nop 0
	s_mov_b32 m0, s52
	s_nop 0
	s_mov_b32 m0, s53
	s_nop 0
	s_waitcnt vmcnt(10)
	s_waitcnt lgkmcnt(0)
	s_setprio 1
	s_barrier
	s_waitcnt lgkmcnt(0)
	v_mfma_f32_16x16x32_bf16 v[62:65], v[98:101], v[162:165], v[62:65]
	v_mfma_f32_16x16x32_bf16 v[58:61], v[122:125], v[162:165], v[58:61]
	v_mfma_f32_16x16x32_bf16 v[46:49], v[98:101], v[170:173], v[46:49]
	v_mfma_f32_16x16x32_bf16 v[42:45], v[122:125], v[170:173], v[42:45]
	v_mfma_f32_16x16x32_bf16 v[30:33], v[98:101], v[178:181], v[30:33]
	v_mfma_f32_16x16x32_bf16 v[26:29], v[122:125], v[178:181], v[26:29]
	v_mfma_f32_16x16x32_bf16 v[14:17], v[98:101], v[186:189], v[14:17]
	v_mfma_f32_16x16x32_bf16 v[10:13], v[122:125], v[186:189], v[10:13]
	v_mfma_f32_16x16x32_bf16 v[62:65], v[110:113], v[166:169], v[62:65]
	v_mfma_f32_16x16x32_bf16 v[58:61], v[134:137], v[166:169], v[58:61]
	v_mfma_f32_16x16x32_bf16 v[46:49], v[110:113], v[174:177], v[46:49]
	v_mfma_f32_16x16x32_bf16 v[42:45], v[134:137], v[174:177], v[42:45]
	v_mfma_f32_16x16x32_bf16 v[30:33], v[110:113], v[182:185], v[30:33]
	v_mfma_f32_16x16x32_bf16 v[26:29], v[134:137], v[182:185], v[26:29]
	v_mfma_f32_16x16x32_bf16 v[14:17], v[110:113], v[204:207], v[14:17]
	v_mfma_f32_16x16x32_bf16 v[10:13], v[134:137], v[204:207], v[10:13]
	s_setprio 0
	s_setprio 1
	v_mfma_f32_16x16x32_bf16 v[54:57], v[138:141], v[162:165], v[54:57]
	v_mfma_f32_16x16x32_bf16 v[50:53], v[146:149], v[162:165], v[50:53]
	v_mfma_f32_16x16x32_bf16 v[38:41], v[138:141], v[170:173], v[38:41]
	v_mfma_f32_16x16x32_bf16 v[34:37], v[146:149], v[170:173], v[34:37]
	v_mfma_f32_16x16x32_bf16 v[22:25], v[138:141], v[178:181], v[22:25]
	v_mfma_f32_16x16x32_bf16 v[18:21], v[146:149], v[178:181], v[18:21]
	v_mfma_f32_16x16x32_bf16 v[6:9], v[138:141], v[186:189], v[6:9]
	v_mfma_f32_16x16x32_bf16 v[2:5], v[146:149], v[186:189], v[2:5]
	v_mfma_f32_16x16x32_bf16 v[54:57], v[142:145], v[166:169], v[54:57]
	v_mfma_f32_16x16x32_bf16 v[50:53], v[150:153], v[166:169], v[50:53]
	v_mfma_f32_16x16x32_bf16 v[38:41], v[142:145], v[174:177], v[38:41]
	v_mfma_f32_16x16x32_bf16 v[34:37], v[150:153], v[174:177], v[34:37]
	v_mfma_f32_16x16x32_bf16 v[22:25], v[142:145], v[182:185], v[22:25]
	v_mfma_f32_16x16x32_bf16 v[18:21], v[150:153], v[182:185], v[18:21]
	v_mfma_f32_16x16x32_bf16 v[6:9], v[142:145], v[204:207], v[6:9]
	s_setprio 3
	s_barrier
	v_mfma_f32_16x16x32_bf16 v[2:5], v[150:153], v[204:207], v[2:5]
	s_setprio 0
	s_add_i32 s62, s62, 2
	s_add_u32 s40, s40, 0x100
	s_addc_u32 s41, s41, 0
	s_add_u32 s60, s60, 0x100
	s_addc_u32 s61, s61, 0
	s_branch .Lrp_done_p3

; #define PG8_STAGE(bufoff, gbase, voff) do { _Pragma("unroll") for (int _i = 0; _i < 2; ++_i) \
;         __builtin_amdgcn_global_load_lds((const unsigned*)((const char*)(gbase) + (voff)[_i]), (PG8_LAS unsigned*)(lds + (bufoff) + ldsw + _i * 8192), 16, 0, 0); } while (0)
; #define PG8_LDA(dst, b, h) do { _Pragma("unroll") for (int m = 0; m < 4; ++m) _Pragma("unroll") for (int k = 0; k < 2; ++k) dst[m][k] = *(const PG8_LAS bf16x8*)(lds + PG8_SA(b, h) + aoff + m * 2048 + k * 1024); } while (0)
; #define PG8_LDB(dst, b, h) do { _Pragma("unroll") for (int n = 0; n < 2; ++n) _Pragma("unroll") for (int k = 0; k < 2; ++k) dst[n][k] = *(const PG8_LAS bf16x8*)(lds + PG8_SB(b, h) + boff + n * 2048 + k * 1024); } while (0)
; #define PG8_MMA(ai, bj, At, Bt) do { __builtin_amdgcn_s_setprio(1); _Pragma("unroll") for (int m = 0; m < 4; ++m) _Pragma("unroll") for (int n = 0; n < 2; ++n) _Pragma("unroll") for (int k = 0; k < 2; ++k) \
;         acc[ai][bj][m][n] = __builtin_amdgcn_mfma_f32_16x16x32_bf16(Bt[n][k], At[m][k], acc[ai][bj][m][n], 0, 0, 0); __builtin_amdgcn_s_setprio(0); } while (0)
; #define PG8_WAIT_V(n) asm volatile("s_waitcnt vmcnt(" #n ")" ::: "memory")
; template <class Epi, class Sched, bool ALIGN_EPI = false, bool SP2 = false>
; __device__ __forceinline__ void gemm_phase(PG8_LAS unsigned char* lds, const Gemm g, const Sched& S, const Epi& E) {
;     ...
;             PG8_LDB(B0, 0, 0); PG8_LDB(B1, 0, 1); PG8_SCHED; PG8_LDA(At, 0, 0); PG8_STAGE(PG8_SA(1, 1), a1 + hstep, voffA);
;             PG8_WAIT_V(8); PG8_WAIT_L(0); PG8_BAR; PG8_MMA(0, 0, At, B0); PG8_MMA(0, 1, At, B1); PG8_BAR; PG8_SCHED;
;             PG8_LDA(At, 0, 1); PG8_STAGE(PG8_SB(0, 0), b2, voffB); PG8_STAGE(PG8_SB(0, 1), b2 + hstep, voffB); PG8_STAGE(PG8_SA(0, 0), a2, voffA);
;             PG8_WAIT_V(8); PG8_WAIT_L(0); PG8_BAR; PG8_MMA(1, 0, At, B0); PG8_MMA(1, 1, At, B1); PG8_BAR; PG8_SCHED;
;             PG8_LDB(B0, 1, 0); PG8_LDB(B1, 1, 1); PG8_SCHED; PG8_LDA(At, 1, 0); PG8_STAGE(PG8_SA(0, 1), a2 + hstep, voffA);
;             PG8_WAIT_V(8); PG8_WAIT_L(0); PG8_BAR; PG8_MMA(0, 0, At, B0); PG8_MMA(0, 1, At, B1); PG8_BAR; PG8_SCHED;
;             PG8_LDA(At, 1, 1); PG8_STAGE(PG8_SB(1, 0), b3, voffB); PG8_STAGE(PG8_SB(1, 1), b3 + hstep, voffB); PG8_STAGE(PG8_SA(1, 0), a3, voffA);
;             PG8_WAIT_V(8); PG8_WAIT_L(0); PG8_BAR; PG8_MMA(1, 0, At, B0); PG8_MMA(1, 1, At, B1); PG8_BAR; PG8_SCHED;
.LBB0_738:
	ds_read_b128 v[148:151], v195
	ds_read_b128 v[152:155], v195 offset:1024
	ds_read_b128 v[156:159], v195 offset:2048
	ds_read_b128 v[160:163], v195 offset:3072
	ds_read_b128 v[164:167], v196
	ds_read_b128 v[168:171], v196 offset:1024
	ds_read_b128 v[172:175], v196 offset:2048
	ds_read_b128 v[198:201], v196 offset:3072
	s_add_u32 s6, s4, 0xfffc0080
	s_addc_u32 s7, s5, -1
	s_cmp_eq_u32 s66, 12
	s_cselect_b32 s31, s1, s7
	s_cselect_b32 s30, s41, s6
	s_cselect_b32 s7, s39, s47
	s_cselect_b32 s6, s65, s46
	v_lshl_add_u64 v[176:177], s[4:5], 0, v[140:141]
	s_add_i32 m0, s49, 0xc000
	ds_read_b128 v[202:205], v197
	ds_read_b128 v[206:209], v197 offset:1024
	ds_read_b128 v[210:213], v197 offset:2048
	ds_read_b128 v[214:217], v197 offset:3072
	ds_read_b128 v[218:221], v197 offset:4096
	ds_read_b128 v[222:225], v197 offset:5120
	ds_read_b128 v[226:229], v197 offset:6144
	ds_read_b128 v[230:233], v197 offset:7168
	global_load_lds_dwordx4 v[176:177], off
	v_lshl_add_u64 v[176:177], s[4:5], 0, v[142:143]
	s_add_i32 m0, s49, 0xe000
	s_nop 0
	global_load_lds_dwordx4 v[176:177], off
	s_waitcnt vmcnt(8)
	s_waitcnt lgkmcnt(0)
	s_setprio 1
	s_barrier
	s_waitcnt lgkmcnt(0)
	v_mfma_f32_16x16x32_bf16 v[126:129], v[148:151], v[202:205], v[126:129]
	v_mfma_f32_16x16x32_bf16 v[118:121], v[156:159], v[202:205], v[118:121]
	v_mfma_f32_16x16x32_bf16 v[110:113], v[148:151], v[210:213], v[110:113]
	v_mfma_f32_16x16x32_bf16 v[102:105], v[156:159], v[210:213], v[102:105]
	v_mfma_f32_16x16x32_bf16 v[94:97], v[148:151], v[218:221], v[94:97]
	v_mfma_f32_16x16x32_bf16 v[86:89], v[156:159], v[218:221], v[86:89]
	v_mfma_f32_16x16x32_bf16 v[78:81], v[148:151], v[226:229], v[78:81]
	v_mfma_f32_16x16x32_bf16 v[70:73], v[156:159], v[226:229], v[70:73]
	v_mfma_f32_16x16x32_bf16 v[126:129], v[152:155], v[206:209], v[126:129]
	v_mfma_f32_16x16x32_bf16 v[118:121], v[160:163], v[206:209], v[118:121]
	v_mfma_f32_16x16x32_bf16 v[110:113], v[152:155], v[214:217], v[110:113]
	v_mfma_f32_16x16x32_bf16 v[102:105], v[160:163], v[214:217], v[102:105]
	v_mfma_f32_16x16x32_bf16 v[94:97], v[152:155], v[222:225], v[94:97]
	v_mfma_f32_16x16x32_bf16 v[86:89], v[160:163], v[222:225], v[86:89]
	v_mfma_f32_16x16x32_bf16 v[78:81], v[152:155], v[230:233], v[78:81]
	v_mfma_f32_16x16x32_bf16 v[70:73], v[160:163], v[230:233], v[70:73]
	s_setprio 0
	s_setprio 1
	v_mfma_f32_16x16x32_bf16 v[122:125], v[164:167], v[202:205], v[122:125]
	v_mfma_f32_16x16x32_bf16 v[114:117], v[172:175], v[202:205], v[114:117]
	v_mfma_f32_16x16x32_bf16 v[106:109], v[164:167], v[210:213], v[106:109]
	v_mfma_f32_16x16x32_bf16 v[98:101], v[172:175], v[210:213], v[98:101]
	v_mfma_f32_16x16x32_bf16 v[90:93], v[164:167], v[218:221], v[90:93]
	v_mfma_f32_16x16x32_bf16 v[82:85], v[172:175], v[218:221], v[82:85]
	v_mfma_f32_16x16x32_bf16 v[74:77], v[164:167], v[226:229], v[74:77]
	v_mfma_f32_16x16x32_bf16 v[66:69], v[172:175], v[226:229], v[66:69]
	v_mfma_f32_16x16x32_bf16 v[122:125], v[168:171], v[206:209], v[122:125]
	v_mfma_f32_16x16x32_bf16 v[114:117], v[198:201], v[206:209], v[114:117]
	v_mfma_f32_16x16x32_bf16 v[106:109], v[168:171], v[214:217], v[106:109]
	v_mfma_f32_16x16x32_bf16 v[98:101], v[198:201], v[214:217], v[98:101]
	v_mfma_f32_16x16x32_bf16 v[90:93], v[168:171], v[222:225], v[90:93]
	v_mfma_f32_16x16x32_bf16 v[82:85], v[198:201], v[222:225], v[82:85]
	v_mfma_f32_16x16x32_bf16 v[74:77], v[168:171], v[230:233], v[74:77]
	s_setprio 3
	s_barrier
	v_mfma_f32_16x16x32_bf16 v[66:69], v[198:201], v[230:233], v[66:69]
	s_setprio 0
	s_add_i32 s18, s59, s25
	v_lshl_add_u64 v[176:177], s[6:7], 0, v[134:135]
	s_mov_b32 m0, s18
	ds_read_b128 v[202:205], v197 offset:16384
	ds_read_b128 v[206:209], v197 offset:17408
	ds_read_b128 v[210:213], v197 offset:18432
	ds_read_b128 v[214:217], v197 offset:19456
	ds_read_b128 v[218:221], v197 offset:20480
	ds_read_b128 v[222:225], v197 offset:21504
	ds_read_b128 v[226:229], v197 offset:22528
	ds_read_b128 v[230:233], v197 offset:23552
	global_load_lds_dwordx4 v[176:177], off
	s_add_i32 m0, s18, 0x2000
	s_add_u32 s18, s6, 0x40000
	v_lshl_add_u64 v[234:235], s[6:7], 0, v[130:131]
	s_addc_u32 s19, s7, 0
	s_add_i32 s67, s60, s25
	global_load_lds_dwordx4 v[234:235], off
	v_lshl_add_u64 v[238:239], s[18:19], 0, v[134:135]
	s_mov_b32 m0, s67
	v_lshl_add_u64 v[240:241], s[30:31], 0, v[132:133]
	global_load_lds_dwordx4 v[238:239], off
	v_lshl_add_u64 v[238:239], s[18:19], 0, v[130:131]
	s_add_i32 m0, s67, 0x2000
	s_nop 0
	global_load_lds_dwordx4 v[238:239], off
	v_lshl_add_u64 v[238:239], s[30:31], 0, v[136:137]
	s_mov_b32 m0, s49
	s_nop 0
	global_load_lds_dwordx4 v[238:239], off
	s_mov_b32 m0, s52
	s_nop 0
	global_load_lds_dwordx4 v[240:241], off
	s_waitcnt vmcnt(8)
	s_waitcnt lgkmcnt(0)
	s_setprio 1
	s_barrier
; #define PG8_STAGE(bufoff, gbase, voff) do { _Pragma("unroll") for (int _i = 0; _i < 2; ++_i) \
;         __builtin_amdgcn_global_load_lds((const unsigned*)((const char*)(gbase) + (voff)[_i]), (PG8_LAS unsigned*)(lds + (bufoff) + ldsw + _i * 8192), 16, 0, 0); } while (0)
; #define PG8_LDA(dst, b, h) do { _Pragma("unroll") for (int m = 0; m < 4; ++m) _Pragma("unroll") for (int k = 0; k < 2; ++k) dst[m][k] = *(const PG8_LAS bf16x8*)(lds + PG8_SA(b, h) + aoff + m * 2048 + k * 1024); } while (0)
; #define PG8_LDB(dst, b, h) do { _Pragma("unroll") for (int n = 0; n < 2; ++n) _Pragma("unroll") for (int k = 0; k < 2; ++k) dst[n][k] = *(const PG8_LAS bf16x8*)(lds + PG8_SB(b, h) + boff + n * 2048 + k * 1024); } while (0)
; #define PG8_MMA(ai, bj, At, Bt) do { __builtin_amdgcn_s_setprio(1); _Pragma("unroll") for (int m = 0; m < 4; ++m) _Pragma("unroll") for (int n = 0; n < 2; ++n) _Pragma("unroll") for (int k = 0; k < 2; ++k) \
;         acc[ai][bj][m][n] = __builtin_amdgcn_mfma_f32_16x16x32_bf16(Bt[n][k], At[m][k], acc[ai][bj][m][n], 0, 0, 0); __builtin_amdgcn_s_setprio(0); } while (0)
; #define PG8_WAIT_V(n) asm volatile("s_waitcnt vmcnt(" #n ")" ::: "memory")
; template <class Epi, class Sched, bool ALIGN_EPI = false, bool SP2 = false>
; __device__ __forceinline__ void gemm_phase(PG8_LAS unsigned char* lds, const Gemm g, const Sched& S, const Epi& E) {
;     ...
;             PG8_LDB(B0, 0, 0); PG8_LDB(B1, 0, 1); PG8_SCHED; PG8_LDA(At, 0, 0); PG8_STAGE(PG8_SA(1, 1), a1 + hstep, voffA);
;             PG8_WAIT_V(8); PG8_WAIT_L(0); PG8_BAR; PG8_MMA(0, 0, At, B0); PG8_MMA(0, 1, At, B1); PG8_BAR; PG8_SCHED;
;             PG8_LDA(At, 0, 1); PG8_STAGE(PG8_SB(0, 0), b2, voffB); PG8_STAGE(PG8_SB(0, 1), b2 + hstep, voffB); PG8_STAGE(PG8_SA(0, 0), a2, voffA);
;             PG8_WAIT_V(8); PG8_WAIT_L(0); PG8_BAR; PG8_MMA(1, 0, At, B0); PG8_MMA(1, 1, At, B1); PG8_BAR; PG8_SCHED;
;             PG8_LDB(B0, 1, 0); PG8_LDB(B1, 1, 1); PG8_SCHED; PG8_LDA(At, 1, 0); PG8_STAGE(PG8_SA(0, 1), a2 + hstep, voffA);
;             PG8_WAIT_V(8); PG8_WAIT_L(0); PG8_BAR; PG8_MMA(0, 0, At, B0); PG8_MMA(0, 1, At, B1); PG8_BAR; PG8_SCHED;
;             PG8_LDA(At, 1, 1); PG8_STAGE(PG8_SB(1, 0), b3, voffB); PG8_STAGE(PG8_SB(1, 1), b3 + hstep, voffB); PG8_STAGE(PG8_SA(1, 0), a3, voffA);
;             PG8_WAIT_V(8); PG8_WAIT_L(0); PG8_BAR; PG8_MMA(1, 0, At, B0); PG8_MMA(1, 1, At, B1); PG8_BAR; PG8_SCHED;
	s_waitcnt lgkmcnt(0)
	v_mfma_f32_16x16x32_bf16 v[62:65], v[148:151], v[202:205], v[62:65]
	v_mfma_f32_16x16x32_bf16 v[54:57], v[156:159], v[202:205], v[54:57]
	v_mfma_f32_16x16x32_bf16 v[46:49], v[148:151], v[210:213], v[46:49]
	v_mfma_f32_16x16x32_bf16 v[38:41], v[156:159], v[210:213], v[38:41]
	v_mfma_f32_16x16x32_bf16 v[30:33], v[148:151], v[218:221], v[30:33]
	v_mfma_f32_16x16x32_bf16 v[22:25], v[156:159], v[218:221], v[22:25]
	v_mfma_f32_16x16x32_bf16 v[14:17], v[148:151], v[226:229], v[14:17]
	v_mfma_f32_16x16x32_bf16 v[6:9], v[156:159], v[226:229], v[6:9]
	v_mfma_f32_16x16x32_bf16 v[62:65], v[152:155], v[206:209], v[62:65]
	v_mfma_f32_16x16x32_bf16 v[54:57], v[160:163], v[206:209], v[54:57]
	v_mfma_f32_16x16x32_bf16 v[46:49], v[152:155], v[214:217], v[46:49]
	v_mfma_f32_16x16x32_bf16 v[38:41], v[160:163], v[214:217], v[38:41]
	v_mfma_f32_16x16x32_bf16 v[30:33], v[152:155], v[222:225], v[30:33]
	v_mfma_f32_16x16x32_bf16 v[22:25], v[160:163], v[222:225], v[22:25]
	v_mfma_f32_16x16x32_bf16 v[14:17], v[152:155], v[230:233], v[14:17]
	v_mfma_f32_16x16x32_bf16 v[6:9], v[160:163], v[230:233], v[6:9]
	s_setprio 0
	s_setprio 1
	v_mfma_f32_16x16x32_bf16 v[58:61], v[164:167], v[202:205], v[58:61]
	v_mfma_f32_16x16x32_bf16 v[50:53], v[172:175], v[202:205], v[50:53]
	v_mfma_f32_16x16x32_bf16 v[42:45], v[164:167], v[210:213], v[42:45]
	v_mfma_f32_16x16x32_bf16 v[34:37], v[172:175], v[210:213], v[34:37]
	v_mfma_f32_16x16x32_bf16 v[26:29], v[164:167], v[218:221], v[26:29]
	v_mfma_f32_16x16x32_bf16 v[18:21], v[172:175], v[218:221], v[18:21]
	v_mfma_f32_16x16x32_bf16 v[10:13], v[164:167], v[226:229], v[10:13]
	v_mfma_f32_16x16x32_bf16 v[2:5], v[172:175], v[226:229], v[2:5]
	v_mfma_f32_16x16x32_bf16 v[58:61], v[168:171], v[206:209], v[58:61]
	v_mfma_f32_16x16x32_bf16 v[50:53], v[198:201], v[206:209], v[50:53]
	v_mfma_f32_16x16x32_bf16 v[42:45], v[168:171], v[214:217], v[42:45]
	v_mfma_f32_16x16x32_bf16 v[34:37], v[198:201], v[214:217], v[34:37]
	v_mfma_f32_16x16x32_bf16 v[26:29], v[168:171], v[222:225], v[26:29]
	v_mfma_f32_16x16x32_bf16 v[18:21], v[198:201], v[222:225], v[18:21]
	v_mfma_f32_16x16x32_bf16 v[10:13], v[168:171], v[230:233], v[10:13]
	s_setprio 3
	s_barrier
	v_mfma_f32_16x16x32_bf16 v[2:5], v[198:201], v[230:233], v[2:5]
	s_setprio 0
	s_add_i32 s67, 0, 0x18000
	s_add_i32 s68, 0, 0x1c000
	v_add_u32_e32 v160, s67, v192
	v_add_u32_e32 v198, s68, v192
	ds_read_b128 v[148:151], v160
	ds_read_b128 v[152:155], v160 offset:1024
	ds_read_b128 v[156:159], v160 offset:2048
	ds_read_b128 v[160:163], v160 offset:3072
	ds_read_b128 v[164:167], v198
	ds_read_b128 v[168:171], v198 offset:1024
	ds_read_b128 v[172:175], v198 offset:2048
	ds_read_b128 v[198:201], v198 offset:3072
	s_add_u32 s18, s30, 0x40000
	s_addc_u32 s19, s31, 0
	s_mov_b32 m0, s53
	v_lshl_add_u64 v[242:243], s[18:19], 0, v[136:137]
	ds_read_b128 v[202:205], v197 offset:32768
	ds_read_b128 v[206:209], v197 offset:33792
	ds_read_b128 v[210:213], v197 offset:34816
	ds_read_b128 v[214:217], v197 offset:35840
	ds_read_b128 v[218:221], v197 offset:36864
	ds_read_b128 v[222:225], v197 offset:37888
	ds_read_b128 v[226:229], v197 offset:38912
	ds_read_b128 v[230:233], v197 offset:39936
	global_load_lds_dwordx4 v[242:243], off
	v_lshl_add_u64 v[242:243], s[18:19], 0, v[132:133]
	s_mov_b32 m0, s54
	s_nop 0
	global_load_lds_dwordx4 v[242:243], off
	s_waitcnt vmcnt(8)
	s_waitcnt lgkmcnt(0)
	s_setprio 1
	s_barrier
	s_waitcnt lgkmcnt(0)
	v_mfma_f32_16x16x32_bf16 v[126:129], v[148:151], v[202:205], v[126:129]
	v_mfma_f32_16x16x32_bf16 v[118:121], v[156:159], v[202:205], v[118:121]
	v_mfma_f32_16x16x32_bf16 v[110:113], v[148:151], v[210:213], v[110:113]
	v_mfma_f32_16x16x32_bf16 v[102:105], v[156:159], v[210:213], v[102:105]
	v_mfma_f32_16x16x32_bf16 v[94:97], v[148:151], v[218:221], v[94:97]
	v_mfma_f32_16x16x32_bf16 v[86:89], v[156:159], v[218:221], v[86:89]
	v_mfma_f32_16x16x32_bf16 v[78:81], v[148:151], v[226:229], v[78:81]
	v_mfma_f32_16x16x32_bf16 v[70:73], v[156:159], v[226:229], v[70:73]
	v_mfma_f32_16x16x32_bf16 v[126:129], v[152:155], v[206:209], v[126:129]
	v_mfma_f32_16x16x32_bf16 v[118:121], v[160:163], v[206:209], v[118:121]
	v_mfma_f32_16x16x32_bf16 v[110:113], v[152:155], v[214:217], v[110:113]
	v_mfma_f32_16x16x32_bf16 v[102:105], v[160:163], v[214:217], v[102:105]
	v_mfma_f32_16x16x32_bf16 v[94:97], v[152:155], v[222:225], v[94:97]
	v_mfma_f32_16x16x32_bf16 v[86:89], v[160:163], v[222:225], v[86:89]
	v_mfma_f32_16x16x32_bf16 v[78:81], v[152:155], v[230:233], v[78:81]
	v_mfma_f32_16x16x32_bf16 v[70:73], v[160:163], v[230:233], v[70:73]
	s_setprio 0
	s_setprio 1
	v_mfma_f32_16x16x32_bf16 v[122:125], v[164:167], v[202:205], v[122:125]
	v_mfma_f32_16x16x32_bf16 v[114:117], v[172:175], v[202:205], v[114:117]
	v_mfma_f32_16x16x32_bf16 v[106:109], v[164:167], v[210:213], v[106:109]
	v_mfma_f32_16x16x32_bf16 v[98:101], v[172:175], v[210:213], v[98:101]
	v_mfma_f32_16x16x32_bf16 v[90:93], v[164:167], v[218:221], v[90:93]
	v_mfma_f32_16x16x32_bf16 v[82:85], v[172:175], v[218:221], v[82:85]
	v_mfma_f32_16x16x32_bf16 v[74:77], v[164:167], v[226:229], v[74:77]
	v_mfma_f32_16x16x32_bf16 v[66:69], v[172:175], v[226:229], v[66:69]
	v_mfma_f32_16x16x32_bf16 v[122:125], v[168:171], v[206:209], v[122:125]
	v_mfma_f32_16x16x32_bf16 v[114:117], v[198:201], v[206:209], v[114:117]
	v_mfma_f32_16x16x32_bf16 v[106:109], v[168:171], v[214:217], v[106:109]
	v_mfma_f32_16x16x32_bf16 v[98:101], v[198:201], v[214:217], v[98:101]
	v_mfma_f32_16x16x32_bf16 v[90:93], v[168:171], v[222:225], v[90:93]
	v_mfma_f32_16x16x32_bf16 v[82:85], v[198:201], v[222:225], v[82:85]
	v_mfma_f32_16x16x32_bf16 v[74:77], v[168:171], v[230:233], v[74:77]
	s_setprio 3
	s_barrier
; #define PG8_STAGE(bufoff, gbase, voff) do { _Pragma("unroll") for (int _i = 0; _i < 2; ++_i) \
;         __builtin_amdgcn_global_load_lds((const unsigned*)((const char*)(gbase) + (voff)[_i]), (PG8_LAS unsigned*)(lds + (bufoff) + ldsw + _i * 8192), 16, 0, 0); } while (0)
; #define PG8_LDA(dst, b, h) do { _Pragma("unroll") for (int m = 0; m < 4; ++m) _Pragma("unroll") for (int k = 0; k < 2; ++k) dst[m][k] = *(const PG8_LAS bf16x8*)(lds + PG8_SA(b, h) + aoff + m * 2048 + k * 1024); } while (0)
; #define PG8_LDB(dst, b, h) do { _Pragma("unroll") for (int n = 0; n < 2; ++n) _Pragma("unroll") for (int k = 0; k < 2; ++k) dst[n][k] = *(const PG8_LAS bf16x8*)(lds + PG8_SB(b, h) + boff + n * 2048 + k * 1024); } while (0)
; #define PG8_MMA(ai, bj, At, Bt) do { __builtin_amdgcn_s_setprio(1); _Pragma("unroll") for (int m = 0; m < 4; ++m) _Pragma("unroll") for (int n = 0; n < 2; ++n) _Pragma("unroll") for (int k = 0; k < 2; ++k) \
;         acc[ai][bj][m][n] = __builtin_amdgcn_mfma_f32_16x16x32_bf16(Bt[n][k], At[m][k], acc[ai][bj][m][n], 0, 0, 0); __builtin_amdgcn_s_setprio(0); } while (0)
; template <class Epi, class Sched, bool ALIGN_EPI = false, bool SP2 = false>
; __device__ __forceinline__ void gemm_phase(PG8_LAS unsigned char* lds, const Gemm g, const Sched& S, const Epi& E) {
;     ...
;             PG8_LDB(B0, 0, 0); PG8_LDB(B1, 0, 1); PG8_SCHED; PG8_LDA(At, 0, 0); PG8_STAGE(PG8_SA(1, 1), a1 + hstep, voffA);
;             PG8_WAIT_V(8); PG8_WAIT_L(0); PG8_BAR; PG8_MMA(0, 0, At, B0); PG8_MMA(0, 1, At, B1); PG8_BAR; PG8_SCHED;
;             PG8_LDA(At, 0, 1); PG8_STAGE(PG8_SB(0, 0), b2, voffB); PG8_STAGE(PG8_SB(0, 1), b2 + hstep, voffB); PG8_STAGE(PG8_SA(0, 0), a2, voffA);
;             PG8_WAIT_V(8); PG8_WAIT_L(0); PG8_BAR; PG8_MMA(1, 0, At, B0); PG8_MMA(1, 1, At, B1); PG8_BAR; PG8_SCHED;
;             PG8_LDB(B0, 1, 0); PG8_LDB(B1, 1, 1); PG8_SCHED; PG8_LDA(At, 1, 0); PG8_STAGE(PG8_SA(0, 1), a2 + hstep, voffA);
;             PG8_WAIT_V(8); PG8_WAIT_L(0); PG8_BAR; PG8_MMA(0, 0, At, B0); PG8_MMA(0, 1, At, B1); PG8_BAR; PG8_SCHED;
;             PG8_LDA(At, 1, 1); PG8_STAGE(PG8_SB(1, 0), b3, voffB); PG8_STAGE(PG8_SB(1, 1), b3 + hstep, voffB); PG8_STAGE(PG8_SA(1, 0), a3, voffA);
;             PG8_WAIT_V(8); PG8_WAIT_L(0); PG8_BAR; PG8_MMA(1, 0, At, B0); PG8_MMA(1, 1, At, B1); PG8_BAR; PG8_SCHED;
;     ...
;         if constexpr (ALIGN_EPI) { if (wr == 0) PG8_BAR; }
	v_mfma_f32_16x16x32_bf16 v[66:69], v[198:201], v[230:233], v[66:69]
	s_setprio 0
	s_add_i32 s18, s67, s25
	v_lshl_add_u64 v[176:177], v[176:177], 0, s[14:15]
	s_mov_b32 m0, s18
	ds_read_b128 v[202:205], v197 offset:49152
	ds_read_b128 v[206:209], v197 offset:50176
	ds_read_b128 v[210:213], v197 offset:51200
	ds_read_b128 v[214:217], v197 offset:52224
	ds_read_b128 v[218:221], v197 offset:53248
	ds_read_b128 v[222:225], v197 offset:54272
	ds_read_b128 v[226:229], v197 offset:55296
	ds_read_b128 v[230:233], v197 offset:56320
	global_load_lds_dwordx4 v[176:177], off
	s_add_i32 m0, s18, 0x2000
	s_add_u32 s6, s6, 0x40080
	v_lshl_add_u64 v[176:177], v[234:235], 0, s[14:15]
	s_addc_u32 s7, s7, 0
	s_add_i32 s18, s68, s25
	global_load_lds_dwordx4 v[176:177], off
	v_lshl_add_u64 v[176:177], s[6:7], 0, v[134:135]
	s_mov_b32 m0, s18
	s_nop 0
	global_load_lds_dwordx4 v[176:177], off
	v_lshl_add_u64 v[176:177], s[6:7], 0, v[130:131]
	s_add_i32 m0, s18, 0x2000
	s_nop 0
	global_load_lds_dwordx4 v[176:177], off
	v_lshl_add_u64 v[176:177], v[238:239], 0, s[14:15]
	s_mov_b32 m0, s56
	s_nop 0
	global_load_lds_dwordx4 v[176:177], off
	v_lshl_add_u64 v[176:177], v[240:241], 0, s[14:15]
	s_mov_b32 m0, s57
	s_nop 0
	global_load_lds_dwordx4 v[176:177], off
	s_waitcnt vmcnt(8)
	s_waitcnt lgkmcnt(0)
	s_setprio 1
	s_barrier
	s_waitcnt lgkmcnt(0)
	v_mfma_f32_16x16x32_bf16 v[62:65], v[148:151], v[202:205], v[62:65]
	v_mfma_f32_16x16x32_bf16 v[54:57], v[156:159], v[202:205], v[54:57]
	v_mfma_f32_16x16x32_bf16 v[46:49], v[148:151], v[210:213], v[46:49]
	v_mfma_f32_16x16x32_bf16 v[38:41], v[156:159], v[210:213], v[38:41]
	v_mfma_f32_16x16x32_bf16 v[30:33], v[148:151], v[218:221], v[30:33]
	v_mfma_f32_16x16x32_bf16 v[22:25], v[156:159], v[218:221], v[22:25]
	v_mfma_f32_16x16x32_bf16 v[14:17], v[148:151], v[226:229], v[14:17]
	v_mfma_f32_16x16x32_bf16 v[6:9], v[156:159], v[226:229], v[6:9]
	v_mfma_f32_16x16x32_bf16 v[62:65], v[152:155], v[206:209], v[62:65]
	v_mfma_f32_16x16x32_bf16 v[54:57], v[160:163], v[206:209], v[54:57]
	v_mfma_f32_16x16x32_bf16 v[46:49], v[152:155], v[214:217], v[46:49]
	v_mfma_f32_16x16x32_bf16 v[38:41], v[160:163], v[214:217], v[38:41]
	v_mfma_f32_16x16x32_bf16 v[30:33], v[152:155], v[222:225], v[30:33]
	v_mfma_f32_16x16x32_bf16 v[22:25], v[160:163], v[222:225], v[22:25]
	v_mfma_f32_16x16x32_bf16 v[14:17], v[152:155], v[230:233], v[14:17]
	v_mfma_f32_16x16x32_bf16 v[6:9], v[160:163], v[230:233], v[6:9]
	s_setprio 0
	s_setprio 1
	v_mfma_f32_16x16x32_bf16 v[58:61], v[164:167], v[202:205], v[58:61]
	v_mfma_f32_16x16x32_bf16 v[50:53], v[172:175], v[202:205], v[50:53]
	v_mfma_f32_16x16x32_bf16 v[42:45], v[164:167], v[210:213], v[42:45]
	v_mfma_f32_16x16x32_bf16 v[34:37], v[172:175], v[210:213], v[34:37]
	v_mfma_f32_16x16x32_bf16 v[26:29], v[164:167], v[218:221], v[26:29]
	v_mfma_f32_16x16x32_bf16 v[18:21], v[172:175], v[218:221], v[18:21]
	v_mfma_f32_16x16x32_bf16 v[10:13], v[164:167], v[226:229], v[10:13]
	v_mfma_f32_16x16x32_bf16 v[2:5], v[172:175], v[226:229], v[2:5]
	v_mfma_f32_16x16x32_bf16 v[58:61], v[168:171], v[206:209], v[58:61]
	v_mfma_f32_16x16x32_bf16 v[50:53], v[198:201], v[206:209], v[50:53]
	v_mfma_f32_16x16x32_bf16 v[42:45], v[168:171], v[214:217], v[42:45]
	v_mfma_f32_16x16x32_bf16 v[34:37], v[198:201], v[214:217], v[34:37]
	v_mfma_f32_16x16x32_bf16 v[26:29], v[168:171], v[222:225], v[26:29]
	v_mfma_f32_16x16x32_bf16 v[18:21], v[198:201], v[222:225], v[18:21]
	v_mfma_f32_16x16x32_bf16 v[10:13], v[168:171], v[230:233], v[10:13]
	s_setprio 3
	s_barrier
	v_mfma_f32_16x16x32_bf16 v[2:5], v[198:201], v[230:233], v[2:5]
	s_setprio 0
	s_add_i32 s66, s66, 2
	s_add_u32 s4, s4, 0x100
	s_addc_u32 s5, s5, 0
	s_add_u32 s46, s46, 0x100
	s_addc_u32 s47, s47, 0
	s_cmp_gt_u32 s66, 13
	s_cbranch_scc0 .LBB0_738
	s_and_b64 vcc, exec, s[16:17]
	s_cbranch_vccz .LBB0_741
	s_barrier

; #define PG8_STAGE(bufoff, gbase, voff) do { _Pragma("unroll") for (int _i = 0; _i < 2; ++_i) \
;         __builtin_amdgcn_global_load_lds((const unsigned*)((const char*)(gbase) + (voff)[_i]), (PG8_LAS unsigned*)(lds + (bufoff) + ldsw + _i * 8192), 16, 0, 0); } while (0)
; #define PG8_LDA(dst, b, h) do { _Pragma("unroll") for (int m = 0; m < 4; ++m) _Pragma("unroll") for (int k = 0; k < 2; ++k) dst[m][k] = *(const PG8_LAS bf16x8*)(lds + PG8_SA(b, h) + aoff + m * 2048 + k * 1024); } while (0)
; #define PG8_LDB(dst, b, h) do { _Pragma("unroll") for (int n = 0; n < 2; ++n) _Pragma("unroll") for (int k = 0; k < 2; ++k) dst[n][k] = *(const PG8_LAS bf16x8*)(lds + PG8_SB(b, h) + boff + n * 2048 + k * 1024); } while (0)
; #define PG8_BAR __builtin_amdgcn_s_barrier()
; template <class Epi, class Sched, bool ALIGN_EPI = false, bool SP2 = false>
; __device__ __forceinline__ void gemm_phase(PG8_LAS unsigned char* lds, const Gemm g, const Sched& S, const Epi& E) {
;     ...
;             const bool last = (t == nt - 2);
;             const char* a1 = cA + (size_t)(t + 1) * kstep;
;             const char* a2 = last ? nA : cA + (size_t)(t + 2) * kstep; const char* b2 = last ? nB : cB + (size_t)(t + 2) * kstep;
;             const char* a3 = a2 + kstep; const char* b3 = b2 + kstep;
;             if (last && has_next) S.a_ready(nxt);
;             if constexpr (SP2) {
;             PG8_LDB(B0, 0, 0); PG8_LDB(B1, 0, 1); PG8_SCHED; PG8_LDA(At, 0, 0); PG8_STAGE(PG8_SA(1, 1), a1 + hstep, voffA);
;             PG8_WAIT_V(8); PG8_WAIT_L(0); PG8_BAR; PG8_MMA(0, 0, At, B0); PG8_MMA(0, 1, At, B1); PG8_BAR; PG8_SCHED;
;             PG8_LDA(At, 0, 1); PG8_STAGE(PG8_SB(0, 0), b2, voffB); PG8_STAGE(PG8_SB(0, 1), b2 + hstep, voffB); PG8_STAGE(PG8_SA(0, 0), a2, voffA);
;             PG8_WAIT_V(8); PG8_WAIT_L(0); PG8_BAR; PG8_MMA(1, 0, At, B0); PG8_MMA(1, 1, At, B1); PG8_BAR; PG8_SCHED;
;             PG8_LDB(B0, 1, 0); PG8_LDB(B1, 1, 1); PG8_SCHED; PG8_LDA(At, 1, 0); PG8_STAGE(PG8_SA(0, 1), a2 + hstep, voffA);
;             PG8_WAIT_V(8); PG8_WAIT_L(0); PG8_BAR; PG8_MMA(0, 0, At, B0); PG8_MMA(0, 1, At, B1); PG8_BAR; PG8_SCHED;
;             PG8_LDA(At, 1, 1); PG8_STAGE(PG8_SB(1, 0), b3, voffB); PG8_STAGE(PG8_SB(1, 1), b3 + hstep, voffB); PG8_STAGE(PG8_SA(1, 0), a3, voffA);
;             PG8_WAIT_V(8); PG8_WAIT_L(0); PG8_BAR; PG8_MMA(1, 0, At, B0); PG8_MMA(1, 1, At, B1); PG8_BAR; PG8_SCHED;
.LBB0_777:
	ds_read_b128 v[148:151], v1
	ds_read_b128 v[152:155], v1 offset:1024
	ds_read_b128 v[156:159], v1 offset:2048
	ds_read_b128 v[160:163], v1 offset:3072
	ds_read_b128 v[164:167], v145
	ds_read_b128 v[168:171], v145 offset:1024
	ds_read_b128 v[172:175], v145 offset:2048
	ds_read_b128 v[176:179], v145 offset:3072
	s_add_i32 s76, s30, 2
	s_add_u32 s18, s46, 0x80
	s_addc_u32 s19, s47, 0
	s_cmp_eq_u32 s67, s30
	s_cselect_b32 s30, s42, s18
	s_cselect_b32 s31, s43, s19
	s_cselect_b32 s19, s45, s49
	s_cselect_b32 s18, s44, s48
	v_lshl_add_u64 v[212:213], s[46:47], 0, v[138:139]
	s_add_i32 m0, s53, 0xc000
	ds_read_b128 v[180:183], v146
	ds_read_b128 v[184:187], v146 offset:1024
	ds_read_b128 v[188:191], v146 offset:2048
	ds_read_b128 v[192:195], v146 offset:3072
	ds_read_b128 v[196:199], v146 offset:4096
	ds_read_b128 v[200:203], v146 offset:5120
	ds_read_b128 v[204:207], v146 offset:6144
	ds_read_b128 v[208:211], v146 offset:7168
	global_load_lds_dwordx4 v[212:213], off
	v_lshl_add_u64 v[212:213], s[46:47], 0, v[140:141]
	s_add_i32 m0, s53, 0xe000
	s_nop 0
	global_load_lds_dwordx4 v[212:213], off
	s_waitcnt vmcnt(8)
	s_waitcnt lgkmcnt(0)
	s_setprio 1
	s_barrier
	s_waitcnt lgkmcnt(0)
	v_mfma_f32_16x16x32_bf16 v[122:125], v[148:151], v[180:183], v[122:125]
	v_mfma_f32_16x16x32_bf16 v[126:129], v[156:159], v[180:183], v[126:129]
	v_mfma_f32_16x16x32_bf16 v[110:113], v[148:151], v[188:191], v[110:113]
	v_mfma_f32_16x16x32_bf16 v[106:109], v[156:159], v[188:191], v[106:109]
	v_mfma_f32_16x16x32_bf16 v[94:97], v[148:151], v[196:199], v[94:97]
	v_mfma_f32_16x16x32_bf16 v[90:93], v[156:159], v[196:199], v[90:93]
	v_mfma_f32_16x16x32_bf16 v[78:81], v[148:151], v[204:207], v[78:81]
	v_mfma_f32_16x16x32_bf16 v[74:77], v[156:159], v[204:207], v[74:77]
	v_mfma_f32_16x16x32_bf16 v[122:125], v[152:155], v[184:187], v[122:125]
	v_mfma_f32_16x16x32_bf16 v[126:129], v[160:163], v[184:187], v[126:129]
	v_mfma_f32_16x16x32_bf16 v[110:113], v[152:155], v[192:195], v[110:113]
	v_mfma_f32_16x16x32_bf16 v[106:109], v[160:163], v[192:195], v[106:109]
	v_mfma_f32_16x16x32_bf16 v[94:97], v[152:155], v[200:203], v[94:97]
	v_mfma_f32_16x16x32_bf16 v[90:93], v[160:163], v[200:203], v[90:93]
	v_mfma_f32_16x16x32_bf16 v[78:81], v[152:155], v[208:211], v[78:81]
	v_mfma_f32_16x16x32_bf16 v[74:77], v[160:163], v[208:211], v[74:77]
	s_setprio 0
	s_setprio 1
	v_mfma_f32_16x16x32_bf16 v[118:121], v[164:167], v[180:183], v[118:121]
	v_mfma_f32_16x16x32_bf16 v[114:117], v[172:175], v[180:183], v[114:117]
	v_mfma_f32_16x16x32_bf16 v[102:105], v[164:167], v[188:191], v[102:105]
	v_mfma_f32_16x16x32_bf16 v[98:101], v[172:175], v[188:191], v[98:101]
	v_mfma_f32_16x16x32_bf16 v[86:89], v[164:167], v[196:199], v[86:89]
	v_mfma_f32_16x16x32_bf16 v[82:85], v[172:175], v[196:199], v[82:85]
	v_mfma_f32_16x16x32_bf16 v[70:73], v[164:167], v[204:207], v[70:73]
	v_mfma_f32_16x16x32_bf16 v[66:69], v[172:175], v[204:207], v[66:69]
	v_mfma_f32_16x16x32_bf16 v[118:121], v[168:171], v[184:187], v[118:121]
	v_mfma_f32_16x16x32_bf16 v[114:117], v[176:179], v[184:187], v[114:117]
	v_mfma_f32_16x16x32_bf16 v[102:105], v[168:171], v[192:195], v[102:105]
	v_mfma_f32_16x16x32_bf16 v[98:101], v[176:179], v[192:195], v[98:101]
	v_mfma_f32_16x16x32_bf16 v[86:89], v[168:171], v[200:203], v[86:89]
	v_mfma_f32_16x16x32_bf16 v[82:85], v[176:179], v[200:203], v[82:85]
	v_mfma_f32_16x16x32_bf16 v[70:73], v[168:171], v[208:211], v[70:73]
	s_setprio 3
	s_barrier
	v_mfma_f32_16x16x32_bf16 v[66:69], v[176:179], v[208:211], v[66:69]
	s_setprio 0
	s_add_i32 s77, s68, s52
	v_lshl_add_u64 v[212:213], s[18:19], 0, v[132:133]
	s_mov_b32 m0, s77
	ds_read_b128 v[180:183], v146 offset:16384
	ds_read_b128 v[184:187], v146 offset:17408
	ds_read_b128 v[188:191], v146 offset:18432
	ds_read_b128 v[192:195], v146 offset:19456
	ds_read_b128 v[196:199], v146 offset:20480
	ds_read_b128 v[200:203], v146 offset:21504
	ds_read_b128 v[204:207], v146 offset:22528
	ds_read_b128 v[208:211], v146 offset:23552
	global_load_lds_dwordx4 v[212:213], off
	s_add_i32 m0, s77, 0x2000
	v_lshl_add_u64 v[214:215], s[18:19], 0, v[136:137]
	s_add_u32 s18, s18, s4
	s_addc_u32 s19, s19, s5
	s_add_i32 s77, s69, s52
	global_load_lds_dwordx4 v[214:215], off
	v_lshl_add_u64 v[216:217], s[18:19], 0, v[132:133]
	s_mov_b32 m0, s77
	v_lshl_add_u64 v[218:219], s[18:19], 0, v[136:137]
	global_load_lds_dwordx4 v[216:217], off
	s_add_i32 m0, s77, 0x2000
	v_lshl_add_u64 v[220:221], s[30:31], 0, v[130:131]
	global_load_lds_dwordx4 v[218:219], off
	s_mov_b32 m0, s53
	v_lshl_add_u64 v[222:223], s[30:31], 0, v[134:135]
	global_load_lds_dwordx4 v[220:221], off
	s_mov_b32 m0, s54
	s_nop 0
	global_load_lds_dwordx4 v[222:223], off
	s_waitcnt vmcnt(8)
	s_waitcnt lgkmcnt(0)
	s_setprio 1
	s_barrier
; #define PG8_STAGE(bufoff, gbase, voff) do { _Pragma("unroll") for (int _i = 0; _i < 2; ++_i) \
;         __builtin_amdgcn_global_load_lds((const unsigned*)((const char*)(gbase) + (voff)[_i]), (PG8_LAS unsigned*)(lds + (bufoff) + ldsw + _i * 8192), 16, 0, 0); } while (0)
; #define PG8_LDA(dst, b, h) do { _Pragma("unroll") for (int m = 0; m < 4; ++m) _Pragma("unroll") for (int k = 0; k < 2; ++k) dst[m][k] = *(const PG8_LAS bf16x8*)(lds + PG8_SA(b, h) + aoff + m * 2048 + k * 1024); } while (0)
; #define PG8_LDB(dst, b, h) do { _Pragma("unroll") for (int n = 0; n < 2; ++n) _Pragma("unroll") for (int k = 0; k < 2; ++k) dst[n][k] = *(const PG8_LAS bf16x8*)(lds + PG8_SB(b, h) + boff + n * 2048 + k * 1024); } while (0)
; #define PG8_MMA(ai, bj, At, Bt) do { __builtin_amdgcn_s_setprio(1); _Pragma("unroll") for (int m = 0; m < 4; ++m) _Pragma("unroll") for (int n = 0; n < 2; ++n) _Pragma("unroll") for (int k = 0; k < 2; ++k) \
;         acc[ai][bj][m][n] = __builtin_amdgcn_mfma_f32_16x16x32_bf16(Bt[n][k], At[m][k], acc[ai][bj][m][n], 0, 0, 0); __builtin_amdgcn_s_setprio(0); } while (0)
; #define PG8_WAIT_V(n) asm volatile("s_waitcnt vmcnt(" #n ")" ::: "memory")
; template <class Epi, class Sched, bool ALIGN_EPI = false, bool SP2 = false>
; __device__ __forceinline__ void gemm_phase(PG8_LAS unsigned char* lds, const Gemm g, const Sched& S, const Epi& E) {
;     ...
;             PG8_LDB(B0, 0, 0); PG8_LDB(B1, 0, 1); PG8_SCHED; PG8_LDA(At, 0, 0); PG8_STAGE(PG8_SA(1, 1), a1 + hstep, voffA);
;             PG8_WAIT_V(8); PG8_WAIT_L(0); PG8_BAR; PG8_MMA(0, 0, At, B0); PG8_MMA(0, 1, At, B1); PG8_BAR; PG8_SCHED;
;             PG8_LDA(At, 0, 1); PG8_STAGE(PG8_SB(0, 0), b2, voffB); PG8_STAGE(PG8_SB(0, 1), b2 + hstep, voffB); PG8_STAGE(PG8_SA(0, 0), a2, voffA);
;             PG8_WAIT_V(8); PG8_WAIT_L(0); PG8_BAR; PG8_MMA(1, 0, At, B0); PG8_MMA(1, 1, At, B1); PG8_BAR; PG8_SCHED;
;             PG8_LDB(B0, 1, 0); PG8_LDB(B1, 1, 1); PG8_SCHED; PG8_LDA(At, 1, 0); PG8_STAGE(PG8_SA(0, 1), a2 + hstep, voffA);
;             PG8_WAIT_V(8); PG8_WAIT_L(0); PG8_BAR; PG8_MMA(0, 0, At, B0); PG8_MMA(0, 1, At, B1); PG8_BAR; PG8_SCHED;
;             PG8_LDA(At, 1, 1); PG8_STAGE(PG8_SB(1, 0), b3, voffB); PG8_STAGE(PG8_SB(1, 1), b3 + hstep, voffB); PG8_STAGE(PG8_SA(1, 0), a3, voffA);
;             PG8_WAIT_V(8); PG8_WAIT_L(0); PG8_BAR; PG8_MMA(1, 0, At, B0); PG8_MMA(1, 1, At, B1); PG8_BAR; PG8_SCHED;
	s_waitcnt lgkmcnt(0)
	v_mfma_f32_16x16x32_bf16 v[62:65], v[148:151], v[180:183], v[62:65]
	v_mfma_f32_16x16x32_bf16 v[58:61], v[156:159], v[180:183], v[58:61]
	v_mfma_f32_16x16x32_bf16 v[46:49], v[148:151], v[188:191], v[46:49]
	v_mfma_f32_16x16x32_bf16 v[42:45], v[156:159], v[188:191], v[42:45]
	v_mfma_f32_16x16x32_bf16 v[30:33], v[148:151], v[196:199], v[30:33]
	v_mfma_f32_16x16x32_bf16 v[26:29], v[156:159], v[196:199], v[26:29]
	v_mfma_f32_16x16x32_bf16 v[14:17], v[148:151], v[204:207], v[14:17]
	v_mfma_f32_16x16x32_bf16 v[10:13], v[156:159], v[204:207], v[10:13]
	v_mfma_f32_16x16x32_bf16 v[62:65], v[152:155], v[184:187], v[62:65]
	v_mfma_f32_16x16x32_bf16 v[58:61], v[160:163], v[184:187], v[58:61]
	v_mfma_f32_16x16x32_bf16 v[46:49], v[152:155], v[192:195], v[46:49]
	v_mfma_f32_16x16x32_bf16 v[42:45], v[160:163], v[192:195], v[42:45]
	v_mfma_f32_16x16x32_bf16 v[30:33], v[152:155], v[200:203], v[30:33]
	v_mfma_f32_16x16x32_bf16 v[26:29], v[160:163], v[200:203], v[26:29]
	v_mfma_f32_16x16x32_bf16 v[14:17], v[152:155], v[208:211], v[14:17]
	v_mfma_f32_16x16x32_bf16 v[10:13], v[160:163], v[208:211], v[10:13]
	s_setprio 0
	s_setprio 1
	v_mfma_f32_16x16x32_bf16 v[54:57], v[164:167], v[180:183], v[54:57]
	v_mfma_f32_16x16x32_bf16 v[50:53], v[172:175], v[180:183], v[50:53]
	v_mfma_f32_16x16x32_bf16 v[38:41], v[164:167], v[188:191], v[38:41]
	v_mfma_f32_16x16x32_bf16 v[34:37], v[172:175], v[188:191], v[34:37]
	v_mfma_f32_16x16x32_bf16 v[22:25], v[164:167], v[196:199], v[22:25]
	v_mfma_f32_16x16x32_bf16 v[18:21], v[172:175], v[196:199], v[18:21]
	v_mfma_f32_16x16x32_bf16 v[6:9], v[164:167], v[204:207], v[6:9]
	v_mfma_f32_16x16x32_bf16 v[2:5], v[172:175], v[204:207], v[2:5]
	v_mfma_f32_16x16x32_bf16 v[54:57], v[168:171], v[184:187], v[54:57]
	v_mfma_f32_16x16x32_bf16 v[50:53], v[176:179], v[184:187], v[50:53]
	v_mfma_f32_16x16x32_bf16 v[38:41], v[168:171], v[192:195], v[38:41]
	v_mfma_f32_16x16x32_bf16 v[34:37], v[176:179], v[192:195], v[34:37]
	v_mfma_f32_16x16x32_bf16 v[22:25], v[168:171], v[200:203], v[22:25]
	v_mfma_f32_16x16x32_bf16 v[18:21], v[176:179], v[200:203], v[18:21]
	v_mfma_f32_16x16x32_bf16 v[6:9], v[168:171], v[208:211], v[6:9]
	s_setprio 3
	s_barrier
	v_mfma_f32_16x16x32_bf16 v[2:5], v[176:179], v[208:211], v[2:5]
	s_setprio 0
	s_add_i32 s77, 0, 0x18000
	v_add_u32_e32 v147, s77, v143
	s_add_i32 s78, 0, 0x1c000
	ds_read_b128 v[148:151], v147
	ds_read_b128 v[152:155], v147 offset:1024
	ds_read_b128 v[156:159], v147 offset:2048
	ds_read_b128 v[160:163], v147 offset:3072
	v_add_u32_e32 v147, s78, v143
	ds_read_b128 v[164:167], v147
	ds_read_b128 v[168:171], v147 offset:1024
	ds_read_b128 v[172:175], v147 offset:2048
	ds_read_b128 v[176:179], v147 offset:3072
	s_add_u32 s18, s30, s4
	s_addc_u32 s19, s31, s5
	s_mov_b32 m0, s55
	v_lshl_add_u64 v[224:225], s[18:19], 0, v[130:131]
	ds_read_b128 v[180:183], v146 offset:32768
	ds_read_b128 v[184:187], v146 offset:33792
	ds_read_b128 v[188:191], v146 offset:34816
	ds_read_b128 v[192:195], v146 offset:35840
	ds_read_b128 v[196:199], v146 offset:36864
	ds_read_b128 v[200:203], v146 offset:37888
	ds_read_b128 v[204:207], v146 offset:38912
	ds_read_b128 v[208:211], v146 offset:39936
	global_load_lds_dwordx4 v[224:225], off
	v_lshl_add_u64 v[224:225], s[18:19], 0, v[134:135]
	s_mov_b32 m0, s56
	s_nop 0
	global_load_lds_dwordx4 v[224:225], off
	s_waitcnt vmcnt(8)
	s_waitcnt lgkmcnt(0)
	s_setprio 1
	s_barrier
	s_waitcnt lgkmcnt(0)
	v_mfma_f32_16x16x32_bf16 v[122:125], v[148:151], v[180:183], v[122:125]
	v_mfma_f32_16x16x32_bf16 v[126:129], v[156:159], v[180:183], v[126:129]
	v_mfma_f32_16x16x32_bf16 v[110:113], v[148:151], v[188:191], v[110:113]
	v_mfma_f32_16x16x32_bf16 v[106:109], v[156:159], v[188:191], v[106:109]
	v_mfma_f32_16x16x32_bf16 v[94:97], v[148:151], v[196:199], v[94:97]
	v_mfma_f32_16x16x32_bf16 v[90:93], v[156:159], v[196:199], v[90:93]
	v_mfma_f32_16x16x32_bf16 v[78:81], v[148:151], v[204:207], v[78:81]
	v_mfma_f32_16x16x32_bf16 v[74:77], v[156:159], v[204:207], v[74:77]
	v_mfma_f32_16x16x32_bf16 v[122:125], v[152:155], v[184:187], v[122:125]
	v_mfma_f32_16x16x32_bf16 v[126:129], v[160:163], v[184:187], v[126:129]
	v_mfma_f32_16x16x32_bf16 v[110:113], v[152:155], v[192:195], v[110:113]
	v_mfma_f32_16x16x32_bf16 v[106:109], v[160:163], v[192:195], v[106:109]
	v_mfma_f32_16x16x32_bf16 v[94:97], v[152:155], v[200:203], v[94:97]
	v_mfma_f32_16x16x32_bf16 v[90:93], v[160:163], v[200:203], v[90:93]
	v_mfma_f32_16x16x32_bf16 v[78:81], v[152:155], v[208:211], v[78:81]
	v_mfma_f32_16x16x32_bf16 v[74:77], v[160:163], v[208:211], v[74:77]
	s_setprio 0
	s_setprio 1
	v_mfma_f32_16x16x32_bf16 v[118:121], v[164:167], v[180:183], v[118:121]
	v_mfma_f32_16x16x32_bf16 v[114:117], v[172:175], v[180:183], v[114:117]
	v_mfma_f32_16x16x32_bf16 v[102:105], v[164:167], v[188:191], v[102:105]
	v_mfma_f32_16x16x32_bf16 v[98:101], v[172:175], v[188:191], v[98:101]
	v_mfma_f32_16x16x32_bf16 v[86:89], v[164:167], v[196:199], v[86:89]
	v_mfma_f32_16x16x32_bf16 v[82:85], v[172:175], v[196:199], v[82:85]
	v_mfma_f32_16x16x32_bf16 v[70:73], v[164:167], v[204:207], v[70:73]
	v_mfma_f32_16x16x32_bf16 v[66:69], v[172:175], v[204:207], v[66:69]
	v_mfma_f32_16x16x32_bf16 v[118:121], v[168:171], v[184:187], v[118:121]
	v_mfma_f32_16x16x32_bf16 v[114:117], v[176:179], v[184:187], v[114:117]
	v_mfma_f32_16x16x32_bf16 v[102:105], v[168:171], v[192:195], v[102:105]
	v_mfma_f32_16x16x32_bf16 v[98:101], v[176:179], v[192:195], v[98:101]
	v_mfma_f32_16x16x32_bf16 v[86:89], v[168:171], v[200:203], v[86:89]
	v_mfma_f32_16x16x32_bf16 v[82:85], v[176:179], v[200:203], v[82:85]
	v_mfma_f32_16x16x32_bf16 v[70:73], v[168:171], v[208:211], v[70:73]
	s_setprio 3
	s_barrier
; #define PG8_STAGE(bufoff, gbase, voff) do { _Pragma("unroll") for (int _i = 0; _i < 2; ++_i) \
;         __builtin_amdgcn_global_load_lds((const unsigned*)((const char*)(gbase) + (voff)[_i]), (PG8_LAS unsigned*)(lds + (bufoff) + ldsw + _i * 8192), 16, 0, 0); } while (0)
; #define PG8_LDA(dst, b, h) do { _Pragma("unroll") for (int m = 0; m < 4; ++m) _Pragma("unroll") for (int k = 0; k < 2; ++k) dst[m][k] = *(const PG8_LAS bf16x8*)(lds + PG8_SA(b, h) + aoff + m * 2048 + k * 1024); } while (0)
; #define PG8_MMA(ai, bj, At, Bt) do { __builtin_amdgcn_s_setprio(1); _Pragma("unroll") for (int m = 0; m < 4; ++m) _Pragma("unroll") for (int n = 0; n < 2; ++n) _Pragma("unroll") for (int k = 0; k < 2; ++k) \
;         acc[ai][bj][m][n] = __builtin_amdgcn_mfma_f32_16x16x32_bf16(Bt[n][k], At[m][k], acc[ai][bj][m][n], 0, 0, 0); __builtin_amdgcn_s_setprio(0); } while (0)
; #define PG8_WAIT_V(n) asm volatile("s_waitcnt vmcnt(" #n ")" ::: "memory")
; #define PG8_WAIT_L(n) asm volatile("s_waitcnt lgkmcnt(" #n ")" ::: "memory")
; #define PG8_BAR __builtin_amdgcn_s_barrier()
; #define PG8_SCHED __builtin_amdgcn_sched_barrier(0)
; template <class Epi, class Sched, bool ALIGN_EPI = false, bool SP2 = false>
; __device__ __forceinline__ void gemm_phase(PG8_LAS unsigned char* lds, const Gemm g, const Sched& S, const Epi& E) {
;     ...
;             PG8_LDA(At, 1, 1); PG8_STAGE(PG8_SB(1, 0), b3, voffB); PG8_STAGE(PG8_SB(1, 1), b3 + hstep, voffB); PG8_STAGE(PG8_SA(1, 0), a3, voffA);
;             PG8_WAIT_V(8); PG8_WAIT_L(0); PG8_BAR; PG8_MMA(1, 0, At, B0); PG8_MMA(1, 1, At, B1); PG8_BAR; PG8_SCHED;
	v_mfma_f32_16x16x32_bf16 v[66:69], v[176:179], v[208:211], v[66:69]
	s_setprio 0
	s_add_i32 s18, s77, s52
	v_lshl_add_u64 v[212:213], v[212:213], 0, s[14:15]
	s_mov_b32 m0, s18
	ds_read_b128 v[180:183], v146 offset:49152
	ds_read_b128 v[184:187], v146 offset:50176
	ds_read_b128 v[188:191], v146 offset:51200
	ds_read_b128 v[192:195], v146 offset:52224
	ds_read_b128 v[196:199], v146 offset:53248
	ds_read_b128 v[200:203], v146 offset:54272
	ds_read_b128 v[204:207], v146 offset:55296
	ds_read_b128 v[208:211], v146 offset:56320
	global_load_lds_dwordx4 v[212:213], off
	v_lshl_add_u64 v[212:213], v[214:215], 0, s[14:15]
	s_add_i32 m0, s18, 0x2000
	s_add_i32 s18, s78, s52
	global_load_lds_dwordx4 v[212:213], off
	v_lshl_add_u64 v[212:213], v[216:217], 0, s[14:15]
	s_mov_b32 m0, s18
	s_nop 0
	global_load_lds_dwordx4 v[212:213], off
	v_lshl_add_u64 v[212:213], v[218:219], 0, s[14:15]
	s_add_i32 m0, s18, 0x2000
	s_nop 0
	global_load_lds_dwordx4 v[212:213], off
	v_lshl_add_u64 v[212:213], v[220:221], 0, s[14:15]
	s_mov_b32 m0, s58
	s_nop 0
	global_load_lds_dwordx4 v[212:213], off
	v_lshl_add_u64 v[212:213], v[222:223], 0, s[14:15]
	s_mov_b32 m0, s59
	s_nop 0
	global_load_lds_dwordx4 v[212:213], off
	s_waitcnt vmcnt(8)
	s_waitcnt lgkmcnt(0)
	s_setprio 1
	s_barrier
	s_waitcnt lgkmcnt(0)
	v_mfma_f32_16x16x32_bf16 v[62:65], v[148:151], v[180:183], v[62:65]
	v_mfma_f32_16x16x32_bf16 v[58:61], v[156:159], v[180:183], v[58:61]
	v_mfma_f32_16x16x32_bf16 v[46:49], v[148:151], v[188:191], v[46:49]
	v_mfma_f32_16x16x32_bf16 v[42:45], v[156:159], v[188:191], v[42:45]
	v_mfma_f32_16x16x32_bf16 v[30:33], v[148:151], v[196:199], v[30:33]
	v_mfma_f32_16x16x32_bf16 v[26:29], v[156:159], v[196:199], v[26:29]
	v_mfma_f32_16x16x32_bf16 v[14:17], v[148:151], v[204:207], v[14:17]
	v_mfma_f32_16x16x32_bf16 v[10:13], v[156:159], v[204:207], v[10:13]
	v_mfma_f32_16x16x32_bf16 v[62:65], v[152:155], v[184:187], v[62:65]
	v_mfma_f32_16x16x32_bf16 v[58:61], v[160:163], v[184:187], v[58:61]
	v_mfma_f32_16x16x32_bf16 v[46:49], v[152:155], v[192:195], v[46:49]
	v_mfma_f32_16x16x32_bf16 v[42:45], v[160:163], v[192:195], v[42:45]
	v_mfma_f32_16x16x32_bf16 v[30:33], v[152:155], v[200:203], v[30:33]
	v_mfma_f32_16x16x32_bf16 v[26:29], v[160:163], v[200:203], v[26:29]
	v_mfma_f32_16x16x32_bf16 v[14:17], v[152:155], v[208:211], v[14:17]
	v_mfma_f32_16x16x32_bf16 v[10:13], v[160:163], v[208:211], v[10:13]
	s_setprio 0
	s_setprio 1
	v_mfma_f32_16x16x32_bf16 v[54:57], v[164:167], v[180:183], v[54:57]
	v_mfma_f32_16x16x32_bf16 v[50:53], v[172:175], v[180:183], v[50:53]
	v_mfma_f32_16x16x32_bf16 v[38:41], v[164:167], v[188:191], v[38:41]
	v_mfma_f32_16x16x32_bf16 v[34:37], v[172:175], v[188:191], v[34:37]
	v_mfma_f32_16x16x32_bf16 v[22:25], v[164:167], v[196:199], v[22:25]
	v_mfma_f32_16x16x32_bf16 v[18:21], v[172:175], v[196:199], v[18:21]
	v_mfma_f32_16x16x32_bf16 v[6:9], v[164:167], v[204:207], v[6:9]
	v_mfma_f32_16x16x32_bf16 v[2:5], v[172:175], v[204:207], v[2:5]
	v_mfma_f32_16x16x32_bf16 v[54:57], v[168:171], v[184:187], v[54:57]
	v_mfma_f32_16x16x32_bf16 v[50:53], v[176:179], v[184:187], v[50:53]
	v_mfma_f32_16x16x32_bf16 v[38:41], v[168:171], v[192:195], v[38:41]
	v_mfma_f32_16x16x32_bf16 v[34:37], v[176:179], v[192:195], v[34:37]
	v_mfma_f32_16x16x32_bf16 v[22:25], v[168:171], v[200:203], v[22:25]
	v_mfma_f32_16x16x32_bf16 v[18:21], v[176:179], v[200:203], v[18:21]
	v_mfma_f32_16x16x32_bf16 v[6:9], v[168:171], v[208:211], v[6:9]
	s_setprio 3
	s_barrier
	v_mfma_f32_16x16x32_bf16 v[2:5], v[176:179], v[208:211], v[2:5]
	s_setprio 0
	s_add_u32 s46, s46, 0x100
	s_addc_u32 s47, s47, 0
	s_add_u32 s48, s48, 0x100
	s_addc_u32 s49, s49, 0
	s_cmp_ge_i32 s76, s60
	s_mov_b32 s30, s76
	s_cbranch_scc0 .LBB0_777

; #define PG8_STAGE(bufoff, gbase, voff) do { _Pragma("unroll") for (int _i = 0; _i < 2; ++_i) \
;         __builtin_amdgcn_global_load_lds((const unsigned*)((const char*)(gbase) + (voff)[_i]), (PG8_LAS unsigned*)(lds + (bufoff) + ldsw + _i * 8192), 16, 0, 0); } while (0)
; #define PG8_LDA(dst, b, h) do { _Pragma("unroll") for (int m = 0; m < 4; ++m) _Pragma("unroll") for (int k = 0; k < 2; ++k) dst[m][k] = *(const PG8_LAS bf16x8*)(lds + PG8_SA(b, h) + aoff + m * 2048 + k * 1024); } while (0)
; #define PG8_LDB(dst, b, h) do { _Pragma("unroll") for (int n = 0; n < 2; ++n) _Pragma("unroll") for (int k = 0; k < 2; ++k) dst[n][k] = *(const PG8_LAS bf16x8*)(lds + PG8_SB(b, h) + boff + n * 2048 + k * 1024); } while (0)
; #define PG8_MMA(ai, bj, At, Bt) do { __builtin_amdgcn_s_setprio(1); _Pragma("unroll") for (int m = 0; m < 4; ++m) _Pragma("unroll") for (int n = 0; n < 2; ++n) _Pragma("unroll") for (int k = 0; k < 2; ++k) \
;         acc[ai][bj][m][n] = __builtin_amdgcn_mfma_f32_16x16x32_bf16(Bt[n][k], At[m][k], acc[ai][bj][m][n], 0, 0, 0); __builtin_amdgcn_s_setprio(0); } while (0)
; #define PG8_WAIT_V(n) asm volatile("s_waitcnt vmcnt(" #n ")" ::: "memory")
; #define PG8_WAIT_L(n) asm volatile("s_waitcnt lgkmcnt(" #n ")" ::: "memory")
; #define PG8_BAR __builtin_amdgcn_s_barrier()
; #define PG8_SCHED __builtin_amdgcn_sched_barrier(0)
; template <class Epi, class Sched, bool ALIGN_EPI = false, bool SP2 = false>
; __device__ __forceinline__ void gemm_phase(PG8_LAS unsigned char* lds, const Gemm g, const Sched& S, const Epi& E) {
;     ...
;             PG8_LDB(B0, 0, 0); PG8_LDB(B1, 0, 1); PG8_SCHED; PG8_LDA(At, 0, 0); PG8_STAGE(PG8_SA(1, 1), a1 + hstep, voffA);
;             PG8_WAIT_V(8); PG8_WAIT_L(0); PG8_BAR; PG8_MMA(0, 0, At, B0); PG8_MMA(0, 1, At, B1); PG8_BAR; PG8_SCHED;
;             PG8_LDA(At, 0, 1); PG8_STAGE(PG8_SB(0, 0), b2, voffB); PG8_STAGE(PG8_SB(0, 1), b2 + hstep, voffB); PG8_STAGE(PG8_SA(0, 0), a2, voffA);
;             PG8_WAIT_V(8); PG8_WAIT_L(0); PG8_BAR; PG8_MMA(1, 0, At, B0); PG8_MMA(1, 1, At, B1); PG8_BAR; PG8_SCHED;
.LBB0_892:
	ds_read_b128 v[98:101], v239
	ds_read_b128 v[110:113], v239 offset:1024
	ds_read_b128 v[122:125], v239 offset:2048
	ds_read_b128 v[134:137], v239 offset:3072
	ds_read_b128 v[138:141], v240
	ds_read_b128 v[142:145], v240 offset:1024
	ds_read_b128 v[146:149], v240 offset:2048
	ds_read_b128 v[150:153], v240 offset:3072
	s_add_u32 s18, s34, 0xfff50080
	s_addc_u32 s19, s35, -1
	s_cmp_eq_u32 s60, 40
	s_cselect_b32 s39, s1, s19
	s_cselect_b32 s38, s0, s18
	s_cselect_b32 s37, s31, s59
	s_cselect_b32 s36, s30, s58
	v_lshl_add_u64 v[208:209], s[34:35], 0, v[198:199]
	s_add_i32 m0, s41, 0xc000
	ds_read_b128 v[162:165], v241
	ds_read_b128 v[166:169], v241 offset:1024
	ds_read_b128 v[170:173], v241 offset:2048
	ds_read_b128 v[174:177], v241 offset:3072
	ds_read_b128 v[178:181], v241 offset:4096
	ds_read_b128 v[182:185], v241 offset:5120
	ds_read_b128 v[186:189], v241 offset:6144
	ds_read_b128 v[204:207], v241 offset:7168
	global_load_lds_dwordx4 v[208:209], off
	v_lshl_add_u64 v[208:209], s[34:35], 0, v[200:201]
	s_add_i32 m0, s41, 0xe000
	s_nop 0
	global_load_lds_dwordx4 v[208:209], off
	s_waitcnt vmcnt(8)
	s_waitcnt lgkmcnt(0)
	s_setprio 1
	s_barrier
	s_waitcnt lgkmcnt(0)
	v_mfma_f32_16x16x32_bf16 v[158:161], v[98:101], v[162:165], v[158:161]
	v_mfma_f32_16x16x32_bf16 v[154:157], v[122:125], v[162:165], v[154:157]
	v_mfma_f32_16x16x32_bf16 v[118:121], v[98:101], v[170:173], v[118:121]
	v_mfma_f32_16x16x32_bf16 v[114:117], v[122:125], v[170:173], v[114:117]
	v_mfma_f32_16x16x32_bf16 v[94:97], v[98:101], v[178:181], v[94:97]
	v_mfma_f32_16x16x32_bf16 v[90:93], v[122:125], v[178:181], v[90:93]
	v_mfma_f32_16x16x32_bf16 v[78:81], v[98:101], v[186:189], v[78:81]
	v_mfma_f32_16x16x32_bf16 v[74:77], v[122:125], v[186:189], v[74:77]
	v_mfma_f32_16x16x32_bf16 v[158:161], v[110:113], v[166:169], v[158:161]
	v_mfma_f32_16x16x32_bf16 v[154:157], v[134:137], v[166:169], v[154:157]
	v_mfma_f32_16x16x32_bf16 v[118:121], v[110:113], v[174:177], v[118:121]
	v_mfma_f32_16x16x32_bf16 v[114:117], v[134:137], v[174:177], v[114:117]
	v_mfma_f32_16x16x32_bf16 v[94:97], v[110:113], v[182:185], v[94:97]
	v_mfma_f32_16x16x32_bf16 v[90:93], v[134:137], v[182:185], v[90:93]
	v_mfma_f32_16x16x32_bf16 v[78:81], v[110:113], v[204:207], v[78:81]
	v_mfma_f32_16x16x32_bf16 v[74:77], v[134:137], v[204:207], v[74:77]
	s_setprio 0
	s_setprio 1
	v_mfma_f32_16x16x32_bf16 v[130:133], v[138:141], v[162:165], v[130:133]
	v_mfma_f32_16x16x32_bf16 v[126:129], v[146:149], v[162:165], v[126:129]
	v_mfma_f32_16x16x32_bf16 v[106:109], v[138:141], v[170:173], v[106:109]
	v_mfma_f32_16x16x32_bf16 v[102:105], v[146:149], v[170:173], v[102:105]
	v_mfma_f32_16x16x32_bf16 v[86:89], v[138:141], v[178:181], v[86:89]
	v_mfma_f32_16x16x32_bf16 v[82:85], v[146:149], v[178:181], v[82:85]
	v_mfma_f32_16x16x32_bf16 v[70:73], v[138:141], v[186:189], v[70:73]
	v_mfma_f32_16x16x32_bf16 v[66:69], v[146:149], v[186:189], v[66:69]
	v_mfma_f32_16x16x32_bf16 v[130:133], v[142:145], v[166:169], v[130:133]
	v_mfma_f32_16x16x32_bf16 v[126:129], v[150:153], v[166:169], v[126:129]
	v_mfma_f32_16x16x32_bf16 v[106:109], v[142:145], v[174:177], v[106:109]
	v_mfma_f32_16x16x32_bf16 v[102:105], v[150:153], v[174:177], v[102:105]
	v_mfma_f32_16x16x32_bf16 v[86:89], v[142:145], v[182:185], v[86:89]
	v_mfma_f32_16x16x32_bf16 v[82:85], v[150:153], v[182:185], v[82:85]
	v_mfma_f32_16x16x32_bf16 v[70:73], v[142:145], v[204:207], v[70:73]
	s_setprio 3
	s_barrier
	v_mfma_f32_16x16x32_bf16 v[66:69], v[150:153], v[204:207], v[66:69]
	s_setprio 0
	s_add_i32 s18, s52, s40
	v_lshl_add_u64 v[208:209], s[36:37], 0, v[192:193]
	s_mov_b32 m0, s18
	ds_read_b128 v[162:165], v241 offset:16384
	ds_read_b128 v[166:169], v241 offset:17408
	ds_read_b128 v[170:173], v241 offset:18432
	ds_read_b128 v[174:177], v241 offset:19456
	ds_read_b128 v[178:181], v241 offset:20480
	ds_read_b128 v[182:185], v241 offset:21504
	ds_read_b128 v[186:189], v241 offset:22528
	ds_read_b128 v[204:207], v241 offset:23552
	global_load_lds_dwordx4 v[208:209], off
	s_add_i32 m0, s18, 0x2000
	s_add_u32 s18, s36, 0xb0000
	v_lshl_add_u64 v[210:211], s[36:37], 0, v[196:197]
	s_addc_u32 s19, s37, 0
	s_add_i32 s61, s53, s40
	global_load_lds_dwordx4 v[210:211], off
	v_lshl_add_u64 v[212:213], s[18:19], 0, v[192:193]
	s_mov_b32 m0, s61
	v_lshl_add_u64 v[214:215], s[38:39], 0, v[194:195]
	global_load_lds_dwordx4 v[212:213], off
	v_lshl_add_u64 v[212:213], s[18:19], 0, v[196:197]
	s_add_i32 m0, s61, 0x2000
	s_nop 0
	global_load_lds_dwordx4 v[212:213], off
	v_lshl_add_u64 v[212:213], s[38:39], 0, v[190:191]
	s_mov_b32 m0, s41
	s_nop 0
	global_load_lds_dwordx4 v[212:213], off
	s_mov_b32 m0, s42
	s_nop 0
	global_load_lds_dwordx4 v[214:215], off
	s_waitcnt vmcnt(8)
	s_waitcnt lgkmcnt(0)
	s_setprio 1
	s_barrier
; #define PG8_STAGE(bufoff, gbase, voff) do { _Pragma("unroll") for (int _i = 0; _i < 2; ++_i) \
;         __builtin_amdgcn_global_load_lds((const unsigned*)((const char*)(gbase) + (voff)[_i]), (PG8_LAS unsigned*)(lds + (bufoff) + ldsw + _i * 8192), 16, 0, 0); } while (0)
; #define PG8_LDA(dst, b, h) do { _Pragma("unroll") for (int m = 0; m < 4; ++m) _Pragma("unroll") for (int k = 0; k < 2; ++k) dst[m][k] = *(const PG8_LAS bf16x8*)(lds + PG8_SA(b, h) + aoff + m * 2048 + k * 1024); } while (0)
; #define PG8_LDB(dst, b, h) do { _Pragma("unroll") for (int n = 0; n < 2; ++n) _Pragma("unroll") for (int k = 0; k < 2; ++k) dst[n][k] = *(const PG8_LAS bf16x8*)(lds + PG8_SB(b, h) + boff + n * 2048 + k * 1024); } while (0)
; #define PG8_MMA(ai, bj, At, Bt) do { __builtin_amdgcn_s_setprio(1); _Pragma("unroll") for (int m = 0; m < 4; ++m) _Pragma("unroll") for (int n = 0; n < 2; ++n) _Pragma("unroll") for (int k = 0; k < 2; ++k) \
;         acc[ai][bj][m][n] = __builtin_amdgcn_mfma_f32_16x16x32_bf16(Bt[n][k], At[m][k], acc[ai][bj][m][n], 0, 0, 0); __builtin_amdgcn_s_setprio(0); } while (0)
; #define PG8_WAIT_V(n) asm volatile("s_waitcnt vmcnt(" #n ")" ::: "memory")
; #define PG8_WAIT_L(n) asm volatile("s_waitcnt lgkmcnt(" #n ")" ::: "memory")
; #define PG8_BAR __builtin_amdgcn_s_barrier()
; #define PG8_SCHED __builtin_amdgcn_sched_barrier(0)
; template <class Epi, class Sched, bool ALIGN_EPI = false, bool SP2 = false>
; __device__ __forceinline__ void gemm_phase(PG8_LAS unsigned char* lds, const Gemm g, const Sched& S, const Epi& E) {
;     ...
;             PG8_WAIT_V(8); PG8_WAIT_L(0); PG8_BAR; PG8_MMA(1, 0, At, B0); PG8_MMA(1, 1, At, B1); PG8_BAR; PG8_SCHED;
;             PG8_LDB(B0, 1, 0); PG8_LDB(B1, 1, 1); PG8_SCHED; PG8_LDA(At, 1, 0); PG8_STAGE(PG8_SA(0, 1), a2 + hstep, voffA);
;             PG8_WAIT_V(8); PG8_WAIT_L(0); PG8_BAR; PG8_MMA(0, 0, At, B0); PG8_MMA(0, 1, At, B1); PG8_BAR; PG8_SCHED;
	s_waitcnt lgkmcnt(0)
	v_mfma_f32_16x16x32_bf16 v[62:65], v[98:101], v[162:165], v[62:65]
	v_mfma_f32_16x16x32_bf16 v[58:61], v[122:125], v[162:165], v[58:61]
	v_mfma_f32_16x16x32_bf16 v[46:49], v[98:101], v[170:173], v[46:49]
	v_mfma_f32_16x16x32_bf16 v[42:45], v[122:125], v[170:173], v[42:45]
	v_mfma_f32_16x16x32_bf16 v[30:33], v[98:101], v[178:181], v[30:33]
	v_mfma_f32_16x16x32_bf16 v[26:29], v[122:125], v[178:181], v[26:29]
	v_mfma_f32_16x16x32_bf16 v[14:17], v[98:101], v[186:189], v[14:17]
	v_mfma_f32_16x16x32_bf16 v[10:13], v[122:125], v[186:189], v[10:13]
	v_mfma_f32_16x16x32_bf16 v[62:65], v[110:113], v[166:169], v[62:65]
	v_mfma_f32_16x16x32_bf16 v[58:61], v[134:137], v[166:169], v[58:61]
	v_mfma_f32_16x16x32_bf16 v[46:49], v[110:113], v[174:177], v[46:49]
	v_mfma_f32_16x16x32_bf16 v[42:45], v[134:137], v[174:177], v[42:45]
	v_mfma_f32_16x16x32_bf16 v[30:33], v[110:113], v[182:185], v[30:33]
	v_mfma_f32_16x16x32_bf16 v[26:29], v[134:137], v[182:185], v[26:29]
	v_mfma_f32_16x16x32_bf16 v[14:17], v[110:113], v[204:207], v[14:17]
	v_mfma_f32_16x16x32_bf16 v[10:13], v[134:137], v[204:207], v[10:13]
	s_setprio 0
	s_setprio 1
	v_mfma_f32_16x16x32_bf16 v[54:57], v[138:141], v[162:165], v[54:57]
	v_mfma_f32_16x16x32_bf16 v[50:53], v[146:149], v[162:165], v[50:53]
	v_mfma_f32_16x16x32_bf16 v[38:41], v[138:141], v[170:173], v[38:41]
	v_mfma_f32_16x16x32_bf16 v[34:37], v[146:149], v[170:173], v[34:37]
	v_mfma_f32_16x16x32_bf16 v[22:25], v[138:141], v[178:181], v[22:25]
	v_mfma_f32_16x16x32_bf16 v[18:21], v[146:149], v[178:181], v[18:21]
	v_mfma_f32_16x16x32_bf16 v[6:9], v[138:141], v[186:189], v[6:9]
	v_mfma_f32_16x16x32_bf16 v[2:5], v[146:149], v[186:189], v[2:5]
	v_mfma_f32_16x16x32_bf16 v[54:57], v[142:145], v[166:169], v[54:57]
	v_mfma_f32_16x16x32_bf16 v[50:53], v[150:153], v[166:169], v[50:53]
	v_mfma_f32_16x16x32_bf16 v[38:41], v[142:145], v[174:177], v[38:41]
	v_mfma_f32_16x16x32_bf16 v[34:37], v[150:153], v[174:177], v[34:37]
	v_mfma_f32_16x16x32_bf16 v[22:25], v[142:145], v[182:185], v[22:25]
	v_mfma_f32_16x16x32_bf16 v[18:21], v[150:153], v[182:185], v[18:21]
	v_mfma_f32_16x16x32_bf16 v[6:9], v[142:145], v[204:207], v[6:9]
	s_setprio 3
	s_barrier
	v_mfma_f32_16x16x32_bf16 v[2:5], v[150:153], v[204:207], v[2:5]
	s_setprio 0
	s_add_i32 s61, 0, 0x18000
	s_add_i32 s62, 0, 0x1c000
	v_add_u32_e32 v134, s61, v237
	v_add_u32_e32 v150, s62, v237
	ds_read_b128 v[98:101], v134
	ds_read_b128 v[110:113], v134 offset:1024
	ds_read_b128 v[122:125], v134 offset:2048
	ds_read_b128 v[134:137], v134 offset:3072
	ds_read_b128 v[138:141], v150
	ds_read_b128 v[142:145], v150 offset:1024
	ds_read_b128 v[146:149], v150 offset:2048
	ds_read_b128 v[150:153], v150 offset:3072
	s_add_u32 s18, s38, 0xb0000
	s_addc_u32 s19, s39, 0
	s_mov_b32 m0, s43
	v_lshl_add_u64 v[216:217], s[18:19], 0, v[190:191]
	ds_read_b128 v[162:165], v241 offset:32768
	ds_read_b128 v[166:169], v241 offset:33792
	ds_read_b128 v[170:173], v241 offset:34816
	ds_read_b128 v[174:177], v241 offset:35840
	ds_read_b128 v[178:181], v241 offset:36864
	ds_read_b128 v[182:185], v241 offset:37888
	ds_read_b128 v[186:189], v241 offset:38912
	ds_read_b128 v[204:207], v241 offset:39936
	global_load_lds_dwordx4 v[216:217], off
	v_lshl_add_u64 v[216:217], s[18:19], 0, v[194:195]
	s_mov_b32 m0, s44
	s_nop 0
	global_load_lds_dwordx4 v[216:217], off
	s_waitcnt vmcnt(8)
	s_waitcnt lgkmcnt(0)
	s_setprio 1
	s_barrier
	s_waitcnt lgkmcnt(0)
	v_mfma_f32_16x16x32_bf16 v[158:161], v[98:101], v[162:165], v[158:161]
	v_mfma_f32_16x16x32_bf16 v[154:157], v[122:125], v[162:165], v[154:157]
	v_mfma_f32_16x16x32_bf16 v[118:121], v[98:101], v[170:173], v[118:121]
	v_mfma_f32_16x16x32_bf16 v[114:117], v[122:125], v[170:173], v[114:117]
	v_mfma_f32_16x16x32_bf16 v[94:97], v[98:101], v[178:181], v[94:97]
	v_mfma_f32_16x16x32_bf16 v[90:93], v[122:125], v[178:181], v[90:93]
	v_mfma_f32_16x16x32_bf16 v[78:81], v[98:101], v[186:189], v[78:81]
	v_mfma_f32_16x16x32_bf16 v[74:77], v[122:125], v[186:189], v[74:77]
	v_mfma_f32_16x16x32_bf16 v[158:161], v[110:113], v[166:169], v[158:161]
	v_mfma_f32_16x16x32_bf16 v[154:157], v[134:137], v[166:169], v[154:157]
	v_mfma_f32_16x16x32_bf16 v[118:121], v[110:113], v[174:177], v[118:121]
	v_mfma_f32_16x16x32_bf16 v[114:117], v[134:137], v[174:177], v[114:117]
	v_mfma_f32_16x16x32_bf16 v[94:97], v[110:113], v[182:185], v[94:97]
	v_mfma_f32_16x16x32_bf16 v[90:93], v[134:137], v[182:185], v[90:93]
	v_mfma_f32_16x16x32_bf16 v[78:81], v[110:113], v[204:207], v[78:81]
	v_mfma_f32_16x16x32_bf16 v[74:77], v[134:137], v[204:207], v[74:77]
	s_setprio 0
	s_setprio 1
	v_mfma_f32_16x16x32_bf16 v[130:133], v[138:141], v[162:165], v[130:133]
	v_mfma_f32_16x16x32_bf16 v[126:129], v[146:149], v[162:165], v[126:129]
	v_mfma_f32_16x16x32_bf16 v[106:109], v[138:141], v[170:173], v[106:109]
	v_mfma_f32_16x16x32_bf16 v[102:105], v[146:149], v[170:173], v[102:105]
	v_mfma_f32_16x16x32_bf16 v[86:89], v[138:141], v[178:181], v[86:89]
	v_mfma_f32_16x16x32_bf16 v[82:85], v[146:149], v[178:181], v[82:85]
	v_mfma_f32_16x16x32_bf16 v[70:73], v[138:141], v[186:189], v[70:73]
	v_mfma_f32_16x16x32_bf16 v[66:69], v[146:149], v[186:189], v[66:69]
	v_mfma_f32_16x16x32_bf16 v[130:133], v[142:145], v[166:169], v[130:133]
	v_mfma_f32_16x16x32_bf16 v[126:129], v[150:153], v[166:169], v[126:129]
	v_mfma_f32_16x16x32_bf16 v[106:109], v[142:145], v[174:177], v[106:109]
	v_mfma_f32_16x16x32_bf16 v[102:105], v[150:153], v[174:177], v[102:105]
	v_mfma_f32_16x16x32_bf16 v[86:89], v[142:145], v[182:185], v[86:89]
	v_mfma_f32_16x16x32_bf16 v[82:85], v[150:153], v[182:185], v[82:85]
	v_mfma_f32_16x16x32_bf16 v[70:73], v[142:145], v[204:207], v[70:73]
	s_setprio 3
	s_barrier
; #define PG8_STAGE(bufoff, gbase, voff) do { _Pragma("unroll") for (int _i = 0; _i < 2; ++_i) \
;         __builtin_amdgcn_global_load_lds((const unsigned*)((const char*)(gbase) + (voff)[_i]), (PG8_LAS unsigned*)(lds + (bufoff) + ldsw + _i * 8192), 16, 0, 0); } while (0)
; #define PG8_LDA(dst, b, h) do { _Pragma("unroll") for (int m = 0; m < 4; ++m) _Pragma("unroll") for (int k = 0; k < 2; ++k) dst[m][k] = *(const PG8_LAS bf16x8*)(lds + PG8_SA(b, h) + aoff + m * 2048 + k * 1024); } while (0)
; #define PG8_MMA(ai, bj, At, Bt) do { __builtin_amdgcn_s_setprio(1); _Pragma("unroll") for (int m = 0; m < 4; ++m) _Pragma("unroll") for (int n = 0; n < 2; ++n) _Pragma("unroll") for (int k = 0; k < 2; ++k) \
;         acc[ai][bj][m][n] = __builtin_amdgcn_mfma_f32_16x16x32_bf16(Bt[n][k], At[m][k], acc[ai][bj][m][n], 0, 0, 0); __builtin_amdgcn_s_setprio(0); } while (0)
; #define PG8_WAIT_V(n) asm volatile("s_waitcnt vmcnt(" #n ")" ::: "memory")
; #define PG8_WAIT_L(n) asm volatile("s_waitcnt lgkmcnt(" #n ")" ::: "memory")
; #define PG8_BAR __builtin_amdgcn_s_barrier()
; #define PG8_SCHED __builtin_amdgcn_sched_barrier(0)
;     __device__ __forceinline__ void operator()(const f32x4 (&acc)[2][2][4][2], const Unit& u, int wr, int wc, int fr, int fq) const {
;     ...
;                 for (int bj = 0; bj < 2; ++bj) bva[ai][m][bj] = *(const u32x4*)(Xb + (size_t)(row0 + ai * HALF + m * 16) * DM + col0 + bj * HALF);
; template <class Epi, class Sched, bool ALIGN_EPI = false, bool SP2 = false>
; __device__ __forceinline__ void gemm_phase(PG8_LAS unsigned char* lds, const Gemm g, const Sched& S, const Epi& E) {
;     ...
;             PG8_LDA(At, 1, 1); PG8_STAGE(PG8_SB(1, 0), b3, voffB); PG8_STAGE(PG8_SB(1, 1), b3 + hstep, voffB); PG8_STAGE(PG8_SA(1, 0), a3, voffA);
;             PG8_WAIT_V(8); PG8_WAIT_L(0); PG8_BAR; PG8_MMA(1, 0, At, B0); PG8_MMA(1, 1, At, B1); PG8_BAR; PG8_SCHED;
	v_mfma_f32_16x16x32_bf16 v[66:69], v[150:153], v[204:207], v[66:69]
	s_setprio 0
	s_add_i32 s18, s61, s40
	v_lshl_add_u64 v[208:209], v[208:209], 0, s[16:17]
	s_mov_b32 m0, s18
	ds_read_b128 v[162:165], v241 offset:49152
	ds_read_b128 v[166:169], v241 offset:50176
	ds_read_b128 v[170:173], v241 offset:51200
	ds_read_b128 v[174:177], v241 offset:52224
	ds_read_b128 v[178:181], v241 offset:53248
	ds_read_b128 v[182:185], v241 offset:54272
	ds_read_b128 v[186:189], v241 offset:55296
	ds_read_b128 v[204:207], v241 offset:56320
	global_load_lds_dwordx4 v[208:209], off
	s_add_i32 m0, s18, 0x2000
	s_add_u32 s18, s36, 0xb0080
	v_lshl_add_u64 v[208:209], v[210:211], 0, s[16:17]
	s_addc_u32 s19, s37, 0
	s_add_i32 s36, s62, s40
	global_load_lds_dwordx4 v[208:209], off
	v_lshl_add_u64 v[208:209], s[18:19], 0, v[192:193]
	s_mov_b32 m0, s36
	s_nop 0
	global_load_lds_dwordx4 v[208:209], off
	v_lshl_add_u64 v[208:209], s[18:19], 0, v[196:197]
	s_add_i32 m0, s36, 0x2000
	s_nop 0
	global_load_lds_dwordx4 v[208:209], off
	v_lshl_add_u64 v[208:209], v[212:213], 0, s[16:17]
	s_mov_b32 m0, s46
	s_nop 0
	global_load_lds_dwordx4 v[208:209], off
	v_lshl_add_u64 v[208:209], v[214:215], 0, s[16:17]
	s_mov_b32 m0, s47
	s_nop 0
	global_load_lds_dwordx4 v[208:209], off
	s_waitcnt vmcnt(8)
	s_waitcnt lgkmcnt(0)
	s_setprio 1
	s_barrier
	s_waitcnt lgkmcnt(0)
	v_mfma_f32_16x16x32_bf16 v[62:65], v[98:101], v[162:165], v[62:65]
	v_mfma_f32_16x16x32_bf16 v[58:61], v[122:125], v[162:165], v[58:61]
	v_mfma_f32_16x16x32_bf16 v[46:49], v[98:101], v[170:173], v[46:49]
	v_mfma_f32_16x16x32_bf16 v[42:45], v[122:125], v[170:173], v[42:45]
	v_mfma_f32_16x16x32_bf16 v[30:33], v[98:101], v[178:181], v[30:33]
	v_mfma_f32_16x16x32_bf16 v[26:29], v[122:125], v[178:181], v[26:29]
	v_mfma_f32_16x16x32_bf16 v[14:17], v[98:101], v[186:189], v[14:17]
	v_mfma_f32_16x16x32_bf16 v[10:13], v[122:125], v[186:189], v[10:13]
	v_mfma_f32_16x16x32_bf16 v[62:65], v[110:113], v[166:169], v[62:65]
	v_mfma_f32_16x16x32_bf16 v[58:61], v[134:137], v[166:169], v[58:61]
	v_mfma_f32_16x16x32_bf16 v[46:49], v[110:113], v[174:177], v[46:49]
	v_mfma_f32_16x16x32_bf16 v[42:45], v[134:137], v[174:177], v[42:45]
	v_mfma_f32_16x16x32_bf16 v[30:33], v[110:113], v[182:185], v[30:33]
	v_mfma_f32_16x16x32_bf16 v[26:29], v[134:137], v[182:185], v[26:29]
	v_mfma_f32_16x16x32_bf16 v[14:17], v[110:113], v[204:207], v[14:17]
	v_mfma_f32_16x16x32_bf16 v[10:13], v[134:137], v[204:207], v[10:13]
	s_setprio 0
	s_setprio 1
	v_mfma_f32_16x16x32_bf16 v[54:57], v[138:141], v[162:165], v[54:57]
	v_mfma_f32_16x16x32_bf16 v[50:53], v[146:149], v[162:165], v[50:53]
	v_mfma_f32_16x16x32_bf16 v[38:41], v[138:141], v[170:173], v[38:41]
	v_mfma_f32_16x16x32_bf16 v[34:37], v[146:149], v[170:173], v[34:37]
	v_mfma_f32_16x16x32_bf16 v[22:25], v[138:141], v[178:181], v[22:25]
	v_mfma_f32_16x16x32_bf16 v[18:21], v[146:149], v[178:181], v[18:21]
	v_mfma_f32_16x16x32_bf16 v[6:9], v[138:141], v[186:189], v[6:9]
	v_mfma_f32_16x16x32_bf16 v[2:5], v[146:149], v[186:189], v[2:5]
	v_mfma_f32_16x16x32_bf16 v[54:57], v[142:145], v[166:169], v[54:57]
	v_mfma_f32_16x16x32_bf16 v[50:53], v[150:153], v[166:169], v[50:53]
	v_mfma_f32_16x16x32_bf16 v[38:41], v[142:145], v[174:177], v[38:41]
	v_mfma_f32_16x16x32_bf16 v[34:37], v[150:153], v[174:177], v[34:37]
	v_mfma_f32_16x16x32_bf16 v[22:25], v[142:145], v[182:185], v[22:25]
	v_mfma_f32_16x16x32_bf16 v[18:21], v[150:153], v[182:185], v[18:21]
	v_mfma_f32_16x16x32_bf16 v[6:9], v[142:145], v[204:207], v[6:9]
	s_setprio 3
	s_barrier
	v_mfma_f32_16x16x32_bf16 v[2:5], v[150:153], v[204:207], v[2:5]
	s_setprio 0
	s_add_i32 s60, s60, 2
	s_add_u32 s34, s34, 0x100
	s_addc_u32 s35, s35, 0
	s_add_u32 s58, s58, 0x100
	s_addc_u32 s59, s59, 0
	s_cmp_gt_u32 s60, 41
	s_cbranch_scc1 .Lrp_gen_p5
	s_cmp_lg_u32 s60, 40
	s_cbranch_scc1 .LBB0_892
	s_cmpk_lg_i32 s33, 0x100
	s_cbranch_scc1 .LBB0_892
	ds_read_b128 v[98:101], v239
	ds_read_b128 v[110:113], v239 offset:1024
	ds_read_b128 v[122:125], v239 offset:2048
	ds_read_b128 v[134:137], v239 offset:3072
	ds_read_b128 v[138:141], v240
	ds_read_b128 v[142:145], v240 offset:1024
	ds_read_b128 v[146:149], v240 offset:2048
	ds_read_b128 v[150:153], v240 offset:3072
	s_add_u32 s18, s34, 0xfff50080
	s_addc_u32 s19, s35, -1
	s_cmp_eq_u32 s60, 40
	s_cselect_b32 s39, s1, s19
	s_cselect_b32 s38, s0, s18
	s_cselect_b32 s37, s31, s59
	s_cselect_b32 s36, s30, s58
	v_lshl_add_u64 v[208:209], s[34:35], 0, v[198:199]
	s_add_i32 m0, s41, 0xc000
	ds_read_b128 v[162:165], v241
	ds_read_b128 v[166:169], v241 offset:1024
	ds_read_b128 v[170:173], v241 offset:2048
	ds_read_b128 v[174:177], v241 offset:3072
	ds_read_b128 v[178:181], v241 offset:4096
	ds_read_b128 v[182:185], v241 offset:5120
	ds_read_b128 v[186:189], v241 offset:6144
	ds_read_b128 v[204:207], v241 offset:7168
	global_load_lds_dwordx4 v[208:209], off
	v_lshl_add_u64 v[208:209], s[34:35], 0, v[200:201]
	s_add_i32 m0, s41, 0xe000
	s_nop 0
	global_load_lds_dwordx4 v[208:209], off
	v_lshl_or_b32 v255, s12, 8, v238
	v_lshl_add_u32 v235, s57, 8, v1
	v_lshlrev_b32_e32 v255, 1, v255
	v_lshl_add_u32 v255, v235, 11, v255
	s_mov_b64 s[84:85], s[20:21]
	global_load_dwordx4 v[242:245], v255, s[84:85]
	global_load_dwordx4 v[208:211], v255, s[84:85] offset:256
	s_add_u32 s84, s20, 0x8000
	s_addc_u32 s85, s21, 0
	global_load_dwordx4 v[212:215], v255, s[84:85]
	global_load_dwordx4 v[216:219], v255, s[84:85] offset:256
	s_add_u32 s84, s20, 0x10000
	s_addc_u32 s85, s21, 0
	global_load_dwordx4 v[220:223], v255, s[84:85]
	global_load_dwordx4 v[224:227], v255, s[84:85] offset:256
	s_add_u32 s84, s20, 0x18000
	s_addc_u32 s85, s21, 0
	global_load_dwordx4 v[228:231], v255, s[84:85]
	global_load_dwordx4 v[232:235], v255, s[84:85] offset:256
	s_add_u32 s84, s20, 0x40000
	s_addc_u32 s85, s21, 0
	global_load_dwordx4 v[246:249], v255, s[84:85]
	global_load_dwordx4 v[250:253], v255, s[84:85] offset:256
	s_waitcnt vmcnt(18)
	s_waitcnt lgkmcnt(0)
	s_setprio 1
	s_barrier
; #define PG8_STAGE(bufoff, gbase, voff) do { _Pragma("unroll") for (int _i = 0; _i < 2; ++_i) \
;         __builtin_amdgcn_global_load_lds((const unsigned*)((const char*)(gbase) + (voff)[_i]), (PG8_LAS unsigned*)(lds + (bufoff) + ldsw + _i * 8192), 16, 0, 0); } while (0)
; #define PG8_LDA(dst, b, h) do { _Pragma("unroll") for (int m = 0; m < 4; ++m) _Pragma("unroll") for (int k = 0; k < 2; ++k) dst[m][k] = *(const PG8_LAS bf16x8*)(lds + PG8_SA(b, h) + aoff + m * 2048 + k * 1024); } while (0)
; #define PG8_LDB(dst, b, h) do { _Pragma("unroll") for (int n = 0; n < 2; ++n) _Pragma("unroll") for (int k = 0; k < 2; ++k) dst[n][k] = *(const PG8_LAS bf16x8*)(lds + PG8_SB(b, h) + boff + n * 2048 + k * 1024); } while (0)
; #define PG8_MMA(ai, bj, At, Bt) do { __builtin_amdgcn_s_setprio(1); _Pragma("unroll") for (int m = 0; m < 4; ++m) _Pragma("unroll") for (int n = 0; n < 2; ++n) _Pragma("unroll") for (int k = 0; k < 2; ++k) \
;         acc[ai][bj][m][n] = __builtin_amdgcn_mfma_f32_16x16x32_bf16(Bt[n][k], At[m][k], acc[ai][bj][m][n], 0, 0, 0); __builtin_amdgcn_s_setprio(0); } while (0)
; #define PG8_WAIT_V(n) asm volatile("s_waitcnt vmcnt(" #n ")" ::: "memory")
; #define PG8_WAIT_L(n) asm volatile("s_waitcnt lgkmcnt(" #n ")" ::: "memory")
; #define PG8_BAR __builtin_amdgcn_s_barrier()
; #define PG8_SCHED __builtin_amdgcn_sched_barrier(0)
; template <class Epi, class Sched, bool ALIGN_EPI = false, bool SP2 = false>
; __device__ __forceinline__ void gemm_phase(PG8_LAS unsigned char* lds, const Gemm g, const Sched& S, const Epi& E) {
;     ...
;             PG8_WAIT_V(8); PG8_WAIT_L(0); PG8_BAR; PG8_MMA(0, 0, At, B0); PG8_MMA(0, 1, At, B1); PG8_BAR; PG8_SCHED;
;             PG8_LDA(At, 0, 1); PG8_STAGE(PG8_SB(0, 0), b2, voffB); PG8_STAGE(PG8_SB(0, 1), b2 + hstep, voffB); PG8_STAGE(PG8_SA(0, 0), a2, voffA);
;             PG8_WAIT_V(8); PG8_WAIT_L(0); PG8_BAR; PG8_MMA(1, 0, At, B0); PG8_MMA(1, 1, At, B1); PG8_BAR; PG8_SCHED;
;             PG8_LDB(B0, 1, 0); PG8_LDB(B1, 1, 1); PG8_SCHED; PG8_LDA(At, 1, 0); PG8_STAGE(PG8_SA(0, 1), a2 + hstep, voffA);
;             PG8_WAIT_V(8); PG8_WAIT_L(0); PG8_BAR; PG8_MMA(0, 0, At, B0); PG8_MMA(0, 1, At, B1); PG8_BAR; PG8_SCHED;
	s_waitcnt lgkmcnt(0)
	v_mfma_f32_16x16x32_bf16 v[158:161], v[98:101], v[162:165], v[158:161]
	v_mfma_f32_16x16x32_bf16 v[154:157], v[122:125], v[162:165], v[154:157]
	v_mfma_f32_16x16x32_bf16 v[118:121], v[98:101], v[170:173], v[118:121]
	v_mfma_f32_16x16x32_bf16 v[114:117], v[122:125], v[170:173], v[114:117]
	v_mfma_f32_16x16x32_bf16 v[94:97], v[98:101], v[178:181], v[94:97]
	v_mfma_f32_16x16x32_bf16 v[90:93], v[122:125], v[178:181], v[90:93]
	v_mfma_f32_16x16x32_bf16 v[78:81], v[98:101], v[186:189], v[78:81]
	v_mfma_f32_16x16x32_bf16 v[74:77], v[122:125], v[186:189], v[74:77]
	v_mfma_f32_16x16x32_bf16 v[158:161], v[110:113], v[166:169], v[158:161]
	v_mfma_f32_16x16x32_bf16 v[154:157], v[134:137], v[166:169], v[154:157]
	v_mfma_f32_16x16x32_bf16 v[118:121], v[110:113], v[174:177], v[118:121]
	v_mfma_f32_16x16x32_bf16 v[114:117], v[134:137], v[174:177], v[114:117]
	v_mfma_f32_16x16x32_bf16 v[94:97], v[110:113], v[182:185], v[94:97]
	v_mfma_f32_16x16x32_bf16 v[90:93], v[134:137], v[182:185], v[90:93]
	v_mfma_f32_16x16x32_bf16 v[78:81], v[110:113], v[204:207], v[78:81]
	v_mfma_f32_16x16x32_bf16 v[74:77], v[134:137], v[204:207], v[74:77]
	s_setprio 0
	s_setprio 1
	v_mfma_f32_16x16x32_bf16 v[130:133], v[138:141], v[162:165], v[130:133]
	v_mfma_f32_16x16x32_bf16 v[126:129], v[146:149], v[162:165], v[126:129]
	v_mfma_f32_16x16x32_bf16 v[106:109], v[138:141], v[170:173], v[106:109]
	v_mfma_f32_16x16x32_bf16 v[102:105], v[146:149], v[170:173], v[102:105]
	v_mfma_f32_16x16x32_bf16 v[86:89], v[138:141], v[178:181], v[86:89]
	v_mfma_f32_16x16x32_bf16 v[82:85], v[146:149], v[178:181], v[82:85]
	v_mfma_f32_16x16x32_bf16 v[70:73], v[138:141], v[186:189], v[70:73]
	v_mfma_f32_16x16x32_bf16 v[66:69], v[146:149], v[186:189], v[66:69]
	v_mfma_f32_16x16x32_bf16 v[130:133], v[142:145], v[166:169], v[130:133]
	v_mfma_f32_16x16x32_bf16 v[126:129], v[150:153], v[166:169], v[126:129]
	v_mfma_f32_16x16x32_bf16 v[106:109], v[142:145], v[174:177], v[106:109]
	v_mfma_f32_16x16x32_bf16 v[102:105], v[150:153], v[174:177], v[102:105]
	v_mfma_f32_16x16x32_bf16 v[86:89], v[142:145], v[182:185], v[86:89]
	v_mfma_f32_16x16x32_bf16 v[82:85], v[150:153], v[182:185], v[82:85]
	v_mfma_f32_16x16x32_bf16 v[70:73], v[142:145], v[204:207], v[70:73]
	s_setprio 3
	s_barrier
	v_mfma_f32_16x16x32_bf16 v[66:69], v[150:153], v[204:207], v[66:69]
	s_setprio 0
	s_add_i32 s18, s52, s40
	s_mov_b32 m0, s18
	ds_read_b128 v[162:165], v241 offset:16384
	ds_read_b128 v[166:169], v241 offset:17408
	ds_read_b128 v[170:173], v241 offset:18432
	ds_read_b128 v[174:177], v241 offset:19456
	ds_read_b128 v[178:181], v241 offset:20480
	ds_read_b128 v[182:185], v241 offset:21504
	ds_read_b128 v[186:189], v241 offset:22528
	ds_read_b128 v[204:207], v241 offset:23552
	s_add_i32 m0, s18, 0x2000
	s_add_u32 s18, s36, 0xb0000
	s_addc_u32 s19, s37, 0
	s_add_i32 s61, s53, s40
	s_mov_b32 m0, s61
	s_add_i32 m0, s61, 0x2000
	s_nop 0
	s_mov_b32 m0, s41
	s_nop 0
	s_mov_b32 m0, s42
	s_nop 0
	s_waitcnt vmcnt(12)
	s_waitcnt lgkmcnt(0)
	s_setprio 1
	s_barrier
	s_waitcnt lgkmcnt(0)
	v_mfma_f32_16x16x32_bf16 v[62:65], v[98:101], v[162:165], v[62:65]
	v_mfma_f32_16x16x32_bf16 v[58:61], v[122:125], v[162:165], v[58:61]
	v_mfma_f32_16x16x32_bf16 v[46:49], v[98:101], v[170:173], v[46:49]
	v_mfma_f32_16x16x32_bf16 v[42:45], v[122:125], v[170:173], v[42:45]
	v_mfma_f32_16x16x32_bf16 v[30:33], v[98:101], v[178:181], v[30:33]
	v_mfma_f32_16x16x32_bf16 v[26:29], v[122:125], v[178:181], v[26:29]
	v_mfma_f32_16x16x32_bf16 v[14:17], v[98:101], v[186:189], v[14:17]
	v_mfma_f32_16x16x32_bf16 v[10:13], v[122:125], v[186:189], v[10:13]
	v_mfma_f32_16x16x32_bf16 v[62:65], v[110:113], v[166:169], v[62:65]
	v_mfma_f32_16x16x32_bf16 v[58:61], v[134:137], v[166:169], v[58:61]
	v_mfma_f32_16x16x32_bf16 v[46:49], v[110:113], v[174:177], v[46:49]
	v_mfma_f32_16x16x32_bf16 v[42:45], v[134:137], v[174:177], v[42:45]
	v_mfma_f32_16x16x32_bf16 v[30:33], v[110:113], v[182:185], v[30:33]
	v_mfma_f32_16x16x32_bf16 v[26:29], v[134:137], v[182:185], v[26:29]
	v_mfma_f32_16x16x32_bf16 v[14:17], v[110:113], v[204:207], v[14:17]
	v_mfma_f32_16x16x32_bf16 v[10:13], v[134:137], v[204:207], v[10:13]
	s_setprio 0
	s_setprio 1
	v_mfma_f32_16x16x32_bf16 v[54:57], v[138:141], v[162:165], v[54:57]
	v_mfma_f32_16x16x32_bf16 v[50:53], v[146:149], v[162:165], v[50:53]
	v_mfma_f32_16x16x32_bf16 v[38:41], v[138:141], v[170:173], v[38:41]
	v_mfma_f32_16x16x32_bf16 v[34:37], v[146:149], v[170:173], v[34:37]
	v_mfma_f32_16x16x32_bf16 v[22:25], v[138:141], v[178:181], v[22:25]
	v_mfma_f32_16x16x32_bf16 v[18:21], v[146:149], v[178:181], v[18:21]
	v_mfma_f32_16x16x32_bf16 v[6:9], v[138:141], v[186:189], v[6:9]
	v_mfma_f32_16x16x32_bf16 v[2:5], v[146:149], v[186:189], v[2:5]
	v_mfma_f32_16x16x32_bf16 v[54:57], v[142:145], v[166:169], v[54:57]
	v_mfma_f32_16x16x32_bf16 v[50:53], v[150:153], v[166:169], v[50:53]
	v_mfma_f32_16x16x32_bf16 v[38:41], v[142:145], v[174:177], v[38:41]
	v_mfma_f32_16x16x32_bf16 v[34:37], v[150:153], v[174:177], v[34:37]
	v_mfma_f32_16x16x32_bf16 v[22:25], v[142:145], v[182:185], v[22:25]
	v_mfma_f32_16x16x32_bf16 v[18:21], v[150:153], v[182:185], v[18:21]
	v_mfma_f32_16x16x32_bf16 v[6:9], v[142:145], v[204:207], v[6:9]
	s_setprio 3
	s_barrier
; #define PG8_STAGE(bufoff, gbase, voff) do { _Pragma("unroll") for (int _i = 0; _i < 2; ++_i) \
;         __builtin_amdgcn_global_load_lds((const unsigned*)((const char*)(gbase) + (voff)[_i]), (PG8_LAS unsigned*)(lds + (bufoff) + ldsw + _i * 8192), 16, 0, 0); } while (0)
; #define PG8_LDA(dst, b, h) do { _Pragma("unroll") for (int m = 0; m < 4; ++m) _Pragma("unroll") for (int k = 0; k < 2; ++k) dst[m][k] = *(const PG8_LAS bf16x8*)(lds + PG8_SA(b, h) + aoff + m * 2048 + k * 1024); } while (0)
; #define PG8_LDB(dst, b, h) do { _Pragma("unroll") for (int n = 0; n < 2; ++n) _Pragma("unroll") for (int k = 0; k < 2; ++k) dst[n][k] = *(const PG8_LAS bf16x8*)(lds + PG8_SB(b, h) + boff + n * 2048 + k * 1024); } while (0)
; #define PG8_MMA(ai, bj, At, Bt) do { __builtin_amdgcn_s_setprio(1); _Pragma("unroll") for (int m = 0; m < 4; ++m) _Pragma("unroll") for (int n = 0; n < 2; ++n) _Pragma("unroll") for (int k = 0; k < 2; ++k) \
;         acc[ai][bj][m][n] = __builtin_amdgcn_mfma_f32_16x16x32_bf16(Bt[n][k], At[m][k], acc[ai][bj][m][n], 0, 0, 0); __builtin_amdgcn_s_setprio(0); } while (0)
; #define PG8_WAIT_V(n) asm volatile("s_waitcnt vmcnt(" #n ")" ::: "memory")
; #define PG8_WAIT_L(n) asm volatile("s_waitcnt lgkmcnt(" #n ")" ::: "memory")
; #define PG8_BAR __builtin_amdgcn_s_barrier()
; #define PG8_SCHED __builtin_amdgcn_sched_barrier(0)
; template <class Epi, class Sched, bool ALIGN_EPI = false, bool SP2 = false>
; __device__ __forceinline__ void gemm_phase(PG8_LAS unsigned char* lds, const Gemm g, const Sched& S, const Epi& E) {
;     ...
;             PG8_WAIT_V(8); PG8_WAIT_L(0); PG8_BAR; PG8_MMA(1, 0, At, B0); PG8_MMA(1, 1, At, B1); PG8_BAR; PG8_SCHED;
;             PG8_LDB(B0, 1, 0); PG8_LDB(B1, 1, 1); PG8_SCHED; PG8_LDA(At, 1, 0); PG8_STAGE(PG8_SA(0, 1), a2 + hstep, voffA);
;             PG8_WAIT_V(8); PG8_WAIT_L(0); PG8_BAR; PG8_MMA(0, 0, At, B0); PG8_MMA(0, 1, At, B1); PG8_BAR; PG8_SCHED;
;             PG8_LDA(At, 1, 1); PG8_STAGE(PG8_SB(1, 0), b3, voffB); PG8_STAGE(PG8_SB(1, 1), b3 + hstep, voffB); PG8_STAGE(PG8_SA(1, 0), a3, voffA);
;             PG8_WAIT_V(8); PG8_WAIT_L(0); PG8_BAR; PG8_MMA(1, 0, At, B0); PG8_MMA(1, 1, At, B1); PG8_BAR; PG8_SCHED;
	v_mfma_f32_16x16x32_bf16 v[2:5], v[150:153], v[204:207], v[2:5]
	s_setprio 0
	s_add_i32 s61, 0, 0x18000
	s_add_i32 s62, 0, 0x1c000
	v_add_u32_e32 v134, s61, v237
	v_add_u32_e32 v150, s62, v237
	ds_read_b128 v[98:101], v134
	ds_read_b128 v[110:113], v134 offset:1024
	ds_read_b128 v[122:125], v134 offset:2048
	ds_read_b128 v[134:137], v134 offset:3072
	ds_read_b128 v[138:141], v150
	ds_read_b128 v[142:145], v150 offset:1024
	ds_read_b128 v[146:149], v150 offset:2048
	ds_read_b128 v[150:153], v150 offset:3072
	s_add_u32 s18, s38, 0xb0000
	s_addc_u32 s19, s39, 0
	s_mov_b32 m0, s43
	ds_read_b128 v[162:165], v241 offset:32768
	ds_read_b128 v[166:169], v241 offset:33792
	ds_read_b128 v[170:173], v241 offset:34816
	ds_read_b128 v[174:177], v241 offset:35840
	ds_read_b128 v[178:181], v241 offset:36864
	ds_read_b128 v[182:185], v241 offset:37888
	ds_read_b128 v[186:189], v241 offset:38912
	ds_read_b128 v[204:207], v241 offset:39936
	s_mov_b32 m0, s44
	s_nop 0
	s_waitcnt vmcnt(10)
	s_waitcnt lgkmcnt(0)
	s_setprio 1
	s_barrier
	s_waitcnt lgkmcnt(0)
	v_mfma_f32_16x16x32_bf16 v[158:161], v[98:101], v[162:165], v[158:161]
	v_mfma_f32_16x16x32_bf16 v[154:157], v[122:125], v[162:165], v[154:157]
	v_mfma_f32_16x16x32_bf16 v[118:121], v[98:101], v[170:173], v[118:121]
	v_mfma_f32_16x16x32_bf16 v[114:117], v[122:125], v[170:173], v[114:117]
	v_mfma_f32_16x16x32_bf16 v[94:97], v[98:101], v[178:181], v[94:97]
	v_mfma_f32_16x16x32_bf16 v[90:93], v[122:125], v[178:181], v[90:93]
	v_mfma_f32_16x16x32_bf16 v[78:81], v[98:101], v[186:189], v[78:81]
	v_mfma_f32_16x16x32_bf16 v[74:77], v[122:125], v[186:189], v[74:77]
	v_mfma_f32_16x16x32_bf16 v[158:161], v[110:113], v[166:169], v[158:161]
	v_mfma_f32_16x16x32_bf16 v[154:157], v[134:137], v[166:169], v[154:157]
	v_mfma_f32_16x16x32_bf16 v[118:121], v[110:113], v[174:177], v[118:121]
	v_mfma_f32_16x16x32_bf16 v[114:117], v[134:137], v[174:177], v[114:117]
	v_mfma_f32_16x16x32_bf16 v[94:97], v[110:113], v[182:185], v[94:97]
	v_mfma_f32_16x16x32_bf16 v[90:93], v[134:137], v[182:185], v[90:93]
	v_mfma_f32_16x16x32_bf16 v[78:81], v[110:113], v[204:207], v[78:81]
	v_mfma_f32_16x16x32_bf16 v[74:77], v[134:137], v[204:207], v[74:77]
	s_setprio 0
	s_setprio 1
	v_mfma_f32_16x16x32_bf16 v[130:133], v[138:141], v[162:165], v[130:133]
	v_mfma_f32_16x16x32_bf16 v[126:129], v[146:149], v[162:165], v[126:129]
	v_mfma_f32_16x16x32_bf16 v[106:109], v[138:141], v[170:173], v[106:109]
	v_mfma_f32_16x16x32_bf16 v[102:105], v[146:149], v[170:173], v[102:105]
	v_mfma_f32_16x16x32_bf16 v[86:89], v[138:141], v[178:181], v[86:89]
	v_mfma_f32_16x16x32_bf16 v[82:85], v[146:149], v[178:181], v[82:85]
	v_mfma_f32_16x16x32_bf16 v[70:73], v[138:141], v[186:189], v[70:73]
	v_mfma_f32_16x16x32_bf16 v[66:69], v[146:149], v[186:189], v[66:69]
	v_mfma_f32_16x16x32_bf16 v[130:133], v[142:145], v[166:169], v[130:133]
	v_mfma_f32_16x16x32_bf16 v[126:129], v[150:153], v[166:169], v[126:129]
	v_mfma_f32_16x16x32_bf16 v[106:109], v[142:145], v[174:177], v[106:109]
	v_mfma_f32_16x16x32_bf16 v[102:105], v[150:153], v[174:177], v[102:105]
	v_mfma_f32_16x16x32_bf16 v[86:89], v[142:145], v[182:185], v[86:89]
	v_mfma_f32_16x16x32_bf16 v[82:85], v[150:153], v[182:185], v[82:85]
	v_mfma_f32_16x16x32_bf16 v[70:73], v[142:145], v[204:207], v[70:73]
	s_setprio 3
	s_barrier
	v_mfma_f32_16x16x32_bf16 v[66:69], v[150:153], v[204:207], v[66:69]
	s_setprio 0
	s_add_i32 s18, s61, s40
	s_mov_b32 m0, s18
	ds_read_b128 v[162:165], v241 offset:49152
	ds_read_b128 v[166:169], v241 offset:50176
	ds_read_b128 v[170:173], v241 offset:51200
	ds_read_b128 v[174:177], v241 offset:52224
	ds_read_b128 v[178:181], v241 offset:53248
	ds_read_b128 v[182:185], v241 offset:54272
	ds_read_b128 v[186:189], v241 offset:55296
	ds_read_b128 v[204:207], v241 offset:56320
	s_add_i32 m0, s18, 0x2000
	s_add_u32 s18, s36, 0xb0080
	s_addc_u32 s19, s37, 0
	s_add_i32 s36, s62, s40
	s_mov_b32 m0, s36
	s_nop 0
	s_add_i32 m0, s36, 0x2000
	s_nop 0
	s_mov_b32 m0, s46
	s_nop 0
	s_mov_b32 m0, s47
	s_nop 0
	s_waitcnt vmcnt(10)
	s_waitcnt lgkmcnt(0)
	s_setprio 1
	s_barrier
	s_waitcnt lgkmcnt(0)
	v_mfma_f32_16x16x32_bf16 v[62:65], v[98:101], v[162:165], v[62:65]
	v_mfma_f32_16x16x32_bf16 v[58:61], v[122:125], v[162:165], v[58:61]
	v_mfma_f32_16x16x32_bf16 v[46:49], v[98:101], v[170:173], v[46:49]
	v_mfma_f32_16x16x32_bf16 v[42:45], v[122:125], v[170:173], v[42:45]
	v_mfma_f32_16x16x32_bf16 v[30:33], v[98:101], v[178:181], v[30:33]
	v_mfma_f32_16x16x32_bf16 v[26:29], v[122:125], v[178:181], v[26:29]
	v_mfma_f32_16x16x32_bf16 v[14:17], v[98:101], v[186:189], v[14:17]
	v_mfma_f32_16x16x32_bf16 v[10:13], v[122:125], v[186:189], v[10:13]
	v_mfma_f32_16x16x32_bf16 v[62:65], v[110:113], v[166:169], v[62:65]
	v_mfma_f32_16x16x32_bf16 v[58:61], v[134:137], v[166:169], v[58:61]
	v_mfma_f32_16x16x32_bf16 v[46:49], v[110:113], v[174:177], v[46:49]
	v_mfma_f32_16x16x32_bf16 v[42:45], v[134:137], v[174:177], v[42:45]
	v_mfma_f32_16x16x32_bf16 v[30:33], v[110:113], v[182:185], v[30:33]
	v_mfma_f32_16x16x32_bf16 v[26:29], v[134:137], v[182:185], v[26:29]
	v_mfma_f32_16x16x32_bf16 v[14:17], v[110:113], v[204:207], v[14:17]
	v_mfma_f32_16x16x32_bf16 v[10:13], v[134:137], v[204:207], v[10:13]
	s_setprio 0
	s_setprio 1
	v_mfma_f32_16x16x32_bf16 v[54:57], v[138:141], v[162:165], v[54:57]
	v_mfma_f32_16x16x32_bf16 v[50:53], v[146:149], v[162:165], v[50:53]
	v_mfma_f32_16x16x32_bf16 v[38:41], v[138:141], v[170:173], v[38:41]
	v_mfma_f32_16x16x32_bf16 v[34:37], v[146:149], v[170:173], v[34:37]
	v_mfma_f32_16x16x32_bf16 v[22:25], v[138:141], v[178:181], v[22:25]
	v_mfma_f32_16x16x32_bf16 v[18:21], v[146:149], v[178:181], v[18:21]
	v_mfma_f32_16x16x32_bf16 v[6:9], v[138:141], v[186:189], v[6:9]
	v_mfma_f32_16x16x32_bf16 v[2:5], v[146:149], v[186:189], v[2:5]
	v_mfma_f32_16x16x32_bf16 v[54:57], v[142:145], v[166:169], v[54:57]
	v_mfma_f32_16x16x32_bf16 v[50:53], v[150:153], v[166:169], v[50:53]
	v_mfma_f32_16x16x32_bf16 v[38:41], v[142:145], v[174:177], v[38:41]
	v_mfma_f32_16x16x32_bf16 v[34:37], v[150:153], v[174:177], v[34:37]
	v_mfma_f32_16x16x32_bf16 v[22:25], v[142:145], v[182:185], v[22:25]
	v_mfma_f32_16x16x32_bf16 v[18:21], v[150:153], v[182:185], v[18:21]
	v_mfma_f32_16x16x32_bf16 v[6:9], v[142:145], v[204:207], v[6:9]
	s_setprio 3
	s_barrier
	v_mfma_f32_16x16x32_bf16 v[2:5], v[150:153], v[204:207], v[2:5]
	s_setprio 0
	s_add_i32 s60, s60, 2
	s_add_u32 s34, s34, 0x100
	s_addc_u32 s35, s35, 0
	s_add_u32 s58, s58, 0x100
	s_addc_u32 s59, s59, 0
	s_branch .Lrp_done_p5

; #define PG8_STAGE(bufoff, gbase, voff) do { _Pragma("unroll") for (int _i = 0; _i < 2; ++_i) \
;         __builtin_amdgcn_global_load_lds((const unsigned*)((const char*)(gbase) + (voff)[_i]), (PG8_LAS unsigned*)(lds + (bufoff) + ldsw + _i * 8192), 16, 0, 0); } while (0)
; #define PG8_LDA(dst, b, h) do { _Pragma("unroll") for (int m = 0; m < 4; ++m) _Pragma("unroll") for (int k = 0; k < 2; ++k) dst[m][k] = *(const PG8_LAS bf16x8*)(lds + PG8_SA(b, h) + aoff + m * 2048 + k * 1024); } while (0)
; #define PG8_LDB(dst, b, h) do { _Pragma("unroll") for (int n = 0; n < 2; ++n) _Pragma("unroll") for (int k = 0; k < 2; ++k) dst[n][k] = *(const PG8_LAS bf16x8*)(lds + PG8_SB(b, h) + boff + n * 2048 + k * 1024); } while (0)
; #define PG8_MMA(ai, bj, At, Bt) do { __builtin_amdgcn_s_setprio(1); _Pragma("unroll") for (int m = 0; m < 4; ++m) _Pragma("unroll") for (int n = 0; n < 2; ++n) _Pragma("unroll") for (int k = 0; k < 2; ++k) \
;         acc[ai][bj][m][n] = __builtin_amdgcn_mfma_f32_16x16x32_bf16(Bt[n][k], At[m][k], acc[ai][bj][m][n], 0, 0, 0); __builtin_amdgcn_s_setprio(0); } while (0)
; #define PG8_WAIT_V(n) asm volatile("s_waitcnt vmcnt(" #n ")" ::: "memory")
; #define PG8_WAIT_L(n) asm volatile("s_waitcnt lgkmcnt(" #n ")" ::: "memory")
; #define PG8_BAR __builtin_amdgcn_s_barrier()
; #define PG8_SCHED __builtin_amdgcn_sched_barrier(0)
; template <class Epi, class Sched, bool ALIGN_EPI = false, bool SP2 = false>
; __device__ __forceinline__ void gemm_phase(PG8_LAS unsigned char* lds, const Gemm g, const Sched& S, const Epi& E) {
;     ...
;             PG8_LDB(B0, 0, 0); PG8_LDB(B1, 0, 1); PG8_SCHED; PG8_LDA(At, 0, 0); PG8_STAGE(PG8_SA(1, 1), a1 + hstep, voffA);
;             PG8_WAIT_V(8); PG8_WAIT_L(0); PG8_BAR; PG8_MMA(0, 0, At, B0); PG8_MMA(0, 1, At, B1); PG8_BAR; PG8_SCHED;
;             PG8_LDA(At, 0, 1); PG8_STAGE(PG8_SB(0, 0), b2, voffB); PG8_STAGE(PG8_SB(0, 1), b2 + hstep, voffB); PG8_STAGE(PG8_SA(0, 0), a2, voffA);
;             PG8_WAIT_V(8); PG8_WAIT_L(0); PG8_BAR; PG8_MMA(1, 0, At, B0); PG8_MMA(1, 1, At, B1); PG8_BAR; PG8_SCHED;
.LBB0_1033:
	ds_read_b128 v[128:131], v202
	ds_read_b128 v[132:135], v202 offset:1024
	ds_read_b128 v[136:139], v202 offset:2048
	ds_read_b128 v[140:143], v202 offset:3072
	ds_read_b128 v[144:147], v203
	ds_read_b128 v[148:151], v203 offset:1024
	ds_read_b128 v[152:155], v203 offset:2048
	ds_read_b128 v[156:159], v203 offset:3072
	s_add_u32 s6, s4, 0xfffc0080
	s_addc_u32 s7, s5, -1
	s_cmp_eq_u32 s62, 12
	s_cselect_b32 s41, s3, s7
	s_cselect_b32 s40, s35, s6
	s_cselect_b32 s7, s31, s61
	s_cselect_b32 s6, s59, s60
	v_lshl_add_u64 v[218:219], s[4:5], 0, v[170:171]
	s_add_i32 m0, s44, 0xc000
	ds_read_b128 v[178:181], v204
	ds_read_b128 v[182:185], v204 offset:1024
	ds_read_b128 v[186:189], v204 offset:2048
	ds_read_b128 v[190:193], v204 offset:3072
	ds_read_b128 v[194:197], v204 offset:4096
	ds_read_b128 v[206:209], v204 offset:5120
	ds_read_b128 v[210:213], v204 offset:6144
	ds_read_b128 v[214:217], v204 offset:7168
	global_load_lds_dwordx4 v[218:219], off
	v_lshl_add_u64 v[218:219], s[4:5], 0, v[172:173]
	s_add_i32 m0, s44, 0xe000
	s_nop 0
	global_load_lds_dwordx4 v[218:219], off
	s_waitcnt vmcnt(8)
	s_waitcnt lgkmcnt(0)
	s_setprio 1
	s_barrier
	s_waitcnt lgkmcnt(0)
	v_mfma_f32_16x16x32_bf16 v[124:127], v[128:131], v[178:181], v[124:127]
	v_mfma_f32_16x16x32_bf16 v[120:123], v[136:139], v[178:181], v[120:123]
	v_mfma_f32_16x16x32_bf16 v[108:111], v[128:131], v[186:189], v[108:111]
	v_mfma_f32_16x16x32_bf16 v[104:107], v[136:139], v[186:189], v[104:107]
	v_mfma_f32_16x16x32_bf16 v[92:95], v[128:131], v[194:197], v[92:95]
	v_mfma_f32_16x16x32_bf16 v[88:91], v[136:139], v[194:197], v[88:91]
	v_mfma_f32_16x16x32_bf16 v[76:79], v[128:131], v[210:213], v[76:79]
	v_mfma_f32_16x16x32_bf16 v[72:75], v[136:139], v[210:213], v[72:75]
	v_mfma_f32_16x16x32_bf16 v[124:127], v[132:135], v[182:185], v[124:127]
	v_mfma_f32_16x16x32_bf16 v[120:123], v[140:143], v[182:185], v[120:123]
	v_mfma_f32_16x16x32_bf16 v[108:111], v[132:135], v[190:193], v[108:111]
	v_mfma_f32_16x16x32_bf16 v[104:107], v[140:143], v[190:193], v[104:107]
	v_mfma_f32_16x16x32_bf16 v[92:95], v[132:135], v[206:209], v[92:95]
	v_mfma_f32_16x16x32_bf16 v[88:91], v[140:143], v[206:209], v[88:91]
	v_mfma_f32_16x16x32_bf16 v[76:79], v[132:135], v[214:217], v[76:79]
	v_mfma_f32_16x16x32_bf16 v[72:75], v[140:143], v[214:217], v[72:75]
	s_setprio 0
	s_setprio 1
	v_mfma_f32_16x16x32_bf16 v[116:119], v[144:147], v[178:181], v[116:119]
	v_mfma_f32_16x16x32_bf16 v[112:115], v[152:155], v[178:181], v[112:115]
	v_mfma_f32_16x16x32_bf16 v[100:103], v[144:147], v[186:189], v[100:103]
	v_mfma_f32_16x16x32_bf16 v[96:99], v[152:155], v[186:189], v[96:99]
	v_mfma_f32_16x16x32_bf16 v[84:87], v[144:147], v[194:197], v[84:87]
	v_mfma_f32_16x16x32_bf16 v[80:83], v[152:155], v[194:197], v[80:83]
	v_mfma_f32_16x16x32_bf16 v[68:71], v[144:147], v[210:213], v[68:71]
	v_mfma_f32_16x16x32_bf16 v[64:67], v[152:155], v[210:213], v[64:67]
	v_mfma_f32_16x16x32_bf16 v[116:119], v[148:151], v[182:185], v[116:119]
	v_mfma_f32_16x16x32_bf16 v[112:115], v[156:159], v[182:185], v[112:115]
	v_mfma_f32_16x16x32_bf16 v[100:103], v[148:151], v[190:193], v[100:103]
	v_mfma_f32_16x16x32_bf16 v[96:99], v[156:159], v[190:193], v[96:99]
	v_mfma_f32_16x16x32_bf16 v[84:87], v[148:151], v[206:209], v[84:87]
	v_mfma_f32_16x16x32_bf16 v[80:83], v[156:159], v[206:209], v[80:83]
	v_mfma_f32_16x16x32_bf16 v[68:71], v[148:151], v[214:217], v[68:71]
	s_setprio 3
	s_barrier
	v_mfma_f32_16x16x32_bf16 v[64:67], v[156:159], v[214:217], v[64:67]
	s_setprio 0
	s_add_i32 s63, s55, s42
	v_lshl_add_u64 v[218:219], s[6:7], 0, v[162:163]
	s_mov_b32 m0, s63
	ds_read_b128 v[178:181], v204 offset:16384
	ds_read_b128 v[182:185], v204 offset:17408
	ds_read_b128 v[186:189], v204 offset:18432
	ds_read_b128 v[190:193], v204 offset:19456
	ds_read_b128 v[194:197], v204 offset:20480
	ds_read_b128 v[206:209], v204 offset:21504
	ds_read_b128 v[210:213], v204 offset:22528
	ds_read_b128 v[214:217], v204 offset:23552
	global_load_lds_dwordx4 v[218:219], off
	s_add_i32 m0, s63, 0x2000
	s_add_u32 s64, s6, 0x40000
	v_lshl_add_u64 v[220:221], s[6:7], 0, v[166:167]
	s_addc_u32 s65, s7, 0
	s_add_i32 s63, s56, s42
	global_load_lds_dwordx4 v[220:221], off
	v_lshl_add_u64 v[222:223], s[64:65], 0, v[162:163]
	s_mov_b32 m0, s63
	v_lshl_add_u64 v[224:225], s[40:41], 0, v[164:165]
	global_load_lds_dwordx4 v[222:223], off
	v_lshl_add_u64 v[222:223], s[64:65], 0, v[166:167]
	s_add_i32 m0, s63, 0x2000
	s_nop 0
	global_load_lds_dwordx4 v[222:223], off
	v_lshl_add_u64 v[222:223], s[40:41], 0, v[160:161]
	s_mov_b32 m0, s44
	s_nop 0
	global_load_lds_dwordx4 v[222:223], off
	s_mov_b32 m0, s45
	s_nop 0
	global_load_lds_dwordx4 v[224:225], off
	s_waitcnt vmcnt(8)
	s_waitcnt lgkmcnt(0)
	s_setprio 1
	s_barrier
; #define PG8_STAGE(bufoff, gbase, voff) do { _Pragma("unroll") for (int _i = 0; _i < 2; ++_i) \
;         __builtin_amdgcn_global_load_lds((const unsigned*)((const char*)(gbase) + (voff)[_i]), (PG8_LAS unsigned*)(lds + (bufoff) + ldsw + _i * 8192), 16, 0, 0); } while (0)
; #define PG8_LDA(dst, b, h) do { _Pragma("unroll") for (int m = 0; m < 4; ++m) _Pragma("unroll") for (int k = 0; k < 2; ++k) dst[m][k] = *(const PG8_LAS bf16x8*)(lds + PG8_SA(b, h) + aoff + m * 2048 + k * 1024); } while (0)
; #define PG8_LDB(dst, b, h) do { _Pragma("unroll") for (int n = 0; n < 2; ++n) _Pragma("unroll") for (int k = 0; k < 2; ++k) dst[n][k] = *(const PG8_LAS bf16x8*)(lds + PG8_SB(b, h) + boff + n * 2048 + k * 1024); } while (0)
; #define PG8_MMA(ai, bj, At, Bt) do { __builtin_amdgcn_s_setprio(1); _Pragma("unroll") for (int m = 0; m < 4; ++m) _Pragma("unroll") for (int n = 0; n < 2; ++n) _Pragma("unroll") for (int k = 0; k < 2; ++k) \
;         acc[ai][bj][m][n] = __builtin_amdgcn_mfma_f32_16x16x32_bf16(Bt[n][k], At[m][k], acc[ai][bj][m][n], 0, 0, 0); __builtin_amdgcn_s_setprio(0); } while (0)
; #define PG8_WAIT_V(n) asm volatile("s_waitcnt vmcnt(" #n ")" ::: "memory")
; #define PG8_WAIT_L(n) asm volatile("s_waitcnt lgkmcnt(" #n ")" ::: "memory")
; #define PG8_BAR __builtin_amdgcn_s_barrier()
; #define PG8_SCHED __builtin_amdgcn_sched_barrier(0)
; template <class Epi, class Sched, bool ALIGN_EPI = false, bool SP2 = false>
; __device__ __forceinline__ void gemm_phase(PG8_LAS unsigned char* lds, const Gemm g, const Sched& S, const Epi& E) {
;     ...
;             PG8_WAIT_V(8); PG8_WAIT_L(0); PG8_BAR; PG8_MMA(1, 0, At, B0); PG8_MMA(1, 1, At, B1); PG8_BAR; PG8_SCHED;
;             PG8_LDB(B0, 1, 0); PG8_LDB(B1, 1, 1); PG8_SCHED; PG8_LDA(At, 1, 0); PG8_STAGE(PG8_SA(0, 1), a2 + hstep, voffA);
;             PG8_WAIT_V(8); PG8_WAIT_L(0); PG8_BAR; PG8_MMA(0, 0, At, B0); PG8_MMA(0, 1, At, B1); PG8_BAR; PG8_SCHED;
	s_waitcnt lgkmcnt(0)
	v_mfma_f32_16x16x32_bf16 v[60:63], v[128:131], v[178:181], v[60:63]
	v_mfma_f32_16x16x32_bf16 v[56:59], v[136:139], v[178:181], v[56:59]
	v_mfma_f32_16x16x32_bf16 v[44:47], v[128:131], v[186:189], v[44:47]
	v_mfma_f32_16x16x32_bf16 v[40:43], v[136:139], v[186:189], v[40:43]
	v_mfma_f32_16x16x32_bf16 v[28:31], v[128:131], v[194:197], v[28:31]
	v_mfma_f32_16x16x32_bf16 v[24:27], v[136:139], v[194:197], v[24:27]
	v_mfma_f32_16x16x32_bf16 v[12:15], v[128:131], v[210:213], v[12:15]
	v_mfma_f32_16x16x32_bf16 v[8:11], v[136:139], v[210:213], v[8:11]
	v_mfma_f32_16x16x32_bf16 v[60:63], v[132:135], v[182:185], v[60:63]
	v_mfma_f32_16x16x32_bf16 v[56:59], v[140:143], v[182:185], v[56:59]
	v_mfma_f32_16x16x32_bf16 v[44:47], v[132:135], v[190:193], v[44:47]
	v_mfma_f32_16x16x32_bf16 v[40:43], v[140:143], v[190:193], v[40:43]
	v_mfma_f32_16x16x32_bf16 v[28:31], v[132:135], v[206:209], v[28:31]
	v_mfma_f32_16x16x32_bf16 v[24:27], v[140:143], v[206:209], v[24:27]
	v_mfma_f32_16x16x32_bf16 v[12:15], v[132:135], v[214:217], v[12:15]
	v_mfma_f32_16x16x32_bf16 v[8:11], v[140:143], v[214:217], v[8:11]
	s_setprio 0
	s_setprio 1
	v_mfma_f32_16x16x32_bf16 v[52:55], v[144:147], v[178:181], v[52:55]
	v_mfma_f32_16x16x32_bf16 v[48:51], v[152:155], v[178:181], v[48:51]
	v_mfma_f32_16x16x32_bf16 v[36:39], v[144:147], v[186:189], v[36:39]
	v_mfma_f32_16x16x32_bf16 v[32:35], v[152:155], v[186:189], v[32:35]
	v_mfma_f32_16x16x32_bf16 v[20:23], v[144:147], v[194:197], v[20:23]
	v_mfma_f32_16x16x32_bf16 v[16:19], v[152:155], v[194:197], v[16:19]
	v_mfma_f32_16x16x32_bf16 v[4:7], v[144:147], v[210:213], v[4:7]
	v_mfma_f32_16x16x32_bf16 v[0:3], v[152:155], v[210:213], v[0:3]
	v_mfma_f32_16x16x32_bf16 v[52:55], v[148:151], v[182:185], v[52:55]
	v_mfma_f32_16x16x32_bf16 v[48:51], v[156:159], v[182:185], v[48:51]
	v_mfma_f32_16x16x32_bf16 v[36:39], v[148:151], v[190:193], v[36:39]
	v_mfma_f32_16x16x32_bf16 v[32:35], v[156:159], v[190:193], v[32:35]
	v_mfma_f32_16x16x32_bf16 v[20:23], v[148:151], v[206:209], v[20:23]
	v_mfma_f32_16x16x32_bf16 v[16:19], v[156:159], v[206:209], v[16:19]
	v_mfma_f32_16x16x32_bf16 v[4:7], v[148:151], v[214:217], v[4:7]
	s_setprio 3
	s_barrier
	v_mfma_f32_16x16x32_bf16 v[0:3], v[156:159], v[214:217], v[0:3]
	s_setprio 0
	s_add_i32 s63, 0, 0x18000
	s_add_i32 s64, 0, 0x1c000
	v_add_u32_e32 v140, s63, v199
	v_add_u32_e32 v156, s64, v199
	ds_read_b128 v[128:131], v140
	ds_read_b128 v[132:135], v140 offset:1024
	ds_read_b128 v[136:139], v140 offset:2048
	ds_read_b128 v[140:143], v140 offset:3072
	ds_read_b128 v[144:147], v156
	ds_read_b128 v[148:151], v156 offset:1024
	ds_read_b128 v[152:155], v156 offset:2048
	ds_read_b128 v[156:159], v156 offset:3072
	s_add_u32 s40, s40, 0x40000
	s_addc_u32 s41, s41, 0
	s_mov_b32 m0, s46
	v_lshl_add_u64 v[226:227], s[40:41], 0, v[160:161]
	ds_read_b128 v[178:181], v204 offset:32768
	ds_read_b128 v[182:185], v204 offset:33792
	ds_read_b128 v[186:189], v204 offset:34816
	ds_read_b128 v[190:193], v204 offset:35840
	ds_read_b128 v[194:197], v204 offset:36864
	ds_read_b128 v[206:209], v204 offset:37888
	ds_read_b128 v[210:213], v204 offset:38912
	ds_read_b128 v[214:217], v204 offset:39936
	global_load_lds_dwordx4 v[226:227], off
	v_lshl_add_u64 v[226:227], s[40:41], 0, v[164:165]
	s_mov_b32 m0, s47
	s_nop 0
	global_load_lds_dwordx4 v[226:227], off
	s_waitcnt vmcnt(8)
	s_waitcnt lgkmcnt(0)
	s_setprio 1
	s_barrier
	s_waitcnt lgkmcnt(0)
	v_mfma_f32_16x16x32_bf16 v[124:127], v[128:131], v[178:181], v[124:127]
	v_mfma_f32_16x16x32_bf16 v[120:123], v[136:139], v[178:181], v[120:123]
	v_mfma_f32_16x16x32_bf16 v[108:111], v[128:131], v[186:189], v[108:111]
	v_mfma_f32_16x16x32_bf16 v[104:107], v[136:139], v[186:189], v[104:107]
	v_mfma_f32_16x16x32_bf16 v[92:95], v[128:131], v[194:197], v[92:95]
	v_mfma_f32_16x16x32_bf16 v[88:91], v[136:139], v[194:197], v[88:91]
	v_mfma_f32_16x16x32_bf16 v[76:79], v[128:131], v[210:213], v[76:79]
	v_mfma_f32_16x16x32_bf16 v[72:75], v[136:139], v[210:213], v[72:75]
	v_mfma_f32_16x16x32_bf16 v[124:127], v[132:135], v[182:185], v[124:127]
	v_mfma_f32_16x16x32_bf16 v[120:123], v[140:143], v[182:185], v[120:123]
	v_mfma_f32_16x16x32_bf16 v[108:111], v[132:135], v[190:193], v[108:111]
	v_mfma_f32_16x16x32_bf16 v[104:107], v[140:143], v[190:193], v[104:107]
	v_mfma_f32_16x16x32_bf16 v[92:95], v[132:135], v[206:209], v[92:95]
	v_mfma_f32_16x16x32_bf16 v[88:91], v[140:143], v[206:209], v[88:91]
	v_mfma_f32_16x16x32_bf16 v[76:79], v[132:135], v[214:217], v[76:79]
	v_mfma_f32_16x16x32_bf16 v[72:75], v[140:143], v[214:217], v[72:75]
	s_setprio 0
	s_setprio 1
	v_mfma_f32_16x16x32_bf16 v[116:119], v[144:147], v[178:181], v[116:119]
	v_mfma_f32_16x16x32_bf16 v[112:115], v[152:155], v[178:181], v[112:115]
	v_mfma_f32_16x16x32_bf16 v[100:103], v[144:147], v[186:189], v[100:103]
	v_mfma_f32_16x16x32_bf16 v[96:99], v[152:155], v[186:189], v[96:99]
	v_mfma_f32_16x16x32_bf16 v[84:87], v[144:147], v[194:197], v[84:87]
	v_mfma_f32_16x16x32_bf16 v[80:83], v[152:155], v[194:197], v[80:83]
	v_mfma_f32_16x16x32_bf16 v[68:71], v[144:147], v[210:213], v[68:71]
	v_mfma_f32_16x16x32_bf16 v[64:67], v[152:155], v[210:213], v[64:67]
	v_mfma_f32_16x16x32_bf16 v[116:119], v[148:151], v[182:185], v[116:119]
	v_mfma_f32_16x16x32_bf16 v[112:115], v[156:159], v[182:185], v[112:115]
	v_mfma_f32_16x16x32_bf16 v[100:103], v[148:151], v[190:193], v[100:103]
	v_mfma_f32_16x16x32_bf16 v[96:99], v[156:159], v[190:193], v[96:99]
	v_mfma_f32_16x16x32_bf16 v[84:87], v[148:151], v[206:209], v[84:87]
	v_mfma_f32_16x16x32_bf16 v[80:83], v[156:159], v[206:209], v[80:83]
	v_mfma_f32_16x16x32_bf16 v[68:71], v[148:151], v[214:217], v[68:71]
	s_setprio 3
	s_barrier
; #define PG8_STAGE(bufoff, gbase, voff) do { _Pragma("unroll") for (int _i = 0; _i < 2; ++_i) \
;         __builtin_amdgcn_global_load_lds((const unsigned*)((const char*)(gbase) + (voff)[_i]), (PG8_LAS unsigned*)(lds + (bufoff) + ldsw + _i * 8192), 16, 0, 0); } while (0)
; #define PG8_LDA(dst, b, h) do { _Pragma("unroll") for (int m = 0; m < 4; ++m) _Pragma("unroll") for (int k = 0; k < 2; ++k) dst[m][k] = *(const PG8_LAS bf16x8*)(lds + PG8_SA(b, h) + aoff + m * 2048 + k * 1024); } while (0)
; #define PG8_MMA(ai, bj, At, Bt) do { __builtin_amdgcn_s_setprio(1); _Pragma("unroll") for (int m = 0; m < 4; ++m) _Pragma("unroll") for (int n = 0; n < 2; ++n) _Pragma("unroll") for (int k = 0; k < 2; ++k) \
;         acc[ai][bj][m][n] = __builtin_amdgcn_mfma_f32_16x16x32_bf16(Bt[n][k], At[m][k], acc[ai][bj][m][n], 0, 0, 0); __builtin_amdgcn_s_setprio(0); } while (0)
; #define PG8_WAIT_V(n) asm volatile("s_waitcnt vmcnt(" #n ")" ::: "memory")
; #define PG8_WAIT_L(n) asm volatile("s_waitcnt lgkmcnt(" #n ")" ::: "memory")
; #define PG8_BAR __builtin_amdgcn_s_barrier()
; #define PG8_SCHED __builtin_amdgcn_sched_barrier(0)
; template <class Epi, class Sched, bool ALIGN_EPI = false, bool SP2 = false>
; __device__ __forceinline__ void gemm_phase(PG8_LAS unsigned char* lds, const Gemm g, const Sched& S, const Epi& E) {
;     ...
;             PG8_LDA(At, 1, 1); PG8_STAGE(PG8_SB(1, 0), b3, voffB); PG8_STAGE(PG8_SB(1, 1), b3 + hstep, voffB); PG8_STAGE(PG8_SA(1, 0), a3, voffA);
;             PG8_WAIT_V(8); PG8_WAIT_L(0); PG8_BAR; PG8_MMA(1, 0, At, B0); PG8_MMA(1, 1, At, B1); PG8_BAR; PG8_SCHED;
;     ...
;         if constexpr (ALIGN_EPI) { if (wr == 0) PG8_BAR; }
	v_mfma_f32_16x16x32_bf16 v[64:67], v[156:159], v[214:217], v[64:67]
	s_setprio 0
	s_add_i32 s40, s63, s42
	v_lshl_add_u64 v[218:219], v[218:219], 0, s[12:13]
	s_mov_b32 m0, s40
	ds_read_b128 v[178:181], v204 offset:49152
	ds_read_b128 v[182:185], v204 offset:50176
	ds_read_b128 v[186:189], v204 offset:51200
	ds_read_b128 v[190:193], v204 offset:52224
	ds_read_b128 v[194:197], v204 offset:53248
	ds_read_b128 v[206:209], v204 offset:54272
	ds_read_b128 v[210:213], v204 offset:55296
	ds_read_b128 v[214:217], v204 offset:56320
	global_load_lds_dwordx4 v[218:219], off
	s_add_i32 m0, s40, 0x2000
	s_add_u32 s6, s6, 0x40080
	v_lshl_add_u64 v[218:219], v[220:221], 0, s[12:13]
	s_addc_u32 s7, s7, 0
	s_add_i32 s40, s64, s42
	global_load_lds_dwordx4 v[218:219], off
	v_lshl_add_u64 v[218:219], s[6:7], 0, v[162:163]
	s_mov_b32 m0, s40
	s_nop 0
	global_load_lds_dwordx4 v[218:219], off
	v_lshl_add_u64 v[218:219], s[6:7], 0, v[166:167]
	s_add_i32 m0, s40, 0x2000
	s_nop 0
	global_load_lds_dwordx4 v[218:219], off
	v_lshl_add_u64 v[218:219], v[222:223], 0, s[12:13]
	s_mov_b32 m0, s52
	s_nop 0
	global_load_lds_dwordx4 v[218:219], off
	v_lshl_add_u64 v[218:219], v[224:225], 0, s[12:13]
	s_mov_b32 m0, s53
	s_nop 0
	global_load_lds_dwordx4 v[218:219], off
	s_waitcnt vmcnt(8)
	s_waitcnt lgkmcnt(0)
	s_setprio 1
	s_barrier
	s_waitcnt lgkmcnt(0)
	v_mfma_f32_16x16x32_bf16 v[60:63], v[128:131], v[178:181], v[60:63]
	v_mfma_f32_16x16x32_bf16 v[56:59], v[136:139], v[178:181], v[56:59]
	v_mfma_f32_16x16x32_bf16 v[44:47], v[128:131], v[186:189], v[44:47]
	v_mfma_f32_16x16x32_bf16 v[40:43], v[136:139], v[186:189], v[40:43]
	v_mfma_f32_16x16x32_bf16 v[28:31], v[128:131], v[194:197], v[28:31]
	v_mfma_f32_16x16x32_bf16 v[24:27], v[136:139], v[194:197], v[24:27]
	v_mfma_f32_16x16x32_bf16 v[12:15], v[128:131], v[210:213], v[12:15]
	v_mfma_f32_16x16x32_bf16 v[8:11], v[136:139], v[210:213], v[8:11]
	v_mfma_f32_16x16x32_bf16 v[60:63], v[132:135], v[182:185], v[60:63]
	v_mfma_f32_16x16x32_bf16 v[56:59], v[140:143], v[182:185], v[56:59]
	v_mfma_f32_16x16x32_bf16 v[44:47], v[132:135], v[190:193], v[44:47]
	v_mfma_f32_16x16x32_bf16 v[40:43], v[140:143], v[190:193], v[40:43]
	v_mfma_f32_16x16x32_bf16 v[28:31], v[132:135], v[206:209], v[28:31]
	v_mfma_f32_16x16x32_bf16 v[24:27], v[140:143], v[206:209], v[24:27]
	v_mfma_f32_16x16x32_bf16 v[12:15], v[132:135], v[214:217], v[12:15]
	v_mfma_f32_16x16x32_bf16 v[8:11], v[140:143], v[214:217], v[8:11]
	s_setprio 0
	s_setprio 1
	v_mfma_f32_16x16x32_bf16 v[52:55], v[144:147], v[178:181], v[52:55]
	v_mfma_f32_16x16x32_bf16 v[48:51], v[152:155], v[178:181], v[48:51]
	v_mfma_f32_16x16x32_bf16 v[36:39], v[144:147], v[186:189], v[36:39]
	v_mfma_f32_16x16x32_bf16 v[32:35], v[152:155], v[186:189], v[32:35]
	v_mfma_f32_16x16x32_bf16 v[20:23], v[144:147], v[194:197], v[20:23]
	v_mfma_f32_16x16x32_bf16 v[16:19], v[152:155], v[194:197], v[16:19]
	v_mfma_f32_16x16x32_bf16 v[4:7], v[144:147], v[210:213], v[4:7]
	v_mfma_f32_16x16x32_bf16 v[0:3], v[152:155], v[210:213], v[0:3]
	v_mfma_f32_16x16x32_bf16 v[52:55], v[148:151], v[182:185], v[52:55]
	v_mfma_f32_16x16x32_bf16 v[48:51], v[156:159], v[182:185], v[48:51]
	v_mfma_f32_16x16x32_bf16 v[36:39], v[148:151], v[190:193], v[36:39]
	v_mfma_f32_16x16x32_bf16 v[32:35], v[156:159], v[190:193], v[32:35]
	v_mfma_f32_16x16x32_bf16 v[20:23], v[148:151], v[206:209], v[20:23]
	v_mfma_f32_16x16x32_bf16 v[16:19], v[156:159], v[206:209], v[16:19]
	v_mfma_f32_16x16x32_bf16 v[4:7], v[148:151], v[214:217], v[4:7]
	s_setprio 3
	s_barrier
	v_mfma_f32_16x16x32_bf16 v[0:3], v[156:159], v[214:217], v[0:3]
	s_setprio 0
	s_add_i32 s62, s62, 2
	s_add_u32 s4, s4, 0x100
	s_addc_u32 s5, s5, 0
	s_add_u32 s60, s60, 0x100
	s_addc_u32 s61, s61, 0
	s_cmp_gt_u32 s62, 13
	s_cbranch_scc0 .LBB0_1033
	s_and_b64 vcc, exec, s[14:15]
	s_cbranch_vccz .LBB0_1036
	s_barrier
